# GEMM K-loops: the vmcnt and lgkmcnt waits before each pre-MFMA barrier merged into one s_waitcnt, and the already-satisfied lgkmcnt(0) after the barrier removed
# speedup vs baseline: 1.0043x; 1.0016x over previous
.LBB0_329:
	s_waitcnt lgkmcnt(0)
	s_barrier
	v_mfma_f32_16x16x32_bf16 v[66:69], v[150:153], v[190:193], v[66:69]
	v_mfma_f32_16x16x32_bf16 v[58:61], v[158:161], v[190:193], v[58:61]
	v_mfma_f32_16x16x32_bf16 v[50:53], v[150:153], v[182:185], v[50:53]
	v_mfma_f32_16x16x32_bf16 v[42:45], v[158:161], v[182:185], v[42:45]
	v_mfma_f32_16x16x32_bf16 v[34:37], v[150:153], v[174:177], v[34:37]
	v_mfma_f32_16x16x32_bf16 v[26:29], v[158:161], v[174:177], v[26:29]
	v_mfma_f32_16x16x32_bf16 v[18:21], v[150:153], v[166:169], v[18:21]
	v_mfma_f32_16x16x32_bf16 v[10:13], v[158:161], v[166:169], v[10:13]
	v_mfma_f32_16x16x32_bf16 v[66:69], v[154:157], v[194:197], v[66:69]
	v_mfma_f32_16x16x32_bf16 v[58:61], v[162:165], v[194:197], v[58:61]
	v_mfma_f32_16x16x32_bf16 v[50:53], v[154:157], v[186:189], v[50:53]
	v_mfma_f32_16x16x32_bf16 v[42:45], v[162:165], v[186:189], v[42:45]
	v_mfma_f32_16x16x32_bf16 v[34:37], v[154:157], v[178:181], v[34:37]
	v_mfma_f32_16x16x32_bf16 v[26:29], v[162:165], v[178:181], v[26:29]
	v_mfma_f32_16x16x32_bf16 v[18:21], v[154:157], v[170:173], v[18:21]
	v_mfma_f32_16x16x32_bf16 v[10:13], v[162:165], v[170:173], v[10:13]
	v_mfma_f32_16x16x32_bf16 v[62:65], v[134:137], v[190:193], v[62:65]
	v_mfma_f32_16x16x32_bf16 v[54:57], v[142:145], v[190:193], v[54:57]
	v_mfma_f32_16x16x32_bf16 v[46:49], v[134:137], v[182:185], v[46:49]
	v_mfma_f32_16x16x32_bf16 v[38:41], v[142:145], v[182:185], v[38:41]
	v_mfma_f32_16x16x32_bf16 v[30:33], v[134:137], v[174:177], v[30:33]
	v_mfma_f32_16x16x32_bf16 v[22:25], v[142:145], v[174:177], v[22:25]
	v_mfma_f32_16x16x32_bf16 v[14:17], v[134:137], v[166:169], v[14:17]
	v_mfma_f32_16x16x32_bf16 v[6:9], v[142:145], v[166:169], v[6:9]
	v_mfma_f32_16x16x32_bf16 v[62:65], v[138:141], v[194:197], v[62:65]
	v_mfma_f32_16x16x32_bf16 v[54:57], v[146:149], v[194:197], v[54:57]
	v_mfma_f32_16x16x32_bf16 v[46:49], v[138:141], v[186:189], v[46:49]
	v_mfma_f32_16x16x32_bf16 v[38:41], v[146:149], v[186:189], v[38:41]
	v_mfma_f32_16x16x32_bf16 v[30:33], v[138:141], v[178:181], v[30:33]
	v_mfma_f32_16x16x32_bf16 v[22:25], v[146:149], v[178:181], v[22:25]
	v_mfma_f32_16x16x32_bf16 v[14:17], v[138:141], v[170:173], v[14:17]
	v_mfma_f32_16x16x32_bf16 v[6:9], v[146:149], v[170:173], v[6:9]
	s_barrier
	s_add_i32 s61, s61, 2
	s_cmp_gt_u32 s61, 13
	s_cbranch_scc1 .Lkr1_exit

.LBB0_332:
	s_add_u32 s48, s28, 0xfffc0080
	s_addc_u32 s49, s29, -1
	s_and_b64 s[46:47], s[30:31], exec
	s_cselect_b32 s49, s23, s49
	s_cselect_b32 s48, s56, s48
	s_cselect_b32 s47, s57, s60
	s_cselect_b32 s46, s58, s59
	s_add_i32 m0, s40, 0xc000
	s_nop 0
	global_load_lds_dwordx4 v206, s[28:29]
	s_add_i32 m0, s40, 0xe000
	s_nop 0
	global_load_lds_dwordx4 v208, s[28:29]
	s_waitcnt vmcnt(8) lgkmcnt(0)
	s_barrier
	v_mfma_f32_16x16x32_bf16 v[130:133], v[134:137], v[166:169], v[130:133]
	v_mfma_f32_16x16x32_bf16 v[122:125], v[142:145], v[166:169], v[122:125]
	v_mfma_f32_16x16x32_bf16 v[114:117], v[134:137], v[174:177], v[114:117]
	v_mfma_f32_16x16x32_bf16 v[106:109], v[142:145], v[174:177], v[106:109]
	v_mfma_f32_16x16x32_bf16 v[98:101], v[134:137], v[182:185], v[98:101]
	v_mfma_f32_16x16x32_bf16 v[90:93], v[142:145], v[182:185], v[90:93]
	v_mfma_f32_16x16x32_bf16 v[82:85], v[134:137], v[190:193], v[82:85]
	v_mfma_f32_16x16x32_bf16 v[74:77], v[142:145], v[190:193], v[74:77]
	v_mfma_f32_16x16x32_bf16 v[130:133], v[138:141], v[170:173], v[130:133]
	v_mfma_f32_16x16x32_bf16 v[122:125], v[146:149], v[170:173], v[122:125]
	v_mfma_f32_16x16x32_bf16 v[114:117], v[138:141], v[178:181], v[114:117]
	v_mfma_f32_16x16x32_bf16 v[106:109], v[146:149], v[178:181], v[106:109]
	v_mfma_f32_16x16x32_bf16 v[98:101], v[138:141], v[186:189], v[98:101]
	v_mfma_f32_16x16x32_bf16 v[90:93], v[146:149], v[186:189], v[90:93]
	v_mfma_f32_16x16x32_bf16 v[82:85], v[138:141], v[194:197], v[82:85]
	v_mfma_f32_16x16x32_bf16 v[74:77], v[146:149], v[194:197], v[74:77]
	v_mfma_f32_16x16x32_bf16 v[126:129], v[150:153], v[166:169], v[126:129]
	v_mfma_f32_16x16x32_bf16 v[118:121], v[158:161], v[166:169], v[118:121]
	v_mfma_f32_16x16x32_bf16 v[110:113], v[150:153], v[174:177], v[110:113]
	v_mfma_f32_16x16x32_bf16 v[102:105], v[158:161], v[174:177], v[102:105]
	v_mfma_f32_16x16x32_bf16 v[94:97], v[150:153], v[182:185], v[94:97]
	v_mfma_f32_16x16x32_bf16 v[86:89], v[158:161], v[182:185], v[86:89]
	v_mfma_f32_16x16x32_bf16 v[78:81], v[150:153], v[190:193], v[78:81]
	v_mfma_f32_16x16x32_bf16 v[70:73], v[158:161], v[190:193], v[70:73]
	v_mfma_f32_16x16x32_bf16 v[126:129], v[154:157], v[170:173], v[126:129]
	v_mfma_f32_16x16x32_bf16 v[118:121], v[162:165], v[170:173], v[118:121]
	v_mfma_f32_16x16x32_bf16 v[110:113], v[154:157], v[178:181], v[110:113]
	v_mfma_f32_16x16x32_bf16 v[102:105], v[162:165], v[178:181], v[102:105]
	v_mfma_f32_16x16x32_bf16 v[94:97], v[154:157], v[186:189], v[94:97]
	v_mfma_f32_16x16x32_bf16 v[86:89], v[162:165], v[186:189], v[86:89]
	v_mfma_f32_16x16x32_bf16 v[78:81], v[154:157], v[194:197], v[78:81]
	v_mfma_f32_16x16x32_bf16 v[70:73], v[162:165], v[194:197], v[70:73]
	s_barrier
	ds_read_b128 v[166:169], v229 offset:16384
	ds_read_b128 v[170:173], v229 offset:17408
	ds_read_b128 v[174:177], v229 offset:18432
	ds_read_b128 v[178:181], v229 offset:19456
	ds_read_b128 v[182:185], v229 offset:20480
	ds_read_b128 v[186:189], v229 offset:21504
	ds_read_b128 v[190:193], v229 offset:22528
	ds_read_b128 v[194:197], v229 offset:23552
	s_add_i32 s62, s53, s12
	s_add_u32 s98, s46, s10
	s_addc_u32 s99, s47, s11
	s_mov_b32 m0, s62
	s_nop 0
	global_load_lds_dwordx4 v202, s[46:47]
	s_add_i32 m0, s62, 0x2000
	s_add_u32 s62, s46, 0x40000
	s_addc_u32 s63, s47, 0
	s_add_i32 s64, s54, s12
	global_load_lds_dwordx4 v198, s[46:47]
	s_mov_b32 m0, s64
	s_add_u32 s100, s48, s10
	s_addc_u32 s101, s49, s11
	global_load_lds_dwordx4 v202, s[62:63]
	s_add_i32 m0, s64, 0x2000
	s_nop 0
	global_load_lds_dwordx4 v198, s[62:63]
	s_mov_b32 m0, s40
	s_nop 0
	global_load_lds_dwordx4 v204, s[48:49]
	s_mov_b32 m0, s41
	s_nop 0
	global_load_lds_dwordx4 v200, s[48:49]
	s_waitcnt vmcnt(8) lgkmcnt(0)
	s_barrier
	v_mfma_f32_16x16x32_bf16 v[66:69], v[134:137], v[166:169], v[66:69]
	v_mfma_f32_16x16x32_bf16 v[58:61], v[142:145], v[166:169], v[58:61]
	v_mfma_f32_16x16x32_bf16 v[50:53], v[134:137], v[174:177], v[50:53]
	v_mfma_f32_16x16x32_bf16 v[42:45], v[142:145], v[174:177], v[42:45]
	v_mfma_f32_16x16x32_bf16 v[34:37], v[134:137], v[182:185], v[34:37]
	v_mfma_f32_16x16x32_bf16 v[26:29], v[142:145], v[182:185], v[26:29]
	v_mfma_f32_16x16x32_bf16 v[18:21], v[134:137], v[190:193], v[18:21]
	v_mfma_f32_16x16x32_bf16 v[10:13], v[142:145], v[190:193], v[10:13]
	v_mfma_f32_16x16x32_bf16 v[66:69], v[138:141], v[170:173], v[66:69]
	v_mfma_f32_16x16x32_bf16 v[58:61], v[146:149], v[170:173], v[58:61]
	v_mfma_f32_16x16x32_bf16 v[50:53], v[138:141], v[178:181], v[50:53]
	v_mfma_f32_16x16x32_bf16 v[42:45], v[146:149], v[178:181], v[42:45]
	v_mfma_f32_16x16x32_bf16 v[34:37], v[138:141], v[186:189], v[34:37]
	v_mfma_f32_16x16x32_bf16 v[26:29], v[146:149], v[186:189], v[26:29]
	v_mfma_f32_16x16x32_bf16 v[18:21], v[138:141], v[194:197], v[18:21]
	v_mfma_f32_16x16x32_bf16 v[10:13], v[146:149], v[194:197], v[10:13]
	v_mfma_f32_16x16x32_bf16 v[62:65], v[150:153], v[166:169], v[62:65]
	v_mfma_f32_16x16x32_bf16 v[54:57], v[158:161], v[166:169], v[54:57]
	v_mfma_f32_16x16x32_bf16 v[46:49], v[150:153], v[174:177], v[46:49]
	v_mfma_f32_16x16x32_bf16 v[38:41], v[158:161], v[174:177], v[38:41]
	v_mfma_f32_16x16x32_bf16 v[30:33], v[150:153], v[182:185], v[30:33]
	v_mfma_f32_16x16x32_bf16 v[22:25], v[158:161], v[182:185], v[22:25]
	v_mfma_f32_16x16x32_bf16 v[14:17], v[150:153], v[190:193], v[14:17]
	v_mfma_f32_16x16x32_bf16 v[6:9], v[158:161], v[190:193], v[6:9]
	v_mfma_f32_16x16x32_bf16 v[62:65], v[154:157], v[170:173], v[62:65]
	v_mfma_f32_16x16x32_bf16 v[54:57], v[162:165], v[170:173], v[54:57]
	v_mfma_f32_16x16x32_bf16 v[46:49], v[154:157], v[178:181], v[46:49]
	v_mfma_f32_16x16x32_bf16 v[38:41], v[162:165], v[178:181], v[38:41]
	v_mfma_f32_16x16x32_bf16 v[30:33], v[154:157], v[186:189], v[30:33]
	v_mfma_f32_16x16x32_bf16 v[22:25], v[162:165], v[186:189], v[22:25]
	v_mfma_f32_16x16x32_bf16 v[14:17], v[154:157], v[194:197], v[14:17]
	v_mfma_f32_16x16x32_bf16 v[6:9], v[162:165], v[194:197], v[6:9]
	s_barrier
	ds_read_b128 v[166:169], v229 offset:32768
	ds_read_b128 v[170:173], v229 offset:33792
	ds_read_b128 v[174:177], v229 offset:34816
	ds_read_b128 v[178:181], v229 offset:35840
	ds_read_b128 v[182:185], v229 offset:36864
	ds_read_b128 v[186:189], v229 offset:37888
	ds_read_b128 v[190:193], v229 offset:38912
	ds_read_b128 v[194:197], v229 offset:39936
	v_add_u32_e32 v134, 0x18000, v225
	v_add_u32_e32 v146, 0x1c000, v225
	ds_read_b128 v[150:153], v134
	ds_read_b128 v[154:157], v134 offset:1024
	ds_read_b128 v[158:161], v134 offset:2048
	ds_read_b128 v[162:165], v134 offset:3072
	ds_read_b128 v[134:137], v146
	ds_read_b128 v[138:141], v146 offset:1024
	ds_read_b128 v[142:145], v146 offset:2048
	ds_read_b128 v[146:149], v146 offset:3072
	s_add_i32 s62, 0, 0x18000
	s_add_i32 s63, 0, 0x1c000
	s_add_u32 s48, s48, 0x40000
	s_addc_u32 s49, s49, 0
	s_mov_b32 m0, s42
	s_nop 0
	global_load_lds_dwordx4 v204, s[48:49]
	s_mov_b32 m0, s43
	s_nop 0
	global_load_lds_dwordx4 v200, s[48:49]
	s_waitcnt vmcnt(8) lgkmcnt(0)
	s_barrier
	v_mfma_f32_16x16x32_bf16 v[130:133], v[150:153], v[166:169], v[130:133]
	v_mfma_f32_16x16x32_bf16 v[122:125], v[158:161], v[166:169], v[122:125]
	v_mfma_f32_16x16x32_bf16 v[114:117], v[150:153], v[174:177], v[114:117]
	v_mfma_f32_16x16x32_bf16 v[106:109], v[158:161], v[174:177], v[106:109]
	v_mfma_f32_16x16x32_bf16 v[98:101], v[150:153], v[182:185], v[98:101]
	v_mfma_f32_16x16x32_bf16 v[90:93], v[158:161], v[182:185], v[90:93]
	v_mfma_f32_16x16x32_bf16 v[82:85], v[150:153], v[190:193], v[82:85]
	v_mfma_f32_16x16x32_bf16 v[74:77], v[158:161], v[190:193], v[74:77]
	v_mfma_f32_16x16x32_bf16 v[130:133], v[154:157], v[170:173], v[130:133]
	v_mfma_f32_16x16x32_bf16 v[122:125], v[162:165], v[170:173], v[122:125]
	v_mfma_f32_16x16x32_bf16 v[114:117], v[154:157], v[178:181], v[114:117]
	v_mfma_f32_16x16x32_bf16 v[106:109], v[162:165], v[178:181], v[106:109]
	v_mfma_f32_16x16x32_bf16 v[98:101], v[154:157], v[186:189], v[98:101]
	v_mfma_f32_16x16x32_bf16 v[90:93], v[162:165], v[186:189], v[90:93]
	v_mfma_f32_16x16x32_bf16 v[82:85], v[154:157], v[194:197], v[82:85]
	v_mfma_f32_16x16x32_bf16 v[74:77], v[162:165], v[194:197], v[74:77]
	v_mfma_f32_16x16x32_bf16 v[126:129], v[134:137], v[166:169], v[126:129]
	v_mfma_f32_16x16x32_bf16 v[118:121], v[142:145], v[166:169], v[118:121]
	v_mfma_f32_16x16x32_bf16 v[110:113], v[134:137], v[174:177], v[110:113]
	v_mfma_f32_16x16x32_bf16 v[102:105], v[142:145], v[174:177], v[102:105]
	v_mfma_f32_16x16x32_bf16 v[94:97], v[134:137], v[182:185], v[94:97]
	v_mfma_f32_16x16x32_bf16 v[86:89], v[142:145], v[182:185], v[86:89]
	v_mfma_f32_16x16x32_bf16 v[78:81], v[134:137], v[190:193], v[78:81]
	v_mfma_f32_16x16x32_bf16 v[70:73], v[142:145], v[190:193], v[70:73]
	v_mfma_f32_16x16x32_bf16 v[126:129], v[138:141], v[170:173], v[126:129]
	v_mfma_f32_16x16x32_bf16 v[118:121], v[146:149], v[170:173], v[118:121]
	v_mfma_f32_16x16x32_bf16 v[110:113], v[138:141], v[178:181], v[110:113]
	v_mfma_f32_16x16x32_bf16 v[102:105], v[146:149], v[178:181], v[102:105]
	v_mfma_f32_16x16x32_bf16 v[94:97], v[138:141], v[186:189], v[94:97]
	v_mfma_f32_16x16x32_bf16 v[86:89], v[146:149], v[186:189], v[86:89]
	v_mfma_f32_16x16x32_bf16 v[78:81], v[138:141], v[194:197], v[78:81]
	v_mfma_f32_16x16x32_bf16 v[70:73], v[146:149], v[194:197], v[70:73]
	s_barrier
	ds_read_b128 v[190:193], v229 offset:49152
	ds_read_b128 v[194:197], v229 offset:50176
	ds_read_b128 v[182:185], v229 offset:51200
	ds_read_b128 v[186:189], v229 offset:52224
	ds_read_b128 v[174:177], v229 offset:53248
	ds_read_b128 v[178:181], v229 offset:54272
	ds_read_b128 v[166:169], v229 offset:55296
	ds_read_b128 v[170:173], v229 offset:56320
	s_add_i32 s48, s62, s12
	s_mov_b32 m0, s48
	s_nop 0
	global_load_lds_dwordx4 v202, s[98:99]
	s_add_i32 m0, s48, 0x2000
	s_add_u32 s46, s46, 0x40080
	s_addc_u32 s47, s47, 0
	s_add_i32 s48, s63, s12
	global_load_lds_dwordx4 v198, s[98:99]
	s_mov_b32 m0, s48
	s_andn2_b64 vcc, exec, s[30:31]
	global_load_lds_dwordx4 v202, s[46:47]
	s_add_i32 m0, s48, 0x2000
	s_nop 0
	global_load_lds_dwordx4 v198, s[46:47]
	s_mov_b32 m0, s51
	s_nop 0
	global_load_lds_dwordx4 v204, s[100:101]
	s_mov_b32 m0, s52
	s_nop 0
	global_load_lds_dwordx4 v200, s[100:101]
	s_waitcnt vmcnt(8)
	s_cbranch_vccnz .LBB0_329
	s_and_saveexec_b64 s[30:31], s[4:5]
	s_cbranch_execz .LBB0_328
	v_mov_b32_e32 v232, v3
	v_mov_b32_e32 v233, v4
	v_mov_b32_e32 v234, v2
	v_mov_b32_e32 v235, v5
	v_pk_add_f32 v[232:233], v[232:233], v[234:235]
	s_nop 0
	v_add_f32_e32 v226, v232, v233
	v_fmamk_f32 v226, v226, 0x3a800000, v230
	ds_write_b32 v228, v226
	s_branch .LBB0_328

.LBB0_370:
	ds_read_b128 v[2:5], v148
	ds_read_b128 v[6:9], v148 offset:1024
	ds_read_b128 v[10:13], v148 offset:2048
	ds_read_b128 v[14:17], v148 offset:3072
	ds_read_b128 v[18:21], v149
	ds_read_b128 v[22:25], v149 offset:1024
	ds_read_b128 v[26:29], v149 offset:2048
	ds_read_b128 v[30:33], v149 offset:3072
	s_ashr_i32 s47, s46, 31
	s_lshl_b64 s[52:53], s[46:47], 17
	s_add_u32 s52, s0, s52
	s_addc_u32 s53, s1, s53
	s_and_b64 s[6:7], s[6:7], exec
	s_cselect_b32 s7, s53, s61
	s_cselect_b32 s6, s52, s60
	s_add_u32 s66, s58, 0x10080
	s_addc_u32 s67, s59, 0
	s_add_i32 s65, s13, 0xc000
	v_lshl_add_u64 v[66:67], s[66:67], 0, v[130:131]
	s_mov_b32 m0, s65
	s_add_i32 s2, s13, 0xe000
	ds_read_b128 v[34:37], v150
	ds_read_b128 v[38:41], v150 offset:1024
	ds_read_b128 v[42:45], v150 offset:2048
	ds_read_b128 v[46:49], v150 offset:3072
	ds_read_b128 v[50:53], v150 offset:4096
	ds_read_b128 v[54:57], v150 offset:5120
	ds_read_b128 v[58:61], v150 offset:6144
	ds_read_b128 v[62:65], v150 offset:7168
	global_load_lds_dwordx4 v[66:67], off
	v_lshl_add_u64 v[66:67], s[66:67], 0, v[134:135]
	s_mov_b32 m0, s2
	s_nop 0
	global_load_lds_dwordx4 v[66:67], off
	s_waitcnt vmcnt(8) lgkmcnt(0)
	s_barrier
	v_mfma_f32_16x16x32_bf16 v[66:69], v[2:5], v[34:37], 0
	v_mfma_f32_16x16x32_bf16 v[70:73], v[10:13], v[34:37], 0
	v_mfma_f32_16x16x32_bf16 v[74:77], v[2:5], v[42:45], 0
	v_mfma_f32_16x16x32_bf16 v[78:81], v[10:13], v[42:45], 0
	v_mfma_f32_16x16x32_bf16 v[82:85], v[2:5], v[50:53], 0
	v_mfma_f32_16x16x32_bf16 v[86:89], v[10:13], v[50:53], 0
	v_mfma_f32_16x16x32_bf16 v[90:93], v[2:5], v[58:61], 0
	v_mfma_f32_16x16x32_bf16 v[94:97], v[10:13], v[58:61], 0
	v_mfma_f32_16x16x32_bf16 v[66:69], v[6:9], v[38:41], v[66:69]
	v_mfma_f32_16x16x32_bf16 v[70:73], v[14:17], v[38:41], v[70:73]
	v_mfma_f32_16x16x32_bf16 v[74:77], v[6:9], v[46:49], v[74:77]
	v_mfma_f32_16x16x32_bf16 v[78:81], v[14:17], v[46:49], v[78:81]
	v_mfma_f32_16x16x32_bf16 v[82:85], v[6:9], v[54:57], v[82:85]
	v_mfma_f32_16x16x32_bf16 v[86:89], v[14:17], v[54:57], v[86:89]
	v_mfma_f32_16x16x32_bf16 v[90:93], v[6:9], v[62:65], v[90:93]
	v_mfma_f32_16x16x32_bf16 v[94:97], v[14:17], v[62:65], v[94:97]
	v_mfma_f32_16x16x32_bf16 v[98:101], v[18:21], v[34:37], 0
	v_mfma_f32_16x16x32_bf16 v[34:37], v[26:29], v[34:37], 0
	v_mfma_f32_16x16x32_bf16 v[98:101], v[22:25], v[38:41], v[98:101]
	v_mfma_f32_16x16x32_bf16 v[34:37], v[30:33], v[38:41], v[34:37]
	v_mfma_f32_16x16x32_bf16 v[38:41], v[18:21], v[42:45], 0
	v_mfma_f32_16x16x32_bf16 v[42:45], v[26:29], v[42:45], 0
	v_mfma_f32_16x16x32_bf16 v[38:41], v[22:25], v[46:49], v[38:41]
	v_mfma_f32_16x16x32_bf16 v[42:45], v[30:33], v[46:49], v[42:45]
	v_mfma_f32_16x16x32_bf16 v[46:49], v[18:21], v[50:53], 0
	v_mfma_f32_16x16x32_bf16 v[50:53], v[26:29], v[50:53], 0
	v_mfma_f32_16x16x32_bf16 v[46:49], v[22:25], v[54:57], v[46:49]
	v_mfma_f32_16x16x32_bf16 v[50:53], v[30:33], v[54:57], v[50:53]
	v_mfma_f32_16x16x32_bf16 v[54:57], v[18:21], v[58:61], 0
	v_mfma_f32_16x16x32_bf16 v[58:61], v[26:29], v[58:61], 0
	v_mfma_f32_16x16x32_bf16 v[54:57], v[22:25], v[62:65], v[54:57]
	v_mfma_f32_16x16x32_bf16 v[58:61], v[30:33], v[62:65], v[58:61]
	s_barrier
	s_add_i32 s57, s62, s12
	v_lshl_add_u64 v[212:213], s[60:61], 0, v[132:133]
	s_add_i32 s47, s57, 0x2000
	v_lshl_add_u64 v[142:143], v[212:213], 0, s[28:29]
	s_mov_b32 m0, s57
	v_lshl_add_u64 v[214:215], s[60:61], 0, v[136:137]
	s_add_u32 s66, s60, 0x10100
	ds_read_b128 v[62:65], v150 offset:16384
	ds_read_b128 v[102:105], v150 offset:17408
	ds_read_b128 v[106:109], v150 offset:18432
	ds_read_b128 v[110:113], v150 offset:19456
	ds_read_b128 v[114:117], v150 offset:20480
	ds_read_b128 v[118:121], v150 offset:21504
	ds_read_b128 v[122:125], v150 offset:22528
	ds_read_b128 v[126:129], v150 offset:23552
	global_load_lds_dwordx4 v[142:143], off
	v_lshl_add_u64 v[142:143], v[214:215], 0, s[28:29]
	s_mov_b32 m0, s47
	s_addc_u32 s67, s61, 0
	s_add_i32 s49, s63, s12
	global_load_lds_dwordx4 v[142:143], off
	v_lshl_add_u64 v[142:143], s[66:67], 0, v[132:133]
	s_mov_b32 m0, s49
	s_add_i32 s55, s49, 0x2000
	global_load_lds_dwordx4 v[142:143], off
	v_lshl_add_u64 v[142:143], s[66:67], 0, v[136:137]
	s_mov_b32 m0, s55
	v_lshl_add_u64 v[218:219], s[58:59], 0, v[130:131]
	global_load_lds_dwordx4 v[142:143], off
	v_lshl_add_u64 v[142:143], v[218:219], 0, s[28:29]
	s_mov_b32 m0, s13
	v_lshl_add_u64 v[220:221], s[58:59], 0, v[134:135]
	global_load_lds_dwordx4 v[142:143], off
	v_lshl_add_u64 v[142:143], v[220:221], 0, s[28:29]
	s_mov_b32 m0, s14
	s_nop 0
	global_load_lds_dwordx4 v[142:143], off
	s_waitcnt vmcnt(8) lgkmcnt(0)
	s_barrier
	v_mfma_f32_16x16x32_bf16 v[142:145], v[2:5], v[62:65], 0
	v_mfma_f32_16x16x32_bf16 v[156:159], v[2:5], v[106:109], 0
	v_mfma_f32_16x16x32_bf16 v[164:167], v[2:5], v[114:117], 0
	v_mfma_f32_16x16x32_bf16 v[2:5], v[2:5], v[122:125], 0
	v_mfma_f32_16x16x32_bf16 v[142:145], v[6:9], v[102:105], v[142:145]
	v_mfma_f32_16x16x32_bf16 v[156:159], v[6:9], v[110:113], v[156:159]
	v_mfma_f32_16x16x32_bf16 v[164:167], v[6:9], v[118:121], v[164:167]
	v_mfma_f32_16x16x32_bf16 v[2:5], v[6:9], v[126:129], v[2:5]
	v_mfma_f32_16x16x32_bf16 v[6:9], v[10:13], v[122:125], 0
	v_mfma_f32_16x16x32_bf16 v[152:155], v[10:13], v[62:65], 0
	v_mfma_f32_16x16x32_bf16 v[160:163], v[10:13], v[106:109], 0
	v_mfma_f32_16x16x32_bf16 v[168:171], v[10:13], v[114:117], 0
	v_mfma_f32_16x16x32_bf16 v[6:9], v[14:17], v[126:129], v[6:9]
	v_mfma_f32_16x16x32_bf16 v[152:155], v[14:17], v[102:105], v[152:155]
	v_mfma_f32_16x16x32_bf16 v[160:163], v[14:17], v[110:113], v[160:163]
	v_mfma_f32_16x16x32_bf16 v[168:171], v[14:17], v[118:121], v[168:171]
	v_mfma_f32_16x16x32_bf16 v[10:13], v[18:21], v[62:65], 0
	v_mfma_f32_16x16x32_bf16 v[14:17], v[26:29], v[62:65], 0
	v_mfma_f32_16x16x32_bf16 v[10:13], v[22:25], v[102:105], v[10:13]
	v_mfma_f32_16x16x32_bf16 v[14:17], v[30:33], v[102:105], v[14:17]
	v_mfma_f32_16x16x32_bf16 v[62:65], v[18:21], v[106:109], 0
	v_mfma_f32_16x16x32_bf16 v[102:105], v[26:29], v[106:109], 0
	v_mfma_f32_16x16x32_bf16 v[106:109], v[18:21], v[114:117], 0
	v_mfma_f32_16x16x32_bf16 v[18:21], v[18:21], v[122:125], 0
	v_mfma_f32_16x16x32_bf16 v[62:65], v[22:25], v[110:113], v[62:65]
	v_mfma_f32_16x16x32_bf16 v[102:105], v[30:33], v[110:113], v[102:105]
	v_mfma_f32_16x16x32_bf16 v[106:109], v[22:25], v[118:121], v[106:109]
	v_mfma_f32_16x16x32_bf16 v[110:113], v[26:29], v[114:117], 0
	v_mfma_f32_16x16x32_bf16 v[18:21], v[22:25], v[126:129], v[18:21]
	v_mfma_f32_16x16x32_bf16 v[22:25], v[26:29], v[122:125], 0
	v_mfma_f32_16x16x32_bf16 v[110:113], v[30:33], v[118:121], v[110:113]
	v_mfma_f32_16x16x32_bf16 v[22:25], v[30:33], v[126:129], v[22:25]
	s_barrier
	s_add_i32 s64, 0, 0x18000
	s_add_i32 s70, 0, 0x1c000
	v_add_u32_e32 v151, s64, v147
	v_add_u32_e32 v217, s70, v147
	ds_read_b128 v[26:29], v151
	ds_read_b128 v[30:33], v151 offset:1024
	ds_read_b128 v[114:117], v151 offset:2048
	ds_read_b128 v[118:121], v151 offset:3072
	ds_read_b128 v[122:125], v217
	ds_read_b128 v[126:129], v217 offset:1024
	ds_read_b128 v[172:175], v217 offset:2048
	ds_read_b128 v[176:179], v217 offset:3072
	s_add_u32 s66, s58, 0x10100
	s_addc_u32 s67, s59, 0
	s_mov_b32 m0, s15
	v_lshl_add_u64 v[222:223], s[66:67], 0, v[130:131]
	ds_read_b128 v[180:183], v150 offset:32768
	ds_read_b128 v[184:187], v150 offset:33792
	ds_read_b128 v[188:191], v150 offset:34816
	ds_read_b128 v[192:195], v150 offset:35840
	ds_read_b128 v[196:199], v150 offset:36864
	ds_read_b128 v[200:203], v150 offset:37888
	ds_read_b128 v[204:207], v150 offset:38912
	ds_read_b128 v[208:211], v150 offset:39936
	global_load_lds_dwordx4 v[222:223], off
	v_lshl_add_u64 v[222:223], s[66:67], 0, v[134:135]
	s_mov_b32 m0, s33
	s_nop 0
	global_load_lds_dwordx4 v[222:223], off
	s_waitcnt vmcnt(8) lgkmcnt(0)
	s_barrier
	v_mfma_f32_16x16x32_bf16 v[66:69], v[26:29], v[180:183], v[66:69]
	v_mfma_f32_16x16x32_bf16 v[70:73], v[114:117], v[180:183], v[70:73]
	v_mfma_f32_16x16x32_bf16 v[74:77], v[26:29], v[188:191], v[74:77]
	v_mfma_f32_16x16x32_bf16 v[78:81], v[114:117], v[188:191], v[78:81]
	v_mfma_f32_16x16x32_bf16 v[82:85], v[26:29], v[196:199], v[82:85]
	v_mfma_f32_16x16x32_bf16 v[86:89], v[114:117], v[196:199], v[86:89]
	v_mfma_f32_16x16x32_bf16 v[90:93], v[26:29], v[204:207], v[90:93]
	v_mfma_f32_16x16x32_bf16 v[94:97], v[114:117], v[204:207], v[94:97]
	v_mfma_f32_16x16x32_bf16 v[66:69], v[30:33], v[184:187], v[66:69]
	v_mfma_f32_16x16x32_bf16 v[70:73], v[118:121], v[184:187], v[70:73]
	v_mfma_f32_16x16x32_bf16 v[74:77], v[30:33], v[192:195], v[74:77]
	v_mfma_f32_16x16x32_bf16 v[78:81], v[118:121], v[192:195], v[78:81]
	v_mfma_f32_16x16x32_bf16 v[82:85], v[30:33], v[200:203], v[82:85]
	v_mfma_f32_16x16x32_bf16 v[86:89], v[118:121], v[200:203], v[86:89]
	v_mfma_f32_16x16x32_bf16 v[90:93], v[30:33], v[208:211], v[90:93]
	v_mfma_f32_16x16x32_bf16 v[94:97], v[118:121], v[208:211], v[94:97]
	v_mfma_f32_16x16x32_bf16 v[98:101], v[122:125], v[180:183], v[98:101]
	v_mfma_f32_16x16x32_bf16 v[34:37], v[172:175], v[180:183], v[34:37]
	v_mfma_f32_16x16x32_bf16 v[38:41], v[122:125], v[188:191], v[38:41]
	v_mfma_f32_16x16x32_bf16 v[42:45], v[172:175], v[188:191], v[42:45]
	v_mfma_f32_16x16x32_bf16 v[46:49], v[122:125], v[196:199], v[46:49]
	v_mfma_f32_16x16x32_bf16 v[50:53], v[172:175], v[196:199], v[50:53]
	v_mfma_f32_16x16x32_bf16 v[54:57], v[122:125], v[204:207], v[54:57]
	v_mfma_f32_16x16x32_bf16 v[58:61], v[172:175], v[204:207], v[58:61]
	v_mfma_f32_16x16x32_bf16 v[98:101], v[126:129], v[184:187], v[98:101]
	v_mfma_f32_16x16x32_bf16 v[34:37], v[176:179], v[184:187], v[34:37]
	v_mfma_f32_16x16x32_bf16 v[38:41], v[126:129], v[192:195], v[38:41]
	v_mfma_f32_16x16x32_bf16 v[42:45], v[176:179], v[192:195], v[42:45]
	v_mfma_f32_16x16x32_bf16 v[46:49], v[126:129], v[200:203], v[46:49]
	v_mfma_f32_16x16x32_bf16 v[50:53], v[176:179], v[200:203], v[50:53]
	v_mfma_f32_16x16x32_bf16 v[54:57], v[126:129], v[208:211], v[54:57]
	v_mfma_f32_16x16x32_bf16 v[58:61], v[176:179], v[208:211], v[58:61]
	s_barrier
	s_add_i32 s66, s64, s12
	s_add_i32 s64, s66, 0x2000
	v_lshl_add_u64 v[212:213], v[212:213], 0, s[30:31]
	s_mov_b32 m0, s66
	s_add_u32 s68, s60, 0x10180
	ds_read_b128 v[180:183], v150 offset:49152
	ds_read_b128 v[184:187], v150 offset:50176
	ds_read_b128 v[188:191], v150 offset:51200
	ds_read_b128 v[192:195], v150 offset:52224
	ds_read_b128 v[196:199], v150 offset:53248
	ds_read_b128 v[200:203], v150 offset:54272
	ds_read_b128 v[204:207], v150 offset:55296
	ds_read_b128 v[208:211], v150 offset:56320
	global_load_lds_dwordx4 v[212:213], off
	v_lshl_add_u64 v[212:213], v[214:215], 0, s[30:31]
	s_mov_b32 m0, s64
	s_addc_u32 s69, s61, 0
	s_add_i32 s60, s70, s12
	global_load_lds_dwordx4 v[212:213], off
	v_lshl_add_u64 v[212:213], s[68:69], 0, v[132:133]
	s_mov_b32 m0, s60
	s_add_i32 s61, s60, 0x2000
	global_load_lds_dwordx4 v[212:213], off
	v_lshl_add_u64 v[212:213], s[68:69], 0, v[136:137]
	s_mov_b32 m0, s61
	s_nop 0
	global_load_lds_dwordx4 v[212:213], off
	v_lshl_add_u64 v[212:213], v[218:219], 0, s[30:31]
	s_mov_b32 m0, s42
	s_nop 0
	global_load_lds_dwordx4 v[212:213], off
	v_lshl_add_u64 v[212:213], v[220:221], 0, s[30:31]
	s_mov_b32 m0, s43
	s_nop 0
	global_load_lds_dwordx4 v[212:213], off
	s_waitcnt vmcnt(8) lgkmcnt(0)
	s_barrier
	v_mfma_f32_16x16x32_bf16 v[2:5], v[26:29], v[204:207], v[2:5]
	v_mfma_f32_16x16x32_bf16 v[6:9], v[114:117], v[204:207], v[6:9]
	v_mfma_f32_16x16x32_bf16 v[142:145], v[26:29], v[180:183], v[142:145]
	v_mfma_f32_16x16x32_bf16 v[152:155], v[114:117], v[180:183], v[152:155]
	v_mfma_f32_16x16x32_bf16 v[156:159], v[26:29], v[188:191], v[156:159]
	v_mfma_f32_16x16x32_bf16 v[160:163], v[114:117], v[188:191], v[160:163]
	v_mfma_f32_16x16x32_bf16 v[164:167], v[26:29], v[196:199], v[164:167]
	v_mfma_f32_16x16x32_bf16 v[168:171], v[114:117], v[196:199], v[168:171]
	v_mfma_f32_16x16x32_bf16 v[2:5], v[30:33], v[208:211], v[2:5]
	v_mfma_f32_16x16x32_bf16 v[6:9], v[118:121], v[208:211], v[6:9]
	v_mfma_f32_16x16x32_bf16 v[142:145], v[30:33], v[184:187], v[142:145]
	v_mfma_f32_16x16x32_bf16 v[152:155], v[118:121], v[184:187], v[152:155]
	v_mfma_f32_16x16x32_bf16 v[156:159], v[30:33], v[192:195], v[156:159]
	v_mfma_f32_16x16x32_bf16 v[160:163], v[118:121], v[192:195], v[160:163]
	v_mfma_f32_16x16x32_bf16 v[164:167], v[30:33], v[200:203], v[164:167]
	v_mfma_f32_16x16x32_bf16 v[168:171], v[118:121], v[200:203], v[168:171]
	v_mfma_f32_16x16x32_bf16 v[10:13], v[122:125], v[180:183], v[10:13]
	v_mfma_f32_16x16x32_bf16 v[14:17], v[172:175], v[180:183], v[14:17]
	v_mfma_f32_16x16x32_bf16 v[26:29], v[122:125], v[188:191], v[62:65]
	v_mfma_f32_16x16x32_bf16 v[30:33], v[172:175], v[188:191], v[102:105]
	v_mfma_f32_16x16x32_bf16 v[62:65], v[122:125], v[196:199], v[106:109]
	v_mfma_f32_16x16x32_bf16 v[102:105], v[172:175], v[196:199], v[110:113]
	v_mfma_f32_16x16x32_bf16 v[18:21], v[122:125], v[204:207], v[18:21]
	v_mfma_f32_16x16x32_bf16 v[22:25], v[172:175], v[204:207], v[22:25]
	v_mfma_f32_16x16x32_bf16 v[10:13], v[126:129], v[184:187], v[10:13]
	v_mfma_f32_16x16x32_bf16 v[14:17], v[176:179], v[184:187], v[14:17]
	v_mfma_f32_16x16x32_bf16 v[26:29], v[126:129], v[192:195], v[26:29]
	v_mfma_f32_16x16x32_bf16 v[30:33], v[176:179], v[192:195], v[30:33]
	v_mfma_f32_16x16x32_bf16 v[62:65], v[126:129], v[200:203], v[62:65]
	v_mfma_f32_16x16x32_bf16 v[102:105], v[176:179], v[200:203], v[102:105]
	v_mfma_f32_16x16x32_bf16 v[18:21], v[126:129], v[208:211], v[18:21]
	v_mfma_f32_16x16x32_bf16 v[22:25], v[176:179], v[208:211], v[22:25]
	s_barrier
	ds_read_b128 v[106:109], v148
	ds_read_b128 v[110:113], v148 offset:1024
	ds_read_b128 v[114:117], v148 offset:2048
	ds_read_b128 v[118:121], v148 offset:3072
	ds_read_b128 v[122:125], v149
	ds_read_b128 v[126:129], v149 offset:1024
	ds_read_b128 v[172:175], v149 offset:2048
	ds_read_b128 v[176:179], v149 offset:3072
	s_add_u32 s58, s58, 0x10180
	s_addc_u32 s59, s59, 0
	s_mov_b32 m0, s65
	v_lshl_add_u64 v[212:213], s[58:59], 0, v[130:131]
	ds_read_b128 v[180:183], v150
	ds_read_b128 v[184:187], v150 offset:1024
	ds_read_b128 v[188:191], v150 offset:2048
	ds_read_b128 v[192:195], v150 offset:3072
	ds_read_b128 v[196:199], v150 offset:4096
	ds_read_b128 v[200:203], v150 offset:5120
	ds_read_b128 v[204:207], v150 offset:6144
	ds_read_b128 v[208:211], v150 offset:7168
	global_load_lds_dwordx4 v[212:213], off
	v_lshl_add_u64 v[212:213], s[58:59], 0, v[134:135]
	s_mov_b32 m0, s2
	s_nop 0
	global_load_lds_dwordx4 v[212:213], off
	s_waitcnt vmcnt(8) lgkmcnt(0)
	s_barrier
	v_mfma_f32_16x16x32_bf16 v[90:93], v[106:109], v[204:207], v[90:93]
	v_mfma_f32_16x16x32_bf16 v[66:69], v[106:109], v[180:183], v[66:69]
	v_mfma_f32_16x16x32_bf16 v[70:73], v[114:117], v[180:183], v[70:73]
	v_mfma_f32_16x16x32_bf16 v[74:77], v[106:109], v[188:191], v[74:77]
	v_mfma_f32_16x16x32_bf16 v[78:81], v[114:117], v[188:191], v[78:81]
	v_mfma_f32_16x16x32_bf16 v[82:85], v[106:109], v[196:199], v[82:85]
	v_mfma_f32_16x16x32_bf16 v[86:89], v[114:117], v[196:199], v[86:89]
	v_mfma_f32_16x16x32_bf16 v[212:215], v[110:113], v[208:211], v[90:93]
	v_mfma_f32_16x16x32_bf16 v[90:93], v[114:117], v[204:207], v[94:97]
	v_mfma_f32_16x16x32_bf16 v[66:69], v[110:113], v[184:187], v[66:69]
	v_mfma_f32_16x16x32_bf16 v[70:73], v[118:121], v[184:187], v[70:73]
	v_mfma_f32_16x16x32_bf16 v[74:77], v[110:113], v[192:195], v[74:77]
	v_mfma_f32_16x16x32_bf16 v[78:81], v[118:121], v[192:195], v[78:81]
	v_mfma_f32_16x16x32_bf16 v[82:85], v[110:113], v[200:203], v[82:85]
	v_mfma_f32_16x16x32_bf16 v[86:89], v[118:121], v[200:203], v[86:89]
	v_mfma_f32_16x16x32_bf16 v[94:97], v[118:121], v[208:211], v[90:93]
	v_mfma_f32_16x16x32_bf16 v[34:37], v[172:175], v[180:183], v[34:37]
	v_mfma_f32_16x16x32_bf16 v[38:41], v[122:125], v[188:191], v[38:41]
	v_mfma_f32_16x16x32_bf16 v[42:45], v[172:175], v[188:191], v[42:45]
	v_mfma_f32_16x16x32_bf16 v[46:49], v[122:125], v[196:199], v[46:49]
	v_mfma_f32_16x16x32_bf16 v[50:53], v[172:175], v[196:199], v[50:53]
	v_mfma_f32_16x16x32_bf16 v[54:57], v[122:125], v[204:207], v[54:57]
	v_mfma_f32_16x16x32_bf16 v[58:61], v[172:175], v[204:207], v[58:61]
	v_mfma_f32_16x16x32_bf16 v[90:93], v[122:125], v[180:183], v[98:101]
	v_mfma_f32_16x16x32_bf16 v[34:37], v[176:179], v[184:187], v[34:37]
	v_mfma_f32_16x16x32_bf16 v[38:41], v[126:129], v[192:195], v[38:41]
	v_mfma_f32_16x16x32_bf16 v[42:45], v[176:179], v[192:195], v[42:45]
	v_mfma_f32_16x16x32_bf16 v[46:49], v[126:129], v[200:203], v[46:49]
	v_mfma_f32_16x16x32_bf16 v[50:53], v[176:179], v[200:203], v[50:53]
	v_mfma_f32_16x16x32_bf16 v[54:57], v[126:129], v[208:211], v[54:57]
	v_mfma_f32_16x16x32_bf16 v[58:61], v[176:179], v[208:211], v[58:61]
	v_mfma_f32_16x16x32_bf16 v[218:221], v[126:129], v[184:187], v[90:93]
	s_barrier
	s_mov_b32 m0, s57
	v_lshl_add_u64 v[248:249], s[6:7], 0, v[132:133]
	s_add_u32 s58, s6, 0x10000
	ds_read_b128 v[90:93], v150 offset:16384
	ds_read_b128 v[98:101], v150 offset:17408
	ds_read_b128 v[180:183], v150 offset:18432
	ds_read_b128 v[184:187], v150 offset:19456
	ds_read_b128 v[188:191], v150 offset:20480
	ds_read_b128 v[192:195], v150 offset:21504
	ds_read_b128 v[196:199], v150 offset:22528
	ds_read_b128 v[200:203], v150 offset:23552
	global_load_lds_dwordx4 v[248:249], off
	v_lshl_add_u64 v[250:251], s[6:7], 0, v[136:137]
	s_mov_b32 m0, s47
	s_addc_u32 s59, s7, 0
	global_load_lds_dwordx4 v[250:251], off
	v_lshl_add_u64 v[204:205], s[58:59], 0, v[132:133]
	s_mov_b32 m0, s49
	v_lshl_add_u64 v[252:253], s[50:51], 0, v[130:131]
	global_load_lds_dwordx4 v[204:205], off
	v_lshl_add_u64 v[204:205], s[58:59], 0, v[136:137]
	s_mov_b32 m0, s55
	v_lshl_add_u64 v[226:227], s[50:51], 0, v[134:135]
	global_load_lds_dwordx4 v[204:205], off
	s_mov_b32 m0, s13
	s_nop 0
	global_load_lds_dwordx4 v[252:253], off
	s_mov_b32 m0, s14
	s_nop 0
	global_load_lds_dwordx4 v[226:227], off
	s_waitcnt vmcnt(8) lgkmcnt(0)
	s_barrier
	v_mfma_f32_16x16x32_bf16 v[2:5], v[106:109], v[196:199], v[2:5]
	v_mfma_f32_16x16x32_bf16 v[6:9], v[114:117], v[196:199], v[6:9]
	v_mfma_f32_16x16x32_bf16 v[142:145], v[106:109], v[90:93], v[142:145]
	v_mfma_f32_16x16x32_bf16 v[152:155], v[114:117], v[90:93], v[152:155]
	v_mfma_f32_16x16x32_bf16 v[156:159], v[106:109], v[180:183], v[156:159]
	v_mfma_f32_16x16x32_bf16 v[160:163], v[114:117], v[180:183], v[160:163]
	v_mfma_f32_16x16x32_bf16 v[164:167], v[106:109], v[188:191], v[164:167]
	v_mfma_f32_16x16x32_bf16 v[168:171], v[114:117], v[188:191], v[168:171]
	v_mfma_f32_16x16x32_bf16 v[2:5], v[110:113], v[200:203], v[2:5]
	v_mfma_f32_16x16x32_bf16 v[6:9], v[118:121], v[200:203], v[6:9]
	v_mfma_f32_16x16x32_bf16 v[142:145], v[110:113], v[98:101], v[142:145]
	v_mfma_f32_16x16x32_bf16 v[152:155], v[118:121], v[98:101], v[152:155]
	v_mfma_f32_16x16x32_bf16 v[156:159], v[110:113], v[184:187], v[156:159]
	v_mfma_f32_16x16x32_bf16 v[160:163], v[118:121], v[184:187], v[160:163]
	v_mfma_f32_16x16x32_bf16 v[164:167], v[110:113], v[192:195], v[164:167]
	v_mfma_f32_16x16x32_bf16 v[168:171], v[118:121], v[192:195], v[168:171]
	v_mfma_f32_16x16x32_bf16 v[10:13], v[122:125], v[90:93], v[10:13]
	v_mfma_f32_16x16x32_bf16 v[204:207], v[126:129], v[98:101], v[10:13]
	v_mfma_f32_16x16x32_bf16 v[10:13], v[172:175], v[90:93], v[14:17]
	v_mfma_f32_16x16x32_bf16 v[14:17], v[176:179], v[98:101], v[10:13]
	v_mfma_f32_16x16x32_bf16 v[10:13], v[122:125], v[180:183], v[26:29]
	v_mfma_f32_16x16x32_bf16 v[208:211], v[126:129], v[184:187], v[10:13]
	v_mfma_f32_16x16x32_bf16 v[10:13], v[172:175], v[180:183], v[30:33]
	v_mfma_f32_16x16x32_bf16 v[30:33], v[176:179], v[184:187], v[10:13]
	v_mfma_f32_16x16x32_bf16 v[10:13], v[122:125], v[188:191], v[62:65]
	v_mfma_f32_16x16x32_bf16 v[180:183], v[126:129], v[192:195], v[10:13]
	v_mfma_f32_16x16x32_bf16 v[10:13], v[172:175], v[188:191], v[102:105]
	v_mfma_f32_16x16x32_bf16 v[184:187], v[176:179], v[192:195], v[10:13]
	v_mfma_f32_16x16x32_bf16 v[10:13], v[122:125], v[196:199], v[18:21]
	v_mfma_f32_16x16x32_bf16 v[188:191], v[126:129], v[200:203], v[10:13]
	v_mfma_f32_16x16x32_bf16 v[10:13], v[172:175], v[196:199], v[22:25]
	v_mfma_f32_16x16x32_bf16 v[172:175], v[176:179], v[200:203], v[10:13]
	s_barrier
	s_nop 4
	ds_read_b128 v[10:13], v151
	ds_read_b128 v[22:25], v151 offset:1024
	ds_read_b128 v[62:65], v151 offset:2048
	ds_read_b128 v[176:179], v151 offset:3072
	ds_read_b128 v[192:195], v217
	ds_read_b128 v[196:199], v217 offset:1024
	ds_read_b128 v[200:203], v217 offset:2048
	ds_read_b128 v[222:225], v217 offset:3072
	s_add_u32 s58, s50, 0x10000
	s_addc_u32 s59, s51, 0
	s_mov_b32 m0, s15
	v_lshl_add_u64 v[90:91], s[58:59], 0, v[130:131]
	ds_read_b128 v[18:21], v150 offset:32768
	ds_read_b128 v[26:29], v150 offset:33792
	ds_read_b128 v[102:105], v150 offset:34816
	ds_read_b128 v[228:231], v150 offset:35840
	ds_read_b128 v[232:235], v150 offset:36864
	ds_read_b128 v[236:239], v150 offset:37888
	ds_read_b128 v[240:243], v150 offset:38912
	ds_read_b128 v[244:247], v150 offset:39936
	global_load_lds_dwordx4 v[90:91], off
	v_lshl_add_u64 v[90:91], s[58:59], 0, v[134:135]
	s_mov_b32 m0, s33
	s_nop 0
	global_load_lds_dwordx4 v[90:91], off
	s_waitcnt vmcnt(8) lgkmcnt(0)
	s_barrier
	v_mfma_f32_16x16x32_bf16 v[66:69], v[10:13], v[18:21], v[66:69]
	v_mfma_f32_16x16x32_bf16 v[122:125], v[22:25], v[26:29], v[66:69]
	v_mfma_f32_16x16x32_bf16 v[66:69], v[62:65], v[18:21], v[70:73]
	v_mfma_f32_16x16x32_bf16 v[114:117], v[176:179], v[26:29], v[66:69]
	v_mfma_f32_16x16x32_bf16 v[66:69], v[10:13], v[102:105], v[74:77]
	v_mfma_f32_16x16x32_bf16 v[106:109], v[22:25], v[228:231], v[66:69]
	v_mfma_f32_16x16x32_bf16 v[66:69], v[62:65], v[102:105], v[78:81]
	v_mfma_f32_16x16x32_bf16 v[98:101], v[176:179], v[228:231], v[66:69]
	v_mfma_f32_16x16x32_bf16 v[66:69], v[10:13], v[232:235], v[82:85]
	v_mfma_f32_16x16x32_bf16 v[90:93], v[22:25], v[236:239], v[66:69]
	v_mfma_f32_16x16x32_bf16 v[66:69], v[62:65], v[232:235], v[86:89]
	v_mfma_f32_16x16x32_bf16 v[82:85], v[176:179], v[236:239], v[66:69]
	v_mfma_f32_16x16x32_bf16 v[66:69], v[10:13], v[240:243], v[212:215]
	v_mfma_f32_16x16x32_bf16 v[74:77], v[22:25], v[244:247], v[66:69]
	v_mfma_f32_16x16x32_bf16 v[66:69], v[62:65], v[240:243], v[94:97]
	v_mfma_f32_16x16x32_bf16 v[66:69], v[176:179], v[244:247], v[66:69]
	v_mfma_f32_16x16x32_bf16 v[70:73], v[192:195], v[18:21], v[218:221]
	v_mfma_f32_16x16x32_bf16 v[18:21], v[200:203], v[18:21], v[34:37]
	v_mfma_f32_16x16x32_bf16 v[118:121], v[222:225], v[26:29], v[18:21]
	v_mfma_f32_16x16x32_bf16 v[18:21], v[192:195], v[102:105], v[38:41]
	v_mfma_f32_16x16x32_bf16 v[110:113], v[196:199], v[228:231], v[18:21]
	v_mfma_f32_16x16x32_bf16 v[18:21], v[200:203], v[102:105], v[42:45]
	v_mfma_f32_16x16x32_bf16 v[102:105], v[222:225], v[228:231], v[18:21]
	v_mfma_f32_16x16x32_bf16 v[18:21], v[192:195], v[232:235], v[46:49]
	v_mfma_f32_16x16x32_bf16 v[94:97], v[196:199], v[236:239], v[18:21]
	v_mfma_f32_16x16x32_bf16 v[18:21], v[200:203], v[232:235], v[50:53]
	v_mfma_f32_16x16x32_bf16 v[86:89], v[222:225], v[236:239], v[18:21]
	v_mfma_f32_16x16x32_bf16 v[18:21], v[192:195], v[240:243], v[54:57]
	v_mfma_f32_16x16x32_bf16 v[78:81], v[196:199], v[244:247], v[18:21]
	v_mfma_f32_16x16x32_bf16 v[18:21], v[200:203], v[240:243], v[58:61]
	v_mfma_f32_16x16x32_bf16 v[126:129], v[196:199], v[26:29], v[70:73]
	v_mfma_f32_16x16x32_bf16 v[70:73], v[222:225], v[244:247], v[18:21]
	s_barrier
	s_mov_b32 m0, s66
	s_nop 2
	v_lshl_add_u64 v[18:19], v[248:249], 0, s[22:23]
	s_add_u32 s6, s6, 0x10080
	ds_read_b128 v[38:41], v150 offset:49152
	ds_read_b128 v[46:49], v150 offset:50176
	ds_read_b128 v[212:215], v150 offset:51200
	ds_read_b128 v[218:221], v150 offset:52224
	ds_read_b128 v[228:231], v150 offset:53248
	ds_read_b128 v[232:235], v150 offset:54272
	ds_read_b128 v[236:239], v150 offset:55296
	ds_read_b128 v[240:243], v150 offset:56320
	global_load_lds_dwordx4 v[18:19], off
	v_lshl_add_u64 v[18:19], v[250:251], 0, s[22:23]
	s_mov_b32 m0, s64
	s_addc_u32 s7, s7, 0
	global_load_lds_dwordx4 v[18:19], off
	v_lshl_add_u64 v[18:19], s[6:7], 0, v[132:133]
	s_mov_b32 m0, s60
	s_nop 0
	global_load_lds_dwordx4 v[18:19], off
	v_lshl_add_u64 v[18:19], s[6:7], 0, v[136:137]
	s_mov_b32 m0, s61
	s_nop 0
	global_load_lds_dwordx4 v[18:19], off
	v_lshl_add_u64 v[18:19], v[252:253], 0, s[22:23]
	s_mov_b32 m0, s42
	s_nop 0
	global_load_lds_dwordx4 v[18:19], off
	v_lshl_add_u64 v[18:19], v[226:227], 0, s[22:23]
	s_mov_b32 m0, s43
	s_nop 0
	global_load_lds_dwordx4 v[18:19], off
	s_waitcnt vmcnt(8) lgkmcnt(0)
	s_barrier
	v_mfma_f32_16x16x32_bf16 v[18:21], v[10:13], v[38:41], v[142:145]
	v_mfma_f32_16x16x32_bf16 v[58:61], v[22:25], v[46:49], v[18:21]
	v_mfma_f32_16x16x32_bf16 v[18:21], v[62:65], v[38:41], v[152:155]
	v_mfma_f32_16x16x32_bf16 v[50:53], v[176:179], v[46:49], v[18:21]
	v_mfma_f32_16x16x32_bf16 v[18:21], v[10:13], v[212:215], v[156:159]
	v_mfma_f32_16x16x32_bf16 v[42:45], v[22:25], v[218:221], v[18:21]
	v_mfma_f32_16x16x32_bf16 v[18:21], v[62:65], v[212:215], v[160:163]
	v_mfma_f32_16x16x32_bf16 v[34:37], v[176:179], v[218:221], v[18:21]
	v_mfma_f32_16x16x32_bf16 v[18:21], v[10:13], v[228:231], v[164:167]
	v_mfma_f32_16x16x32_bf16 v[2:5], v[10:13], v[236:239], v[2:5]
	v_mfma_f32_16x16x32_bf16 v[26:29], v[22:25], v[232:235], v[18:21]
	v_mfma_f32_16x16x32_bf16 v[18:21], v[62:65], v[228:231], v[168:171]
	v_mfma_f32_16x16x32_bf16 v[10:13], v[22:25], v[240:243], v[2:5]
	v_mfma_f32_16x16x32_bf16 v[2:5], v[62:65], v[236:239], v[6:9]
	v_mfma_f32_16x16x32_bf16 v[18:21], v[176:179], v[232:235], v[18:21]
	v_mfma_f32_16x16x32_bf16 v[2:5], v[176:179], v[240:243], v[2:5]
	v_mfma_f32_16x16x32_bf16 v[6:9], v[192:195], v[38:41], v[204:207]
	v_mfma_f32_16x16x32_bf16 v[62:65], v[196:199], v[46:49], v[6:9]
	v_mfma_f32_16x16x32_bf16 v[6:9], v[200:203], v[38:41], v[14:17]
	v_mfma_f32_16x16x32_bf16 v[54:57], v[222:225], v[46:49], v[6:9]
	v_mfma_f32_16x16x32_bf16 v[6:9], v[192:195], v[212:215], v[208:211]
	v_mfma_f32_16x16x32_bf16 v[46:49], v[196:199], v[218:221], v[6:9]
	v_mfma_f32_16x16x32_bf16 v[6:9], v[200:203], v[212:215], v[30:33]
	v_mfma_f32_16x16x32_bf16 v[38:41], v[222:225], v[218:221], v[6:9]
	v_mfma_f32_16x16x32_bf16 v[6:9], v[192:195], v[228:231], v[180:183]
	v_mfma_f32_16x16x32_bf16 v[30:33], v[196:199], v[232:235], v[6:9]
	v_mfma_f32_16x16x32_bf16 v[6:9], v[200:203], v[228:231], v[184:187]
	v_mfma_f32_16x16x32_bf16 v[22:25], v[222:225], v[232:235], v[6:9]
	v_mfma_f32_16x16x32_bf16 v[6:9], v[192:195], v[236:239], v[188:191]
	v_mfma_f32_16x16x32_bf16 v[14:17], v[196:199], v[240:243], v[6:9]
	v_mfma_f32_16x16x32_bf16 v[6:9], v[200:203], v[236:239], v[172:175]
	v_mfma_f32_16x16x32_bf16 v[6:9], v[222:225], v[240:243], v[6:9]
	s_barrier
	s_andn2_b64 vcc, exec, s[24:25]
	s_cbranch_vccnz .LBB0_372
	s_barrier

.LBB0_619:
	v_add_u32_e32 v153, s44, v151
	ds_read_b128 v[154:157], v153
	ds_read_b128 v[158:161], v153 offset:1024
	ds_read_b128 v[162:165], v153 offset:2048
	ds_read_b128 v[166:169], v153 offset:3072
	v_add_u32_e32 v153, s45, v151
	s_add_u32 s26, s18, s24
	ds_read_b128 v[170:173], v153
	ds_read_b128 v[174:177], v153 offset:1024
	ds_read_b128 v[178:181], v153 offset:2048
	ds_read_b128 v[182:185], v153 offset:3072
	s_addc_u32 s27, s19, s25
	s_add_u32 s26, s26, 0x100
	s_addc_u32 s27, s27, 0
	s_add_u32 s51, s48, s24
	s_addc_u32 s52, s49, s25
	s_cmpk_eq_i32 s24, 0x1500
	s_cselect_b32 s29, s23, s27
	s_cselect_b32 s28, s22, s26
	s_cselect_b32 s27, s9, s52
	s_cselect_b32 s26, s8, s51
	v_lshl_add_u64 v[218:219], v[146:147], 0, s[24:25]
	s_add_i32 m0, s33, 0xc000
	ds_read_b128 v[186:189], v152
	ds_read_b128 v[190:193], v152 offset:1024
	ds_read_b128 v[194:197], v152 offset:2048
	ds_read_b128 v[198:201], v152 offset:3072
	ds_read_b128 v[202:205], v152 offset:4096
	ds_read_b128 v[206:209], v152 offset:5120
	ds_read_b128 v[210:213], v152 offset:6144
	ds_read_b128 v[214:217], v152 offset:7168
	global_load_lds_dwordx4 v[218:219], off
	v_lshl_add_u64 v[218:219], v[148:149], 0, s[24:25]
	s_add_i32 m0, s33, 0xe000
	s_nop 0
	global_load_lds_dwordx4 v[218:219], off
	s_waitcnt vmcnt(8) lgkmcnt(0)
	s_barrier
	v_mfma_f32_16x16x32_bf16 v[126:129], v[154:157], v[186:189], v[126:129]
	v_mfma_f32_16x16x32_bf16 v[122:125], v[162:165], v[186:189], v[122:125]
	v_mfma_f32_16x16x32_bf16 v[110:113], v[154:157], v[194:197], v[110:113]
	v_mfma_f32_16x16x32_bf16 v[106:109], v[162:165], v[194:197], v[106:109]
	v_mfma_f32_16x16x32_bf16 v[94:97], v[154:157], v[202:205], v[94:97]
	v_mfma_f32_16x16x32_bf16 v[90:93], v[162:165], v[202:205], v[90:93]
	v_mfma_f32_16x16x32_bf16 v[78:81], v[154:157], v[210:213], v[78:81]
	v_mfma_f32_16x16x32_bf16 v[74:77], v[162:165], v[210:213], v[74:77]
	v_mfma_f32_16x16x32_bf16 v[126:129], v[158:161], v[190:193], v[126:129]
	v_mfma_f32_16x16x32_bf16 v[122:125], v[166:169], v[190:193], v[122:125]
	v_mfma_f32_16x16x32_bf16 v[110:113], v[158:161], v[198:201], v[110:113]
	v_mfma_f32_16x16x32_bf16 v[106:109], v[166:169], v[198:201], v[106:109]
	v_mfma_f32_16x16x32_bf16 v[94:97], v[158:161], v[206:209], v[94:97]
	v_mfma_f32_16x16x32_bf16 v[90:93], v[166:169], v[206:209], v[90:93]
	v_mfma_f32_16x16x32_bf16 v[78:81], v[158:161], v[214:217], v[78:81]
	v_mfma_f32_16x16x32_bf16 v[74:77], v[166:169], v[214:217], v[74:77]
	v_mfma_f32_16x16x32_bf16 v[118:121], v[170:173], v[186:189], v[118:121]
	v_mfma_f32_16x16x32_bf16 v[114:117], v[178:181], v[186:189], v[114:117]
	v_mfma_f32_16x16x32_bf16 v[102:105], v[170:173], v[194:197], v[102:105]
	v_mfma_f32_16x16x32_bf16 v[98:101], v[178:181], v[194:197], v[98:101]
	v_mfma_f32_16x16x32_bf16 v[86:89], v[170:173], v[202:205], v[86:89]
	v_mfma_f32_16x16x32_bf16 v[82:85], v[178:181], v[202:205], v[82:85]
	v_mfma_f32_16x16x32_bf16 v[70:73], v[170:173], v[210:213], v[70:73]
	v_mfma_f32_16x16x32_bf16 v[66:69], v[178:181], v[210:213], v[66:69]
	v_mfma_f32_16x16x32_bf16 v[118:121], v[174:177], v[190:193], v[118:121]
	v_mfma_f32_16x16x32_bf16 v[114:117], v[182:185], v[190:193], v[114:117]
	v_mfma_f32_16x16x32_bf16 v[102:105], v[174:177], v[198:201], v[102:105]
	v_mfma_f32_16x16x32_bf16 v[98:101], v[182:185], v[198:201], v[98:101]
	v_mfma_f32_16x16x32_bf16 v[86:89], v[174:177], v[206:209], v[86:89]
	v_mfma_f32_16x16x32_bf16 v[82:85], v[182:185], v[206:209], v[82:85]
	v_mfma_f32_16x16x32_bf16 v[70:73], v[174:177], v[214:217], v[70:73]
	v_mfma_f32_16x16x32_bf16 v[66:69], v[182:185], v[214:217], v[66:69]
	s_barrier
	s_add_i32 s51, s44, s13
	s_add_u32 s98, s26, s20
	s_addc_u32 s99, s27, s21
	s_mov_b32 m0, s51
	ds_read_b128 v[186:189], v152 offset:16384
	ds_read_b128 v[190:193], v152 offset:17408
	ds_read_b128 v[194:197], v152 offset:18432
	ds_read_b128 v[198:201], v152 offset:19456
	ds_read_b128 v[202:205], v152 offset:20480
	ds_read_b128 v[206:209], v152 offset:21504
	ds_read_b128 v[210:213], v152 offset:22528
	ds_read_b128 v[214:217], v152 offset:23552
	global_load_lds_dwordx4 v132, s[26:27]
	s_add_i32 m0, s51, 0x2000
	s_add_u32 s52, s26, 0xb0000
	s_addc_u32 s53, s27, 0
	s_add_i32 s51, s45, s13
	global_load_lds_dwordx4 v136, s[26:27]
	s_mov_b32 m0, s51
	s_nop 0
	global_load_lds_dwordx4 v132, s[52:53]
	s_add_i32 m0, s51, 0x2000
	s_nop 0
	global_load_lds_dwordx4 v136, s[52:53]
	s_add_u32 s100, s28, s20
	s_addc_u32 s101, s29, s21
	s_mov_b32 m0, s33
	s_nop 0
	global_load_lds_dwordx4 v130, s[28:29]
	s_mov_b32 m0, s14
	s_nop 0
	global_load_lds_dwordx4 v134, s[28:29]
	s_waitcnt vmcnt(8) lgkmcnt(0)
	s_barrier
	v_mfma_f32_16x16x32_bf16 v[62:65], v[154:157], v[186:189], v[62:65]
	v_mfma_f32_16x16x32_bf16 v[58:61], v[162:165], v[186:189], v[58:61]
	v_mfma_f32_16x16x32_bf16 v[46:49], v[154:157], v[194:197], v[46:49]
	v_mfma_f32_16x16x32_bf16 v[42:45], v[162:165], v[194:197], v[42:45]
	v_mfma_f32_16x16x32_bf16 v[30:33], v[154:157], v[202:205], v[30:33]
	v_mfma_f32_16x16x32_bf16 v[26:29], v[162:165], v[202:205], v[26:29]
	v_mfma_f32_16x16x32_bf16 v[14:17], v[154:157], v[210:213], v[14:17]
	v_mfma_f32_16x16x32_bf16 v[10:13], v[162:165], v[210:213], v[10:13]
	v_mfma_f32_16x16x32_bf16 v[62:65], v[158:161], v[190:193], v[62:65]
	v_mfma_f32_16x16x32_bf16 v[58:61], v[166:169], v[190:193], v[58:61]
	v_mfma_f32_16x16x32_bf16 v[46:49], v[158:161], v[198:201], v[46:49]
	v_mfma_f32_16x16x32_bf16 v[42:45], v[166:169], v[198:201], v[42:45]
	v_mfma_f32_16x16x32_bf16 v[30:33], v[158:161], v[206:209], v[30:33]
	v_mfma_f32_16x16x32_bf16 v[26:29], v[166:169], v[206:209], v[26:29]
	v_mfma_f32_16x16x32_bf16 v[14:17], v[158:161], v[214:217], v[14:17]
	v_mfma_f32_16x16x32_bf16 v[10:13], v[166:169], v[214:217], v[10:13]
	v_mfma_f32_16x16x32_bf16 v[54:57], v[170:173], v[186:189], v[54:57]
	v_mfma_f32_16x16x32_bf16 v[50:53], v[178:181], v[186:189], v[50:53]
	v_mfma_f32_16x16x32_bf16 v[38:41], v[170:173], v[194:197], v[38:41]
	v_mfma_f32_16x16x32_bf16 v[34:37], v[178:181], v[194:197], v[34:37]
	v_mfma_f32_16x16x32_bf16 v[22:25], v[170:173], v[202:205], v[22:25]
	v_mfma_f32_16x16x32_bf16 v[18:21], v[178:181], v[202:205], v[18:21]
	v_mfma_f32_16x16x32_bf16 v[6:9], v[170:173], v[210:213], v[6:9]
	v_mfma_f32_16x16x32_bf16 v[2:5], v[178:181], v[210:213], v[2:5]
	v_mfma_f32_16x16x32_bf16 v[54:57], v[174:177], v[190:193], v[54:57]
	v_mfma_f32_16x16x32_bf16 v[50:53], v[182:185], v[190:193], v[50:53]
	v_mfma_f32_16x16x32_bf16 v[38:41], v[174:177], v[198:201], v[38:41]
	v_mfma_f32_16x16x32_bf16 v[34:37], v[182:185], v[198:201], v[34:37]
	v_mfma_f32_16x16x32_bf16 v[22:25], v[174:177], v[206:209], v[22:25]
	v_mfma_f32_16x16x32_bf16 v[18:21], v[182:185], v[206:209], v[18:21]
	v_mfma_f32_16x16x32_bf16 v[6:9], v[174:177], v[214:217], v[6:9]
	v_mfma_f32_16x16x32_bf16 v[2:5], v[182:185], v[214:217], v[2:5]
	s_barrier
	s_add_i32 s51, 0, 0x18000
	v_add_u32_e32 v153, s51, v151
	s_add_i32 s52, 0, 0x1c000
	ds_read_b128 v[154:157], v153
	ds_read_b128 v[158:161], v153 offset:1024
	ds_read_b128 v[162:165], v153 offset:2048
	ds_read_b128 v[166:169], v153 offset:3072
	v_add_u32_e32 v153, s52, v151
	ds_read_b128 v[170:173], v153
	ds_read_b128 v[174:177], v153 offset:1024
	ds_read_b128 v[178:181], v153 offset:2048
	ds_read_b128 v[182:185], v153 offset:3072
	s_add_u32 s28, s28, 0xb0000
	s_addc_u32 s29, s29, 0
	s_mov_b32 m0, s15
	ds_read_b128 v[186:189], v152 offset:32768
	ds_read_b128 v[190:193], v152 offset:33792
	ds_read_b128 v[194:197], v152 offset:34816
	ds_read_b128 v[198:201], v152 offset:35840
	ds_read_b128 v[202:205], v152 offset:36864
	ds_read_b128 v[206:209], v152 offset:37888
	ds_read_b128 v[210:213], v152 offset:38912
	ds_read_b128 v[214:217], v152 offset:39936
	global_load_lds_dwordx4 v130, s[28:29]
	s_mov_b32 m0, s40
	s_nop 0
	global_load_lds_dwordx4 v134, s[28:29]
	s_waitcnt vmcnt(8) lgkmcnt(0)
	s_barrier
	v_mfma_f32_16x16x32_bf16 v[126:129], v[154:157], v[186:189], v[126:129]
	v_mfma_f32_16x16x32_bf16 v[122:125], v[162:165], v[186:189], v[122:125]
	v_mfma_f32_16x16x32_bf16 v[110:113], v[154:157], v[194:197], v[110:113]
	v_mfma_f32_16x16x32_bf16 v[106:109], v[162:165], v[194:197], v[106:109]
	v_mfma_f32_16x16x32_bf16 v[94:97], v[154:157], v[202:205], v[94:97]
	v_mfma_f32_16x16x32_bf16 v[90:93], v[162:165], v[202:205], v[90:93]
	v_mfma_f32_16x16x32_bf16 v[78:81], v[154:157], v[210:213], v[78:81]
	v_mfma_f32_16x16x32_bf16 v[74:77], v[162:165], v[210:213], v[74:77]
	v_mfma_f32_16x16x32_bf16 v[126:129], v[158:161], v[190:193], v[126:129]
	v_mfma_f32_16x16x32_bf16 v[122:125], v[166:169], v[190:193], v[122:125]
	v_mfma_f32_16x16x32_bf16 v[110:113], v[158:161], v[198:201], v[110:113]
	v_mfma_f32_16x16x32_bf16 v[106:109], v[166:169], v[198:201], v[106:109]
	v_mfma_f32_16x16x32_bf16 v[94:97], v[158:161], v[206:209], v[94:97]
	v_mfma_f32_16x16x32_bf16 v[90:93], v[166:169], v[206:209], v[90:93]
	v_mfma_f32_16x16x32_bf16 v[78:81], v[158:161], v[214:217], v[78:81]
	v_mfma_f32_16x16x32_bf16 v[74:77], v[166:169], v[214:217], v[74:77]
	v_mfma_f32_16x16x32_bf16 v[118:121], v[170:173], v[186:189], v[118:121]
	v_mfma_f32_16x16x32_bf16 v[114:117], v[178:181], v[186:189], v[114:117]
	v_mfma_f32_16x16x32_bf16 v[102:105], v[170:173], v[194:197], v[102:105]
	v_mfma_f32_16x16x32_bf16 v[98:101], v[178:181], v[194:197], v[98:101]
	v_mfma_f32_16x16x32_bf16 v[86:89], v[170:173], v[202:205], v[86:89]
	v_mfma_f32_16x16x32_bf16 v[82:85], v[178:181], v[202:205], v[82:85]
	v_mfma_f32_16x16x32_bf16 v[70:73], v[170:173], v[210:213], v[70:73]
	v_mfma_f32_16x16x32_bf16 v[66:69], v[178:181], v[210:213], v[66:69]
	v_mfma_f32_16x16x32_bf16 v[118:121], v[174:177], v[190:193], v[118:121]
	v_mfma_f32_16x16x32_bf16 v[114:117], v[182:185], v[190:193], v[114:117]
	v_mfma_f32_16x16x32_bf16 v[102:105], v[174:177], v[198:201], v[102:105]
	v_mfma_f32_16x16x32_bf16 v[98:101], v[182:185], v[198:201], v[98:101]
	v_mfma_f32_16x16x32_bf16 v[86:89], v[174:177], v[206:209], v[86:89]
	v_mfma_f32_16x16x32_bf16 v[82:85], v[182:185], v[206:209], v[82:85]
	v_mfma_f32_16x16x32_bf16 v[70:73], v[174:177], v[214:217], v[70:73]
	v_mfma_f32_16x16x32_bf16 v[66:69], v[182:185], v[214:217], v[66:69]
	s_barrier
	s_add_i32 s28, s51, s13
	s_mov_b32 m0, s28
	ds_read_b128 v[186:189], v152 offset:49152
	ds_read_b128 v[190:193], v152 offset:50176
	ds_read_b128 v[194:197], v152 offset:51200
	ds_read_b128 v[198:201], v152 offset:52224
	ds_read_b128 v[202:205], v152 offset:53248
	ds_read_b128 v[206:209], v152 offset:54272
	ds_read_b128 v[210:213], v152 offset:55296
	ds_read_b128 v[214:217], v152 offset:56320
	global_load_lds_dwordx4 v132, s[98:99]
	s_add_i32 m0, s28, 0x2000
	s_add_u32 s26, s26, 0xb0080
	s_addc_u32 s27, s27, 0
	s_add_i32 s28, s52, s13
	global_load_lds_dwordx4 v136, s[98:99]
	s_mov_b32 m0, s28
	s_nop 0
	global_load_lds_dwordx4 v132, s[26:27]
	s_add_i32 m0, s28, 0x2000
	s_nop 0
	global_load_lds_dwordx4 v136, s[26:27]
	s_mov_b32 m0, s42
	s_nop 0
	global_load_lds_dwordx4 v130, s[100:101]
	s_mov_b32 m0, s43
	s_nop 0
	global_load_lds_dwordx4 v134, s[100:101]
	s_waitcnt vmcnt(8) lgkmcnt(0)
	s_barrier
	v_mfma_f32_16x16x32_bf16 v[62:65], v[154:157], v[186:189], v[62:65]
	v_mfma_f32_16x16x32_bf16 v[58:61], v[162:165], v[186:189], v[58:61]
	v_mfma_f32_16x16x32_bf16 v[46:49], v[154:157], v[194:197], v[46:49]
	v_mfma_f32_16x16x32_bf16 v[42:45], v[162:165], v[194:197], v[42:45]
	v_mfma_f32_16x16x32_bf16 v[30:33], v[154:157], v[202:205], v[30:33]
	v_mfma_f32_16x16x32_bf16 v[26:29], v[162:165], v[202:205], v[26:29]
	v_mfma_f32_16x16x32_bf16 v[14:17], v[154:157], v[210:213], v[14:17]
	v_mfma_f32_16x16x32_bf16 v[10:13], v[162:165], v[210:213], v[10:13]
	v_mfma_f32_16x16x32_bf16 v[62:65], v[158:161], v[190:193], v[62:65]
	v_mfma_f32_16x16x32_bf16 v[58:61], v[166:169], v[190:193], v[58:61]
	v_mfma_f32_16x16x32_bf16 v[46:49], v[158:161], v[198:201], v[46:49]
	v_mfma_f32_16x16x32_bf16 v[42:45], v[166:169], v[198:201], v[42:45]
	v_mfma_f32_16x16x32_bf16 v[30:33], v[158:161], v[206:209], v[30:33]
	v_mfma_f32_16x16x32_bf16 v[26:29], v[166:169], v[206:209], v[26:29]
	v_mfma_f32_16x16x32_bf16 v[14:17], v[158:161], v[214:217], v[14:17]
	v_mfma_f32_16x16x32_bf16 v[10:13], v[166:169], v[214:217], v[10:13]
	v_mfma_f32_16x16x32_bf16 v[54:57], v[170:173], v[186:189], v[54:57]
	v_mfma_f32_16x16x32_bf16 v[50:53], v[178:181], v[186:189], v[50:53]
	v_mfma_f32_16x16x32_bf16 v[38:41], v[170:173], v[194:197], v[38:41]
	v_mfma_f32_16x16x32_bf16 v[34:37], v[178:181], v[194:197], v[34:37]
	v_mfma_f32_16x16x32_bf16 v[22:25], v[170:173], v[202:205], v[22:25]
	v_mfma_f32_16x16x32_bf16 v[18:21], v[178:181], v[202:205], v[18:21]
	v_mfma_f32_16x16x32_bf16 v[6:9], v[170:173], v[210:213], v[6:9]
	v_mfma_f32_16x16x32_bf16 v[2:5], v[178:181], v[210:213], v[2:5]
	v_mfma_f32_16x16x32_bf16 v[54:57], v[174:177], v[190:193], v[54:57]
	v_mfma_f32_16x16x32_bf16 v[50:53], v[182:185], v[190:193], v[50:53]
	v_mfma_f32_16x16x32_bf16 v[38:41], v[174:177], v[198:201], v[38:41]
	v_mfma_f32_16x16x32_bf16 v[34:37], v[182:185], v[198:201], v[34:37]
	v_mfma_f32_16x16x32_bf16 v[22:25], v[174:177], v[206:209], v[22:25]
	v_mfma_f32_16x16x32_bf16 v[18:21], v[182:185], v[206:209], v[18:21]
	v_mfma_f32_16x16x32_bf16 v[6:9], v[174:177], v[214:217], v[6:9]
	v_mfma_f32_16x16x32_bf16 v[2:5], v[182:185], v[214:217], v[2:5]
	s_barrier
	s_add_i32 s50, s50, 2
	s_add_u32 s24, s24, 0x100
	s_addc_u32 s25, s25, 0
	s_cmp_gt_u32 s50, 41
	s_cbranch_scc0 .LBB0_619
	s_add_u32 s24, s48, 0xffffff00
	s_addc_u32 s25, s49, -1
	s_and_b64 vcc, exec, s[6:7]
	s_cbranch_vccnz .LBB0_622
	v_mov_b32_e32 v2, 0
	s_mov_b32 s10, s46
	s_mov_b32 s31, s47
	s_mov_b64 s[18:19], s[22:23]
	s_mov_b32 s41, s2
	v_mov_b32_e32 v3, v2
	v_mov_b32_e32 v4, v2
	v_mov_b32_e32 v5, v2
	v_mov_b32_e32 v6, v2
	v_mov_b32_e32 v7, v2
	v_mov_b32_e32 v8, v2
	v_mov_b32_e32 v9, v2
	v_mov_b32_e32 v18, v2
	v_mov_b32_e32 v19, v2
	v_mov_b32_e32 v20, v2
	v_mov_b32_e32 v21, v2
	v_mov_b32_e32 v22, v2
	v_mov_b32_e32 v23, v2
	v_mov_b32_e32 v24, v2
	v_mov_b32_e32 v25, v2
	v_mov_b32_e32 v34, v2
	v_mov_b32_e32 v35, v2
	v_mov_b32_e32 v36, v2
	v_mov_b32_e32 v37, v2
	v_mov_b32_e32 v38, v2
	v_mov_b32_e32 v39, v2
	v_mov_b32_e32 v40, v2
	v_mov_b32_e32 v41, v2
	v_mov_b32_e32 v50, v2
	v_mov_b32_e32 v51, v2
	v_mov_b32_e32 v52, v2
	v_mov_b32_e32 v53, v2
	v_mov_b32_e32 v54, v2
	v_mov_b32_e32 v55, v2
	v_mov_b32_e32 v56, v2
	v_mov_b32_e32 v57, v2
	v_mov_b32_e32 v10, v2
	v_mov_b32_e32 v11, v2
	v_mov_b32_e32 v12, v2
	v_mov_b32_e32 v13, v2
	v_mov_b32_e32 v14, v2
	v_mov_b32_e32 v15, v2
	v_mov_b32_e32 v16, v2
	v_mov_b32_e32 v17, v2
	v_mov_b32_e32 v26, v2
	v_mov_b32_e32 v27, v2
	v_mov_b32_e32 v28, v2
	v_mov_b32_e32 v29, v2
	v_mov_b32_e32 v30, v2
	v_mov_b32_e32 v31, v2
	v_mov_b32_e32 v32, v2
	v_mov_b32_e32 v33, v2
	v_mov_b32_e32 v42, v2
	v_mov_b32_e32 v43, v2
	v_mov_b32_e32 v44, v2
	v_mov_b32_e32 v45, v2
	v_mov_b32_e32 v46, v2
	v_mov_b32_e32 v47, v2
	v_mov_b32_e32 v48, v2
	v_mov_b32_e32 v49, v2
	v_mov_b32_e32 v58, v2
	v_mov_b32_e32 v59, v2
	v_mov_b32_e32 v60, v2
	v_mov_b32_e32 v61, v2
	v_mov_b32_e32 v62, v2
	v_mov_b32_e32 v63, v2
	v_mov_b32_e32 v64, v2
	v_mov_b32_e32 v65, v2
	v_mov_b32_e32 v66, v2
	v_mov_b32_e32 v67, v2
	v_mov_b32_e32 v68, v2
	v_mov_b32_e32 v69, v2
	v_mov_b32_e32 v70, v2
	v_mov_b32_e32 v71, v2
	v_mov_b32_e32 v72, v2
	v_mov_b32_e32 v73, v2
	v_mov_b32_e32 v82, v2
	v_mov_b32_e32 v83, v2
	v_mov_b32_e32 v84, v2
	v_mov_b32_e32 v85, v2
	v_mov_b32_e32 v86, v2
	v_mov_b32_e32 v87, v2
	v_mov_b32_e32 v88, v2
	v_mov_b32_e32 v89, v2
	v_mov_b32_e32 v98, v2
	v_mov_b32_e32 v99, v2
	v_mov_b32_e32 v100, v2
	v_mov_b32_e32 v101, v2
	v_mov_b32_e32 v102, v2
	v_mov_b32_e32 v103, v2
	v_mov_b32_e32 v104, v2
	v_mov_b32_e32 v105, v2
	v_mov_b32_e32 v114, v2
	v_mov_b32_e32 v115, v2
	v_mov_b32_e32 v116, v2
	v_mov_b32_e32 v117, v2
	v_mov_b32_e32 v118, v2
	v_mov_b32_e32 v119, v2
	v_mov_b32_e32 v120, v2
	v_mov_b32_e32 v121, v2
	v_mov_b32_e32 v74, v2
	v_mov_b32_e32 v75, v2
	v_mov_b32_e32 v76, v2
	v_mov_b32_e32 v77, v2
	v_mov_b32_e32 v78, v2
	v_mov_b32_e32 v79, v2
	v_mov_b32_e32 v80, v2
	v_mov_b32_e32 v81, v2
	v_mov_b32_e32 v90, v2
	v_mov_b32_e32 v91, v2
	v_mov_b32_e32 v92, v2
	v_mov_b32_e32 v93, v2
	v_mov_b32_e32 v94, v2
	v_mov_b32_e32 v95, v2
	v_mov_b32_e32 v96, v2
	v_mov_b32_e32 v97, v2
	v_mov_b32_e32 v106, v2
	v_mov_b32_e32 v107, v2
	v_mov_b32_e32 v108, v2
	v_mov_b32_e32 v109, v2
	v_mov_b32_e32 v110, v2
	v_mov_b32_e32 v111, v2
	v_mov_b32_e32 v112, v2
	v_mov_b32_e32 v113, v2
	v_mov_b32_e32 v122, v2
	v_mov_b32_e32 v123, v2
	v_mov_b32_e32 v124, v2
	v_mov_b32_e32 v125, v2
	v_mov_b32_e32 v126, v2
	v_mov_b32_e32 v127, v2
	v_mov_b32_e32 v128, v2
	v_mov_b32_e32 v129, v2
	s_andn2_b64 vcc, exec, s[4:5]
	s_cbranch_vccnz .LBB0_623
	s_branch .LBB0_624

.LBB0_774:
	ds_read_b128 v[38:41], v231
	ds_read_b128 v[42:45], v231 offset:1024
	ds_read_b128 v[54:57], v231 offset:2048
	ds_read_b128 v[58:61], v231 offset:3072
	ds_read_b128 v[126:129], v232
	ds_read_b128 v[146:149], v232 offset:1024
	ds_read_b128 v[166:169], v232 offset:2048
	ds_read_b128 v[170:173], v232 offset:3072
	s_add_u32 s14, s10, 0xfffc0080
	s_addc_u32 s15, s11, -1
	s_cmp_eq_u32 s13, 12
	s_cselect_b32 s59, s0, s15
	s_cselect_b32 s58, s1, s14
	s_cselect_b32 s57, s2, s12
	s_cselect_b32 s56, s7, s9
	s_add_i32 m0, s67, 0xc000
	ds_read_b128 v[174:177], v233
	ds_read_b128 v[194:197], v233 offset:1024
	ds_read_b128 v[198:201], v233 offset:2048
	ds_read_b128 v[202:205], v233 offset:3072
	ds_read_b128 v[206:209], v233 offset:4096
	ds_read_b128 v[210:213], v233 offset:5120
	ds_read_b128 v[214:217], v233 offset:6144
	ds_read_b128 v[218:221], v233 offset:7168
	global_load_lds_dwordx4 v186, s[10:11]
	s_add_i32 m0, s67, 0xe000
	s_nop 0
	global_load_lds_dwordx4 v188, s[10:11]
	s_waitcnt vmcnt(8) lgkmcnt(0)
	s_barrier
	v_mfma_f32_16x16x32_bf16 v[162:165], v[38:41], v[174:177], v[162:165]
	v_mfma_f32_16x16x32_bf16 v[158:161], v[54:57], v[174:177], v[158:161]
	v_mfma_f32_16x16x32_bf16 v[142:145], v[38:41], v[198:201], v[142:145]
	v_mfma_f32_16x16x32_bf16 v[138:141], v[54:57], v[198:201], v[138:141]
	v_mfma_f32_16x16x32_bf16 v[122:125], v[38:41], v[206:209], v[122:125]
	v_mfma_f32_16x16x32_bf16 v[118:121], v[54:57], v[206:209], v[118:121]
	v_mfma_f32_16x16x32_bf16 v[106:109], v[38:41], v[214:217], v[106:109]
	v_mfma_f32_16x16x32_bf16 v[102:105], v[54:57], v[214:217], v[102:105]
	v_mfma_f32_16x16x32_bf16 v[162:165], v[42:45], v[194:197], v[162:165]
	v_mfma_f32_16x16x32_bf16 v[158:161], v[58:61], v[194:197], v[158:161]
	v_mfma_f32_16x16x32_bf16 v[142:145], v[42:45], v[202:205], v[142:145]
	v_mfma_f32_16x16x32_bf16 v[138:141], v[58:61], v[202:205], v[138:141]
	v_mfma_f32_16x16x32_bf16 v[122:125], v[42:45], v[210:213], v[122:125]
	v_mfma_f32_16x16x32_bf16 v[118:121], v[58:61], v[210:213], v[118:121]
	v_mfma_f32_16x16x32_bf16 v[106:109], v[42:45], v[218:221], v[106:109]
	v_mfma_f32_16x16x32_bf16 v[102:105], v[58:61], v[218:221], v[102:105]
	v_mfma_f32_16x16x32_bf16 v[154:157], v[126:129], v[174:177], v[154:157]
	v_mfma_f32_16x16x32_bf16 v[150:153], v[166:169], v[174:177], v[150:153]
	v_mfma_f32_16x16x32_bf16 v[134:137], v[126:129], v[198:201], v[134:137]
	v_mfma_f32_16x16x32_bf16 v[130:133], v[166:169], v[198:201], v[130:133]
	v_mfma_f32_16x16x32_bf16 v[114:117], v[126:129], v[206:209], v[114:117]
	v_mfma_f32_16x16x32_bf16 v[110:113], v[166:169], v[206:209], v[110:113]
	v_mfma_f32_16x16x32_bf16 v[98:101], v[126:129], v[214:217], v[98:101]
	v_mfma_f32_16x16x32_bf16 v[94:97], v[166:169], v[214:217], v[94:97]
	v_mfma_f32_16x16x32_bf16 v[154:157], v[146:149], v[194:197], v[154:157]
	v_mfma_f32_16x16x32_bf16 v[150:153], v[170:173], v[194:197], v[150:153]
	v_mfma_f32_16x16x32_bf16 v[134:137], v[146:149], v[202:205], v[134:137]
	v_mfma_f32_16x16x32_bf16 v[130:133], v[170:173], v[202:205], v[130:133]
	v_mfma_f32_16x16x32_bf16 v[114:117], v[146:149], v[210:213], v[114:117]
	v_mfma_f32_16x16x32_bf16 v[110:113], v[170:173], v[210:213], v[110:113]
	v_mfma_f32_16x16x32_bf16 v[98:101], v[146:149], v[218:221], v[98:101]
	v_mfma_f32_16x16x32_bf16 v[94:97], v[170:173], v[218:221], v[94:97]
	s_barrier
	s_add_i32 s14, s84, s66
	s_add_u32 s98, s56, s20
	s_addc_u32 s99, s57, s21
	s_mov_b32 m0, s14
	ds_read_b128 v[174:177], v233 offset:16384
	ds_read_b128 v[194:197], v233 offset:17408
	ds_read_b128 v[198:201], v233 offset:18432
	ds_read_b128 v[202:205], v233 offset:19456
	ds_read_b128 v[206:209], v233 offset:20480
	ds_read_b128 v[210:213], v233 offset:21504
	ds_read_b128 v[214:217], v233 offset:22528
	ds_read_b128 v[218:221], v233 offset:23552
	global_load_lds_dwordx4 v180, s[56:57]
	s_add_i32 m0, s14, 0x2000
	s_add_u32 s14, s56, 0x40000
	s_addc_u32 s15, s57, 0
	s_add_i32 s33, s85, s66
	global_load_lds_dwordx4 v184, s[56:57]
	s_mov_b32 m0, s33
	s_add_u32 s100, s58, s20
	s_addc_u32 s101, s59, s21
	global_load_lds_dwordx4 v180, s[14:15]
	s_add_i32 m0, s33, 0x2000
	s_nop 0
	global_load_lds_dwordx4 v184, s[14:15]
	s_mov_b32 m0, s67
	s_nop 0
	global_load_lds_dwordx4 v178, s[58:59]
	s_mov_b32 m0, s68
	s_nop 0
	global_load_lds_dwordx4 v182, s[58:59]
	s_waitcnt vmcnt(8) lgkmcnt(0)
	s_barrier
	v_mfma_f32_16x16x32_bf16 v[90:93], v[38:41], v[174:177], v[90:93]
	v_mfma_f32_16x16x32_bf16 v[86:89], v[54:57], v[174:177], v[86:89]
	v_mfma_f32_16x16x32_bf16 v[74:77], v[38:41], v[198:201], v[74:77]
	v_mfma_f32_16x16x32_bf16 v[70:73], v[54:57], v[198:201], v[70:73]
	v_mfma_f32_16x16x32_bf16 v[50:53], v[38:41], v[206:209], v[50:53]
	v_mfma_f32_16x16x32_bf16 v[46:49], v[54:57], v[206:209], v[46:49]
	v_mfma_f32_16x16x32_bf16 v[26:29], v[38:41], v[214:217], v[26:29]
	v_mfma_f32_16x16x32_bf16 v[22:25], v[54:57], v[214:217], v[22:25]
	v_mfma_f32_16x16x32_bf16 v[90:93], v[42:45], v[194:197], v[90:93]
	v_mfma_f32_16x16x32_bf16 v[86:89], v[58:61], v[194:197], v[86:89]
	v_mfma_f32_16x16x32_bf16 v[74:77], v[42:45], v[202:205], v[74:77]
	v_mfma_f32_16x16x32_bf16 v[70:73], v[58:61], v[202:205], v[70:73]
	v_mfma_f32_16x16x32_bf16 v[50:53], v[42:45], v[210:213], v[50:53]
	v_mfma_f32_16x16x32_bf16 v[46:49], v[58:61], v[210:213], v[46:49]
	v_mfma_f32_16x16x32_bf16 v[26:29], v[42:45], v[218:221], v[26:29]
	v_mfma_f32_16x16x32_bf16 v[22:25], v[58:61], v[218:221], v[22:25]
	v_mfma_f32_16x16x32_bf16 v[34:37], v[126:129], v[206:209], v[34:37]
	v_mfma_f32_16x16x32_bf16 v[30:33], v[166:169], v[206:209], v[30:33]
	v_mfma_f32_16x16x32_bf16 v[18:21], v[126:129], v[214:217], v[18:21]
	v_mfma_f32_16x16x32_bf16 v[12:15], v[166:169], v[214:217], v[14:17]
	v_mfma_f32_16x16x32_bf16 v[38:41], v[126:129], v[174:177], v[82:85]
	v_mfma_f32_16x16x32_bf16 v[42:45], v[166:169], v[174:177], v[78:81]
	v_mfma_f32_16x16x32_bf16 v[54:57], v[126:129], v[198:201], v[66:69]
	v_mfma_f32_16x16x32_bf16 v[58:61], v[166:169], v[198:201], v[62:65]
	v_mfma_f32_16x16x32_bf16 v[34:37], v[146:149], v[210:213], v[34:37]
	v_mfma_f32_16x16x32_bf16 v[30:33], v[170:173], v[210:213], v[30:33]
	v_mfma_f32_16x16x32_bf16 v[18:21], v[146:149], v[218:221], v[18:21]
	v_mfma_f32_16x16x32_bf16 v[12:15], v[170:173], v[218:221], v[12:15]
	v_mfma_f32_16x16x32_bf16 v[38:41], v[146:149], v[194:197], v[38:41]
	v_mfma_f32_16x16x32_bf16 v[42:45], v[170:173], v[194:197], v[42:45]
	v_mfma_f32_16x16x32_bf16 v[54:57], v[146:149], v[202:205], v[54:57]
	v_mfma_f32_16x16x32_bf16 v[58:61], v[170:173], v[202:205], v[58:61]
	s_barrier
	s_add_i32 s33, 0, 0x18000
	v_add_u32_e32 v3, s33, v230
	s_add_i32 s40, 0, 0x1c000
	ds_read_b128 v[62:65], v3
	ds_read_b128 v[66:69], v3 offset:1024
	ds_read_b128 v[78:81], v3 offset:2048
	ds_read_b128 v[82:85], v3 offset:3072
	v_add_u32_e32 v3, s40, v230
	ds_read_b128 v[126:129], v3
	ds_read_b128 v[146:149], v3 offset:1024
	ds_read_b128 v[166:169], v3 offset:2048
	ds_read_b128 v[170:173], v3 offset:3072
	s_add_u32 s14, s58, 0x40000
	s_addc_u32 s15, s59, 0
	s_mov_b32 m0, s69
	ds_read_b128 v[174:177], v233 offset:32768
	ds_read_b128 v[194:197], v233 offset:33792
	ds_read_b128 v[198:201], v233 offset:34816
	ds_read_b128 v[202:205], v233 offset:35840
	ds_read_b128 v[206:209], v233 offset:36864
	ds_read_b128 v[210:213], v233 offset:37888
	ds_read_b128 v[214:217], v233 offset:38912
	ds_read_b128 v[218:221], v233 offset:39936
	global_load_lds_dwordx4 v178, s[14:15]
	s_mov_b32 m0, s70
	s_nop 0
	global_load_lds_dwordx4 v182, s[14:15]
	s_waitcnt vmcnt(8) lgkmcnt(0)
	s_barrier
	v_mfma_f32_16x16x32_bf16 v[162:165], v[62:65], v[174:177], v[162:165]
	v_mfma_f32_16x16x32_bf16 v[158:161], v[78:81], v[174:177], v[158:161]
	v_mfma_f32_16x16x32_bf16 v[142:145], v[62:65], v[198:201], v[142:145]
	v_mfma_f32_16x16x32_bf16 v[138:141], v[78:81], v[198:201], v[138:141]
	v_mfma_f32_16x16x32_bf16 v[122:125], v[62:65], v[206:209], v[122:125]
	v_mfma_f32_16x16x32_bf16 v[118:121], v[78:81], v[206:209], v[118:121]
	v_mfma_f32_16x16x32_bf16 v[106:109], v[62:65], v[214:217], v[106:109]
	v_mfma_f32_16x16x32_bf16 v[102:105], v[78:81], v[214:217], v[102:105]
	v_mfma_f32_16x16x32_bf16 v[162:165], v[66:69], v[194:197], v[162:165]
	v_mfma_f32_16x16x32_bf16 v[158:161], v[82:85], v[194:197], v[158:161]
	v_mfma_f32_16x16x32_bf16 v[142:145], v[66:69], v[202:205], v[142:145]
	v_mfma_f32_16x16x32_bf16 v[138:141], v[82:85], v[202:205], v[138:141]
	v_mfma_f32_16x16x32_bf16 v[122:125], v[66:69], v[210:213], v[122:125]
	v_mfma_f32_16x16x32_bf16 v[118:121], v[82:85], v[210:213], v[118:121]
	v_mfma_f32_16x16x32_bf16 v[106:109], v[66:69], v[218:221], v[106:109]
	v_mfma_f32_16x16x32_bf16 v[102:105], v[82:85], v[218:221], v[102:105]
	v_mfma_f32_16x16x32_bf16 v[154:157], v[126:129], v[174:177], v[154:157]
	v_mfma_f32_16x16x32_bf16 v[150:153], v[166:169], v[174:177], v[150:153]
	v_mfma_f32_16x16x32_bf16 v[134:137], v[126:129], v[198:201], v[134:137]
	v_mfma_f32_16x16x32_bf16 v[130:133], v[166:169], v[198:201], v[130:133]
	v_mfma_f32_16x16x32_bf16 v[114:117], v[126:129], v[206:209], v[114:117]
	v_mfma_f32_16x16x32_bf16 v[110:113], v[166:169], v[206:209], v[110:113]
	v_mfma_f32_16x16x32_bf16 v[98:101], v[126:129], v[214:217], v[98:101]
	v_mfma_f32_16x16x32_bf16 v[94:97], v[166:169], v[214:217], v[94:97]
	v_mfma_f32_16x16x32_bf16 v[154:157], v[146:149], v[194:197], v[154:157]
	v_mfma_f32_16x16x32_bf16 v[150:153], v[170:173], v[194:197], v[150:153]
	v_mfma_f32_16x16x32_bf16 v[134:137], v[146:149], v[202:205], v[134:137]
	v_mfma_f32_16x16x32_bf16 v[130:133], v[170:173], v[202:205], v[130:133]
	v_mfma_f32_16x16x32_bf16 v[114:117], v[146:149], v[210:213], v[114:117]
	v_mfma_f32_16x16x32_bf16 v[110:113], v[170:173], v[210:213], v[110:113]
	v_mfma_f32_16x16x32_bf16 v[98:101], v[146:149], v[218:221], v[98:101]
	v_mfma_f32_16x16x32_bf16 v[94:97], v[170:173], v[218:221], v[94:97]
	s_barrier
	s_add_i32 s14, s33, s66
	s_mov_b32 m0, s14
	ds_read_b128 v[174:177], v233 offset:49152
	ds_read_b128 v[194:197], v233 offset:50176
	ds_read_b128 v[198:201], v233 offset:51200
	ds_read_b128 v[202:205], v233 offset:52224
	ds_read_b128 v[206:209], v233 offset:53248
	ds_read_b128 v[210:213], v233 offset:54272
	ds_read_b128 v[214:217], v233 offset:55296
	ds_read_b128 v[218:221], v233 offset:56320
	global_load_lds_dwordx4 v180, s[98:99]
	s_add_i32 m0, s14, 0x2000
	s_add_u32 s14, s56, 0x40080
	s_addc_u32 s15, s57, 0
	s_add_i32 s33, s40, s66
	global_load_lds_dwordx4 v184, s[98:99]
	s_mov_b32 m0, s33
	s_nop 0
	global_load_lds_dwordx4 v180, s[14:15]
	s_add_i32 m0, s33, 0x2000
	s_nop 0
	global_load_lds_dwordx4 v184, s[14:15]
	s_mov_b32 m0, s76
	s_nop 0
	global_load_lds_dwordx4 v178, s[100:101]
	s_mov_b32 m0, s77
	s_nop 0
	global_load_lds_dwordx4 v182, s[100:101]
	s_waitcnt vmcnt(8) lgkmcnt(0)
	s_barrier
	v_mfma_f32_16x16x32_bf16 v[90:93], v[62:65], v[174:177], v[90:93]
	v_mfma_f32_16x16x32_bf16 v[86:89], v[78:81], v[174:177], v[86:89]
	v_mfma_f32_16x16x32_bf16 v[74:77], v[62:65], v[198:201], v[74:77]
	v_mfma_f32_16x16x32_bf16 v[70:73], v[78:81], v[198:201], v[70:73]
	v_mfma_f32_16x16x32_bf16 v[50:53], v[62:65], v[206:209], v[50:53]
	v_mfma_f32_16x16x32_bf16 v[46:49], v[78:81], v[206:209], v[46:49]
	v_mfma_f32_16x16x32_bf16 v[26:29], v[62:65], v[214:217], v[26:29]
	v_mfma_f32_16x16x32_bf16 v[22:25], v[78:81], v[214:217], v[22:25]
	v_mfma_f32_16x16x32_bf16 v[90:93], v[66:69], v[194:197], v[90:93]
	v_mfma_f32_16x16x32_bf16 v[86:89], v[82:85], v[194:197], v[86:89]
	v_mfma_f32_16x16x32_bf16 v[74:77], v[66:69], v[202:205], v[74:77]
	v_mfma_f32_16x16x32_bf16 v[70:73], v[82:85], v[202:205], v[70:73]
	v_mfma_f32_16x16x32_bf16 v[50:53], v[66:69], v[210:213], v[50:53]
	v_mfma_f32_16x16x32_bf16 v[46:49], v[82:85], v[210:213], v[46:49]
	v_mfma_f32_16x16x32_bf16 v[26:29], v[66:69], v[218:221], v[26:29]
	v_mfma_f32_16x16x32_bf16 v[22:25], v[82:85], v[218:221], v[22:25]
	v_mfma_f32_16x16x32_bf16 v[38:41], v[126:129], v[174:177], v[38:41]
	v_mfma_f32_16x16x32_bf16 v[82:85], v[146:149], v[194:197], v[38:41]
	v_mfma_f32_16x16x32_bf16 v[38:41], v[166:169], v[174:177], v[42:45]
	v_mfma_f32_16x16x32_bf16 v[78:81], v[170:173], v[194:197], v[38:41]
	v_mfma_f32_16x16x32_bf16 v[38:41], v[126:129], v[198:201], v[54:57]
	v_mfma_f32_16x16x32_bf16 v[66:69], v[146:149], v[202:205], v[38:41]
	v_mfma_f32_16x16x32_bf16 v[38:41], v[166:169], v[198:201], v[58:61]
	v_mfma_f32_16x16x32_bf16 v[34:37], v[126:129], v[206:209], v[34:37]
	v_mfma_f32_16x16x32_bf16 v[30:33], v[166:169], v[206:209], v[30:33]
	v_mfma_f32_16x16x32_bf16 v[16:19], v[126:129], v[214:217], v[18:21]
	v_mfma_f32_16x16x32_bf16 v[12:15], v[166:169], v[214:217], v[12:15]
	v_mfma_f32_16x16x32_bf16 v[62:65], v[170:173], v[202:205], v[38:41]
	v_mfma_f32_16x16x32_bf16 v[34:37], v[146:149], v[210:213], v[34:37]
	v_mfma_f32_16x16x32_bf16 v[30:33], v[170:173], v[210:213], v[30:33]
	v_mfma_f32_16x16x32_bf16 v[18:21], v[146:149], v[218:221], v[16:19]
	v_mfma_f32_16x16x32_bf16 v[14:17], v[170:173], v[218:221], v[12:15]
	s_barrier
	s_add_i32 s13, s13, 2
	s_add_u32 s10, s10, 0x100
	s_addc_u32 s11, s11, 0
	s_add_u32 s9, s9, 0x100
	s_addc_u32 s12, s12, 0
	s_cmp_gt_u32 s13, 13
	s_cbranch_scc0 .LBB0_774
	s_and_b64 vcc, exec, s[22:23]
	s_cbranch_vccz .LBB0_777
	s_barrier

.LBB0_1038:
	ds_read_b128 v[26:29], v214
	ds_read_b128 v[30:33], v214 offset:1024
	ds_read_b128 v[34:37], v214 offset:2048
	ds_read_b128 v[38:41], v214 offset:3072
	ds_read_b128 v[122:125], v215
	ds_read_b128 v[142:145], v215 offset:1024
	ds_read_b128 v[162:165], v215 offset:2048
	ds_read_b128 v[166:169], v215 offset:3072
	s_add_i32 s33, s31, 2
	s_add_u32 s40, s6, 0xfffd0080
	s_addc_u32 s41, s7, -1
	s_cmp_eq_u32 s13, s31
	s_cselect_b32 s55, s47, s41
	s_cselect_b32 s54, s46, s40
	s_cselect_b32 s53, s1, s15
	s_cselect_b32 s52, s2, s14
	s_add_i32 m0, s66, 0xc000
	ds_read_b128 v[170:173], v216
	ds_read_b128 v[174:177], v216 offset:1024
	ds_read_b128 v[178:181], v216 offset:2048
	ds_read_b128 v[198:201], v216 offset:3072
	ds_read_b128 v[202:205], v216 offset:4096
	ds_read_b128 v[206:209], v216 offset:5120
	ds_read_b128 v[220:223], v216 offset:6144
	ds_read_b128 v[228:231], v216 offset:7168
	global_load_lds_dwordx4 v190, s[6:7]
	s_add_i32 m0, s66, 0xe000
	s_nop 0
	global_load_lds_dwordx4 v192, s[6:7]
	s_waitcnt vmcnt(8) lgkmcnt(0)
	s_barrier
	v_mfma_f32_16x16x32_bf16 v[158:161], v[26:29], v[170:173], v[158:161]
	v_mfma_f32_16x16x32_bf16 v[154:157], v[34:37], v[170:173], v[154:157]
	v_mfma_f32_16x16x32_bf16 v[138:141], v[26:29], v[178:181], v[138:141]
	v_mfma_f32_16x16x32_bf16 v[134:137], v[34:37], v[178:181], v[134:137]
	v_mfma_f32_16x16x32_bf16 v[118:121], v[26:29], v[202:205], v[118:121]
	v_mfma_f32_16x16x32_bf16 v[114:117], v[34:37], v[202:205], v[114:117]
	v_mfma_f32_16x16x32_bf16 v[102:105], v[26:29], v[220:223], v[102:105]
	v_mfma_f32_16x16x32_bf16 v[98:101], v[34:37], v[220:223], v[98:101]
	v_mfma_f32_16x16x32_bf16 v[158:161], v[30:33], v[174:177], v[158:161]
	v_mfma_f32_16x16x32_bf16 v[154:157], v[38:41], v[174:177], v[154:157]
	v_mfma_f32_16x16x32_bf16 v[138:141], v[30:33], v[198:201], v[138:141]
	v_mfma_f32_16x16x32_bf16 v[134:137], v[38:41], v[198:201], v[134:137]
	v_mfma_f32_16x16x32_bf16 v[118:121], v[30:33], v[206:209], v[118:121]
	v_mfma_f32_16x16x32_bf16 v[114:117], v[38:41], v[206:209], v[114:117]
	v_mfma_f32_16x16x32_bf16 v[102:105], v[30:33], v[228:231], v[102:105]
	v_mfma_f32_16x16x32_bf16 v[98:101], v[38:41], v[228:231], v[98:101]
	v_mfma_f32_16x16x32_bf16 v[150:153], v[122:125], v[170:173], v[150:153]
	v_mfma_f32_16x16x32_bf16 v[146:149], v[162:165], v[170:173], v[146:149]
	v_mfma_f32_16x16x32_bf16 v[130:133], v[122:125], v[178:181], v[130:133]
	v_mfma_f32_16x16x32_bf16 v[126:129], v[162:165], v[178:181], v[126:129]
	v_mfma_f32_16x16x32_bf16 v[110:113], v[122:125], v[202:205], v[110:113]
	v_mfma_f32_16x16x32_bf16 v[106:109], v[162:165], v[202:205], v[106:109]
	v_mfma_f32_16x16x32_bf16 v[94:97], v[122:125], v[220:223], v[94:97]
	v_mfma_f32_16x16x32_bf16 v[90:93], v[162:165], v[220:223], v[90:93]
	v_mfma_f32_16x16x32_bf16 v[150:153], v[142:145], v[174:177], v[150:153]
	v_mfma_f32_16x16x32_bf16 v[146:149], v[166:169], v[174:177], v[146:149]
	v_mfma_f32_16x16x32_bf16 v[130:133], v[142:145], v[198:201], v[130:133]
	v_mfma_f32_16x16x32_bf16 v[126:129], v[166:169], v[198:201], v[126:129]
	v_mfma_f32_16x16x32_bf16 v[110:113], v[142:145], v[206:209], v[110:113]
	v_mfma_f32_16x16x32_bf16 v[106:109], v[166:169], v[206:209], v[106:109]
	v_mfma_f32_16x16x32_bf16 v[94:97], v[142:145], v[228:231], v[94:97]
	v_mfma_f32_16x16x32_bf16 v[90:93], v[166:169], v[228:231], v[90:93]
	s_barrier
	s_add_i32 s31, s85, s64
	s_add_u32 s98, s52, s18
	s_addc_u32 s99, s53, s19
	s_mov_b32 m0, s31
	ds_read_b128 v[170:173], v216 offset:16384
	ds_read_b128 v[174:177], v216 offset:17408
	ds_read_b128 v[178:181], v216 offset:18432
	ds_read_b128 v[198:201], v216 offset:19456
	ds_read_b128 v[202:205], v216 offset:20480
	ds_read_b128 v[206:209], v216 offset:21504
	ds_read_b128 v[220:223], v216 offset:22528
	ds_read_b128 v[228:231], v216 offset:23552
	global_load_lds_dwordx4 v184, s[52:53]
	s_add_i32 m0, s31, 0x2000
	s_add_u32 s40, s52, 0x10000
	s_addc_u32 s41, s53, 0
	s_add_i32 s31, s86, s64
	global_load_lds_dwordx4 v188, s[52:53]
	s_mov_b32 m0, s31
	s_add_u32 s100, s54, s18
	s_addc_u32 s101, s55, s19
	global_load_lds_dwordx4 v184, s[40:41]
	s_add_i32 m0, s31, 0x2000
	s_nop 0
	global_load_lds_dwordx4 v188, s[40:41]
	s_mov_b32 m0, s66
	s_nop 0
	global_load_lds_dwordx4 v182, s[54:55]
	s_mov_b32 m0, s67
	s_nop 0
	global_load_lds_dwordx4 v186, s[54:55]
	s_waitcnt vmcnt(8) lgkmcnt(0)
	s_barrier
	v_mfma_f32_16x16x32_bf16 v[86:89], v[26:29], v[170:173], v[86:89]
	v_mfma_f32_16x16x32_bf16 v[82:85], v[34:37], v[170:173], v[82:85]
	v_mfma_f32_16x16x32_bf16 v[70:73], v[26:29], v[178:181], v[70:73]
	v_mfma_f32_16x16x32_bf16 v[66:69], v[34:37], v[178:181], v[66:69]
	v_mfma_f32_16x16x32_bf16 v[54:57], v[26:29], v[202:205], v[54:57]
	v_mfma_f32_16x16x32_bf16 v[50:53], v[34:37], v[202:205], v[50:53]
	v_mfma_f32_16x16x32_bf16 v[22:25], v[26:29], v[220:223], v[22:25]
	v_mfma_f32_16x16x32_bf16 v[18:21], v[34:37], v[220:223], v[18:21]
	v_mfma_f32_16x16x32_bf16 v[86:89], v[30:33], v[174:177], v[86:89]
	v_mfma_f32_16x16x32_bf16 v[82:85], v[38:41], v[174:177], v[82:85]
	v_mfma_f32_16x16x32_bf16 v[70:73], v[30:33], v[198:201], v[70:73]
	v_mfma_f32_16x16x32_bf16 v[66:69], v[38:41], v[198:201], v[66:69]
	v_mfma_f32_16x16x32_bf16 v[54:57], v[30:33], v[206:209], v[54:57]
	v_mfma_f32_16x16x32_bf16 v[50:53], v[38:41], v[206:209], v[50:53]
	v_mfma_f32_16x16x32_bf16 v[22:25], v[30:33], v[228:231], v[22:25]
	v_mfma_f32_16x16x32_bf16 v[18:21], v[38:41], v[228:231], v[18:21]
	v_mfma_f32_16x16x32_bf16 v[46:49], v[122:125], v[202:205], v[46:49]
	v_mfma_f32_16x16x32_bf16 v[42:45], v[162:165], v[202:205], v[42:45]
	v_mfma_f32_16x16x32_bf16 v[14:17], v[122:125], v[220:223], v[14:17]
	v_mfma_f32_16x16x32_bf16 v[8:11], v[162:165], v[220:223], v[10:13]
	v_mfma_f32_16x16x32_bf16 v[26:29], v[122:125], v[170:173], v[78:81]
	v_mfma_f32_16x16x32_bf16 v[30:33], v[162:165], v[170:173], v[74:77]
	v_mfma_f32_16x16x32_bf16 v[34:37], v[122:125], v[178:181], v[62:65]
	v_mfma_f32_16x16x32_bf16 v[38:41], v[162:165], v[178:181], v[58:61]
	v_mfma_f32_16x16x32_bf16 v[46:49], v[142:145], v[206:209], v[46:49]
	v_mfma_f32_16x16x32_bf16 v[42:45], v[166:169], v[206:209], v[42:45]
	v_mfma_f32_16x16x32_bf16 v[14:17], v[142:145], v[228:231], v[14:17]
	v_mfma_f32_16x16x32_bf16 v[8:11], v[166:169], v[228:231], v[8:11]
	v_mfma_f32_16x16x32_bf16 v[26:29], v[142:145], v[174:177], v[26:29]
	v_mfma_f32_16x16x32_bf16 v[30:33], v[166:169], v[174:177], v[30:33]
	v_mfma_f32_16x16x32_bf16 v[34:37], v[142:145], v[198:201], v[34:37]
	v_mfma_f32_16x16x32_bf16 v[38:41], v[166:169], v[198:201], v[38:41]
	s_barrier
	s_add_i32 s31, 0, 0x18000
	v_add_u32_e32 v3, s31, v213
	s_add_i32 s42, 0, 0x1c000
	ds_read_b128 v[58:61], v3
	ds_read_b128 v[62:65], v3 offset:1024
	ds_read_b128 v[74:77], v3 offset:2048
	ds_read_b128 v[78:81], v3 offset:3072
	v_add_u32_e32 v3, s42, v213
	ds_read_b128 v[122:125], v3
	ds_read_b128 v[142:145], v3 offset:1024
	ds_read_b128 v[162:165], v3 offset:2048
	ds_read_b128 v[166:169], v3 offset:3072
	s_add_u32 s40, s54, 0x30000
	s_addc_u32 s41, s55, 0
	s_mov_b32 m0, s68
	ds_read_b128 v[170:173], v216 offset:32768
	ds_read_b128 v[174:177], v216 offset:33792
	ds_read_b128 v[178:181], v216 offset:34816
	ds_read_b128 v[198:201], v216 offset:35840
	ds_read_b128 v[202:205], v216 offset:36864
	ds_read_b128 v[206:209], v216 offset:37888
	ds_read_b128 v[220:223], v216 offset:38912
	ds_read_b128 v[228:231], v216 offset:39936
	global_load_lds_dwordx4 v182, s[40:41]
	s_mov_b32 m0, s69
	s_nop 0
	global_load_lds_dwordx4 v186, s[40:41]
	s_waitcnt vmcnt(8) lgkmcnt(0)
	s_barrier
	v_mfma_f32_16x16x32_bf16 v[158:161], v[58:61], v[170:173], v[158:161]
	v_mfma_f32_16x16x32_bf16 v[154:157], v[74:77], v[170:173], v[154:157]
	v_mfma_f32_16x16x32_bf16 v[138:141], v[58:61], v[178:181], v[138:141]
	v_mfma_f32_16x16x32_bf16 v[134:137], v[74:77], v[178:181], v[134:137]
	v_mfma_f32_16x16x32_bf16 v[118:121], v[58:61], v[202:205], v[118:121]
	v_mfma_f32_16x16x32_bf16 v[114:117], v[74:77], v[202:205], v[114:117]
	v_mfma_f32_16x16x32_bf16 v[102:105], v[58:61], v[220:223], v[102:105]
	v_mfma_f32_16x16x32_bf16 v[98:101], v[74:77], v[220:223], v[98:101]
	v_mfma_f32_16x16x32_bf16 v[158:161], v[62:65], v[174:177], v[158:161]
	v_mfma_f32_16x16x32_bf16 v[154:157], v[78:81], v[174:177], v[154:157]
	v_mfma_f32_16x16x32_bf16 v[138:141], v[62:65], v[198:201], v[138:141]
	v_mfma_f32_16x16x32_bf16 v[134:137], v[78:81], v[198:201], v[134:137]
	v_mfma_f32_16x16x32_bf16 v[118:121], v[62:65], v[206:209], v[118:121]
	v_mfma_f32_16x16x32_bf16 v[114:117], v[78:81], v[206:209], v[114:117]
	v_mfma_f32_16x16x32_bf16 v[102:105], v[62:65], v[228:231], v[102:105]
	v_mfma_f32_16x16x32_bf16 v[98:101], v[78:81], v[228:231], v[98:101]
	v_mfma_f32_16x16x32_bf16 v[150:153], v[122:125], v[170:173], v[150:153]
	v_mfma_f32_16x16x32_bf16 v[146:149], v[162:165], v[170:173], v[146:149]
	v_mfma_f32_16x16x32_bf16 v[130:133], v[122:125], v[178:181], v[130:133]
	v_mfma_f32_16x16x32_bf16 v[126:129], v[162:165], v[178:181], v[126:129]
	v_mfma_f32_16x16x32_bf16 v[110:113], v[122:125], v[202:205], v[110:113]
	v_mfma_f32_16x16x32_bf16 v[106:109], v[162:165], v[202:205], v[106:109]
	v_mfma_f32_16x16x32_bf16 v[94:97], v[122:125], v[220:223], v[94:97]
	v_mfma_f32_16x16x32_bf16 v[90:93], v[162:165], v[220:223], v[90:93]
	v_mfma_f32_16x16x32_bf16 v[150:153], v[142:145], v[174:177], v[150:153]
	v_mfma_f32_16x16x32_bf16 v[146:149], v[166:169], v[174:177], v[146:149]
	v_mfma_f32_16x16x32_bf16 v[130:133], v[142:145], v[198:201], v[130:133]
	v_mfma_f32_16x16x32_bf16 v[126:129], v[166:169], v[198:201], v[126:129]
	v_mfma_f32_16x16x32_bf16 v[110:113], v[142:145], v[206:209], v[110:113]
	v_mfma_f32_16x16x32_bf16 v[106:109], v[166:169], v[206:209], v[106:109]
	v_mfma_f32_16x16x32_bf16 v[94:97], v[142:145], v[228:231], v[94:97]
	v_mfma_f32_16x16x32_bf16 v[90:93], v[166:169], v[228:231], v[90:93]
	s_barrier
	s_add_i32 s31, s31, s64
	s_mov_b32 m0, s31
	ds_read_b128 v[170:173], v216 offset:49152
	ds_read_b128 v[174:177], v216 offset:50176
	ds_read_b128 v[178:181], v216 offset:51200
	ds_read_b128 v[198:201], v216 offset:52224
	ds_read_b128 v[202:205], v216 offset:53248
	ds_read_b128 v[206:209], v216 offset:54272
	ds_read_b128 v[220:223], v216 offset:55296
	ds_read_b128 v[228:231], v216 offset:56320
	global_load_lds_dwordx4 v184, s[98:99]
	s_add_i32 m0, s31, 0x2000
	s_add_u32 s40, s52, 0x10080
	s_addc_u32 s41, s53, 0
	s_add_i32 s31, s42, s64
	global_load_lds_dwordx4 v188, s[98:99]
	s_mov_b32 m0, s31
	s_nop 0
	global_load_lds_dwordx4 v184, s[40:41]
	s_add_i32 m0, s31, 0x2000
	s_nop 0
	global_load_lds_dwordx4 v188, s[40:41]
	s_mov_b32 m0, s76
	s_nop 0
	global_load_lds_dwordx4 v182, s[100:101]
	s_mov_b32 m0, s77
	s_nop 0
	global_load_lds_dwordx4 v186, s[100:101]
	s_waitcnt vmcnt(8) lgkmcnt(0)
	s_barrier
	v_mfma_f32_16x16x32_bf16 v[86:89], v[58:61], v[170:173], v[86:89]
	v_mfma_f32_16x16x32_bf16 v[82:85], v[74:77], v[170:173], v[82:85]
	v_mfma_f32_16x16x32_bf16 v[70:73], v[58:61], v[178:181], v[70:73]
	v_mfma_f32_16x16x32_bf16 v[66:69], v[74:77], v[178:181], v[66:69]
	v_mfma_f32_16x16x32_bf16 v[54:57], v[58:61], v[202:205], v[54:57]
	v_mfma_f32_16x16x32_bf16 v[50:53], v[74:77], v[202:205], v[50:53]
	v_mfma_f32_16x16x32_bf16 v[22:25], v[58:61], v[220:223], v[22:25]
	v_mfma_f32_16x16x32_bf16 v[18:21], v[74:77], v[220:223], v[18:21]
	v_mfma_f32_16x16x32_bf16 v[86:89], v[62:65], v[174:177], v[86:89]
	v_mfma_f32_16x16x32_bf16 v[82:85], v[78:81], v[174:177], v[82:85]
	v_mfma_f32_16x16x32_bf16 v[70:73], v[62:65], v[198:201], v[70:73]
	v_mfma_f32_16x16x32_bf16 v[66:69], v[78:81], v[198:201], v[66:69]
	v_mfma_f32_16x16x32_bf16 v[54:57], v[62:65], v[206:209], v[54:57]
	v_mfma_f32_16x16x32_bf16 v[50:53], v[78:81], v[206:209], v[50:53]
	v_mfma_f32_16x16x32_bf16 v[22:25], v[62:65], v[228:231], v[22:25]
	v_mfma_f32_16x16x32_bf16 v[18:21], v[78:81], v[228:231], v[18:21]
	v_mfma_f32_16x16x32_bf16 v[26:29], v[122:125], v[170:173], v[26:29]
	v_mfma_f32_16x16x32_bf16 v[78:81], v[142:145], v[174:177], v[26:29]
	v_mfma_f32_16x16x32_bf16 v[26:29], v[162:165], v[170:173], v[30:33]
	v_mfma_f32_16x16x32_bf16 v[74:77], v[166:169], v[174:177], v[26:29]
	v_mfma_f32_16x16x32_bf16 v[26:29], v[122:125], v[178:181], v[34:37]
	v_mfma_f32_16x16x32_bf16 v[62:65], v[142:145], v[198:201], v[26:29]
	v_mfma_f32_16x16x32_bf16 v[26:29], v[162:165], v[178:181], v[38:41]
	v_mfma_f32_16x16x32_bf16 v[58:61], v[166:169], v[198:201], v[26:29]
	v_mfma_f32_16x16x32_bf16 v[26:29], v[122:125], v[202:205], v[46:49]
	v_mfma_f32_16x16x32_bf16 v[46:49], v[142:145], v[206:209], v[26:29]
	v_mfma_f32_16x16x32_bf16 v[26:29], v[162:165], v[202:205], v[42:45]
	v_mfma_f32_16x16x32_bf16 v[12:15], v[122:125], v[220:223], v[14:17]
	v_mfma_f32_16x16x32_bf16 v[8:11], v[162:165], v[220:223], v[8:11]
	v_mfma_f32_16x16x32_bf16 v[42:45], v[166:169], v[206:209], v[26:29]
	v_mfma_f32_16x16x32_bf16 v[14:17], v[142:145], v[228:231], v[12:15]
	v_mfma_f32_16x16x32_bf16 v[10:13], v[166:169], v[228:231], v[8:11]
	s_barrier
	s_add_u32 s6, s6, 0x100
	s_addc_u32 s7, s7, 0
	s_add_u32 s14, s14, 0x100
	s_addc_u32 s15, s15, 0
	s_cmp_ge_u32 s33, s12
	s_mov_b32 s31, s33
	s_cbranch_scc0 .LBB0_1038
	s_and_b64 vcc, exec, s[20:21]
	s_cbranch_vccz .LBB0_1041
	s_barrier

.LBB0_1523:
	ds_read_b128 v[2:5], v148
	ds_read_b128 v[6:9], v148 offset:1024
	ds_read_b128 v[10:13], v148 offset:2048
	ds_read_b128 v[14:17], v148 offset:3072
	ds_read_b128 v[18:21], v149
	ds_read_b128 v[22:25], v149 offset:1024
	ds_read_b128 v[26:29], v149 offset:2048
	ds_read_b128 v[30:33], v149 offset:3072
	s_ashr_i32 s47, s46, 31
	s_lshl_b64 s[50:51], s[46:47], 17
	s_add_u32 s50, s1, s50
	s_addc_u32 s51, s12, s51
	s_and_b64 s[6:7], s[6:7], exec
	s_cselect_b32 s7, s51, s59
	s_cselect_b32 s6, s50, s58
	s_add_u32 s64, s56, 0x10080
	s_addc_u32 s65, s57, 0
	s_add_i32 s62, s14, 0xc000
	v_lshl_add_u64 v[66:67], s[64:65], 0, v[130:131]
	s_mov_b32 m0, s62
	s_add_i32 s2, s14, 0xe000
	ds_read_b128 v[34:37], v150
	ds_read_b128 v[38:41], v150 offset:1024
	ds_read_b128 v[42:45], v150 offset:2048
	ds_read_b128 v[46:49], v150 offset:3072
	ds_read_b128 v[50:53], v150 offset:4096
	ds_read_b128 v[54:57], v150 offset:5120
	ds_read_b128 v[58:61], v150 offset:6144
	ds_read_b128 v[62:65], v150 offset:7168
	global_load_lds_dwordx4 v[66:67], off
	v_lshl_add_u64 v[66:67], s[64:65], 0, v[134:135]
	s_mov_b32 m0, s2
	s_nop 0
	global_load_lds_dwordx4 v[66:67], off
	s_waitcnt vmcnt(8) lgkmcnt(0)
	s_barrier
	v_mfma_f32_16x16x32_bf16 v[66:69], v[2:5], v[34:37], 0
	v_mfma_f32_16x16x32_bf16 v[70:73], v[10:13], v[34:37], 0
	v_mfma_f32_16x16x32_bf16 v[74:77], v[2:5], v[42:45], 0
	v_mfma_f32_16x16x32_bf16 v[78:81], v[10:13], v[42:45], 0
	v_mfma_f32_16x16x32_bf16 v[82:85], v[2:5], v[50:53], 0
	v_mfma_f32_16x16x32_bf16 v[86:89], v[10:13], v[50:53], 0
	v_mfma_f32_16x16x32_bf16 v[90:93], v[2:5], v[58:61], 0
	v_mfma_f32_16x16x32_bf16 v[94:97], v[10:13], v[58:61], 0
	v_mfma_f32_16x16x32_bf16 v[66:69], v[6:9], v[38:41], v[66:69]
	v_mfma_f32_16x16x32_bf16 v[70:73], v[14:17], v[38:41], v[70:73]
	v_mfma_f32_16x16x32_bf16 v[74:77], v[6:9], v[46:49], v[74:77]
	v_mfma_f32_16x16x32_bf16 v[78:81], v[14:17], v[46:49], v[78:81]
	v_mfma_f32_16x16x32_bf16 v[82:85], v[6:9], v[54:57], v[82:85]
	v_mfma_f32_16x16x32_bf16 v[86:89], v[14:17], v[54:57], v[86:89]
	v_mfma_f32_16x16x32_bf16 v[90:93], v[6:9], v[62:65], v[90:93]
	v_mfma_f32_16x16x32_bf16 v[94:97], v[14:17], v[62:65], v[94:97]
	v_mfma_f32_16x16x32_bf16 v[98:101], v[18:21], v[34:37], 0
	v_mfma_f32_16x16x32_bf16 v[34:37], v[26:29], v[34:37], 0
	v_mfma_f32_16x16x32_bf16 v[98:101], v[22:25], v[38:41], v[98:101]
	v_mfma_f32_16x16x32_bf16 v[34:37], v[30:33], v[38:41], v[34:37]
	v_mfma_f32_16x16x32_bf16 v[38:41], v[18:21], v[42:45], 0
	v_mfma_f32_16x16x32_bf16 v[42:45], v[26:29], v[42:45], 0
	v_mfma_f32_16x16x32_bf16 v[38:41], v[22:25], v[46:49], v[38:41]
	v_mfma_f32_16x16x32_bf16 v[42:45], v[30:33], v[46:49], v[42:45]
	v_mfma_f32_16x16x32_bf16 v[46:49], v[18:21], v[50:53], 0
	v_mfma_f32_16x16x32_bf16 v[50:53], v[26:29], v[50:53], 0
	v_mfma_f32_16x16x32_bf16 v[46:49], v[22:25], v[54:57], v[46:49]
	v_mfma_f32_16x16x32_bf16 v[50:53], v[30:33], v[54:57], v[50:53]
	v_mfma_f32_16x16x32_bf16 v[54:57], v[18:21], v[58:61], 0
	v_mfma_f32_16x16x32_bf16 v[58:61], v[26:29], v[58:61], 0
	v_mfma_f32_16x16x32_bf16 v[54:57], v[22:25], v[62:65], v[54:57]
	v_mfma_f32_16x16x32_bf16 v[58:61], v[30:33], v[62:65], v[58:61]
	s_barrier
	s_add_i32 s55, s45, s13
	v_lshl_add_u64 v[212:213], s[58:59], 0, v[132:133]
	s_add_i32 s31, s55, 0x2000
	v_lshl_add_u64 v[142:143], v[212:213], 0, s[26:27]
	s_mov_b32 m0, s55
	v_lshl_add_u64 v[214:215], s[58:59], 0, v[136:137]
	s_add_u32 s64, s58, 0x10100
	ds_read_b128 v[62:65], v150 offset:16384
	ds_read_b128 v[102:105], v150 offset:17408
	ds_read_b128 v[106:109], v150 offset:18432
	ds_read_b128 v[110:113], v150 offset:19456
	ds_read_b128 v[114:117], v150 offset:20480
	ds_read_b128 v[118:121], v150 offset:21504
	ds_read_b128 v[122:125], v150 offset:22528
	ds_read_b128 v[126:129], v150 offset:23552
	global_load_lds_dwordx4 v[142:143], off
	v_lshl_add_u64 v[142:143], v[214:215], 0, s[26:27]
	s_mov_b32 m0, s31
	s_addc_u32 s65, s59, 0
	s_add_i32 s47, s60, s13
	global_load_lds_dwordx4 v[142:143], off
	v_lshl_add_u64 v[142:143], s[64:65], 0, v[132:133]
	s_mov_b32 m0, s47
	s_add_i32 s53, s47, 0x2000
	global_load_lds_dwordx4 v[142:143], off
	v_lshl_add_u64 v[142:143], s[64:65], 0, v[136:137]
	s_mov_b32 m0, s53
	v_lshl_add_u64 v[216:217], s[56:57], 0, v[130:131]
	global_load_lds_dwordx4 v[142:143], off
	v_lshl_add_u64 v[142:143], v[216:217], 0, s[26:27]
	s_mov_b32 m0, s14
	v_lshl_add_u64 v[218:219], s[56:57], 0, v[134:135]
	global_load_lds_dwordx4 v[142:143], off
	v_lshl_add_u64 v[142:143], v[218:219], 0, s[26:27]
	s_mov_b32 m0, s15
	s_nop 0
	global_load_lds_dwordx4 v[142:143], off
	s_waitcnt vmcnt(8) lgkmcnt(0)
	s_barrier
	v_mfma_f32_16x16x32_bf16 v[142:145], v[2:5], v[62:65], 0
	v_mfma_f32_16x16x32_bf16 v[156:159], v[2:5], v[106:109], 0
	v_mfma_f32_16x16x32_bf16 v[164:167], v[2:5], v[114:117], 0
	v_mfma_f32_16x16x32_bf16 v[2:5], v[2:5], v[122:125], 0
	v_mfma_f32_16x16x32_bf16 v[142:145], v[6:9], v[102:105], v[142:145]
	v_mfma_f32_16x16x32_bf16 v[156:159], v[6:9], v[110:113], v[156:159]
	v_mfma_f32_16x16x32_bf16 v[164:167], v[6:9], v[118:121], v[164:167]
	v_mfma_f32_16x16x32_bf16 v[2:5], v[6:9], v[126:129], v[2:5]
	v_mfma_f32_16x16x32_bf16 v[6:9], v[10:13], v[122:125], 0
	v_mfma_f32_16x16x32_bf16 v[152:155], v[10:13], v[62:65], 0
	v_mfma_f32_16x16x32_bf16 v[160:163], v[10:13], v[106:109], 0
	v_mfma_f32_16x16x32_bf16 v[168:171], v[10:13], v[114:117], 0
	v_mfma_f32_16x16x32_bf16 v[6:9], v[14:17], v[126:129], v[6:9]
	v_mfma_f32_16x16x32_bf16 v[152:155], v[14:17], v[102:105], v[152:155]
	v_mfma_f32_16x16x32_bf16 v[160:163], v[14:17], v[110:113], v[160:163]
	v_mfma_f32_16x16x32_bf16 v[168:171], v[14:17], v[118:121], v[168:171]
	v_mfma_f32_16x16x32_bf16 v[10:13], v[18:21], v[62:65], 0
	v_mfma_f32_16x16x32_bf16 v[14:17], v[26:29], v[62:65], 0
	v_mfma_f32_16x16x32_bf16 v[10:13], v[22:25], v[102:105], v[10:13]
	v_mfma_f32_16x16x32_bf16 v[14:17], v[30:33], v[102:105], v[14:17]
	v_mfma_f32_16x16x32_bf16 v[62:65], v[18:21], v[106:109], 0
	v_mfma_f32_16x16x32_bf16 v[102:105], v[26:29], v[106:109], 0
	v_mfma_f32_16x16x32_bf16 v[106:109], v[18:21], v[114:117], 0
	v_mfma_f32_16x16x32_bf16 v[18:21], v[18:21], v[122:125], 0
	v_mfma_f32_16x16x32_bf16 v[62:65], v[22:25], v[110:113], v[62:65]
	v_mfma_f32_16x16x32_bf16 v[102:105], v[30:33], v[110:113], v[102:105]
	v_mfma_f32_16x16x32_bf16 v[106:109], v[22:25], v[118:121], v[106:109]
	v_mfma_f32_16x16x32_bf16 v[110:113], v[26:29], v[114:117], 0
	v_mfma_f32_16x16x32_bf16 v[18:21], v[22:25], v[126:129], v[18:21]
	v_mfma_f32_16x16x32_bf16 v[22:25], v[26:29], v[122:125], 0
	v_mfma_f32_16x16x32_bf16 v[110:113], v[30:33], v[118:121], v[110:113]
	v_mfma_f32_16x16x32_bf16 v[22:25], v[30:33], v[126:129], v[22:25]
	s_barrier
	s_add_i32 s63, 0, 0x18000
	s_add_i32 s66, 0, 0x1c000
	v_add_u32_e32 v151, s63, v147
	v_add_u32_e32 v222, s66, v147
	ds_read_b128 v[26:29], v151
	ds_read_b128 v[30:33], v151 offset:1024
	ds_read_b128 v[114:117], v151 offset:2048
	ds_read_b128 v[118:121], v151 offset:3072
	ds_read_b128 v[122:125], v222
	ds_read_b128 v[126:129], v222 offset:1024
	ds_read_b128 v[172:175], v222 offset:2048
	ds_read_b128 v[176:179], v222 offset:3072
	s_add_u32 s64, s56, 0x10100
	s_addc_u32 s65, s57, 0
	s_mov_b32 m0, s33
	v_lshl_add_u64 v[220:221], s[64:65], 0, v[130:131]
	ds_read_b128 v[180:183], v150 offset:32768
	ds_read_b128 v[184:187], v150 offset:33792
	ds_read_b128 v[188:191], v150 offset:34816
	ds_read_b128 v[192:195], v150 offset:35840
	ds_read_b128 v[196:199], v150 offset:36864
	ds_read_b128 v[200:203], v150 offset:37888
	ds_read_b128 v[204:207], v150 offset:38912
	ds_read_b128 v[208:211], v150 offset:39936
	global_load_lds_dwordx4 v[220:221], off
	v_lshl_add_u64 v[220:221], s[64:65], 0, v[134:135]
	s_mov_b32 m0, s40
	s_nop 0
	global_load_lds_dwordx4 v[220:221], off
	s_waitcnt vmcnt(8) lgkmcnt(0)
	s_barrier
	v_mfma_f32_16x16x32_bf16 v[66:69], v[26:29], v[180:183], v[66:69]
	v_mfma_f32_16x16x32_bf16 v[70:73], v[114:117], v[180:183], v[70:73]
	v_mfma_f32_16x16x32_bf16 v[74:77], v[26:29], v[188:191], v[74:77]
	v_mfma_f32_16x16x32_bf16 v[78:81], v[114:117], v[188:191], v[78:81]
	v_mfma_f32_16x16x32_bf16 v[82:85], v[26:29], v[196:199], v[82:85]
	v_mfma_f32_16x16x32_bf16 v[86:89], v[114:117], v[196:199], v[86:89]
	v_mfma_f32_16x16x32_bf16 v[90:93], v[26:29], v[204:207], v[90:93]
	v_mfma_f32_16x16x32_bf16 v[94:97], v[114:117], v[204:207], v[94:97]
	v_mfma_f32_16x16x32_bf16 v[66:69], v[30:33], v[184:187], v[66:69]
	v_mfma_f32_16x16x32_bf16 v[70:73], v[118:121], v[184:187], v[70:73]
	v_mfma_f32_16x16x32_bf16 v[74:77], v[30:33], v[192:195], v[74:77]
	v_mfma_f32_16x16x32_bf16 v[78:81], v[118:121], v[192:195], v[78:81]
	v_mfma_f32_16x16x32_bf16 v[82:85], v[30:33], v[200:203], v[82:85]
	v_mfma_f32_16x16x32_bf16 v[86:89], v[118:121], v[200:203], v[86:89]
	v_mfma_f32_16x16x32_bf16 v[90:93], v[30:33], v[208:211], v[90:93]
	v_mfma_f32_16x16x32_bf16 v[94:97], v[118:121], v[208:211], v[94:97]
	v_mfma_f32_16x16x32_bf16 v[98:101], v[122:125], v[180:183], v[98:101]
	v_mfma_f32_16x16x32_bf16 v[34:37], v[172:175], v[180:183], v[34:37]
	v_mfma_f32_16x16x32_bf16 v[38:41], v[122:125], v[188:191], v[38:41]
	v_mfma_f32_16x16x32_bf16 v[42:45], v[172:175], v[188:191], v[42:45]
	v_mfma_f32_16x16x32_bf16 v[46:49], v[122:125], v[196:199], v[46:49]
	v_mfma_f32_16x16x32_bf16 v[50:53], v[172:175], v[196:199], v[50:53]
	v_mfma_f32_16x16x32_bf16 v[54:57], v[122:125], v[204:207], v[54:57]
	v_mfma_f32_16x16x32_bf16 v[58:61], v[172:175], v[204:207], v[58:61]
	v_mfma_f32_16x16x32_bf16 v[98:101], v[126:129], v[184:187], v[98:101]
	v_mfma_f32_16x16x32_bf16 v[34:37], v[176:179], v[184:187], v[34:37]
	v_mfma_f32_16x16x32_bf16 v[38:41], v[126:129], v[192:195], v[38:41]
	v_mfma_f32_16x16x32_bf16 v[42:45], v[176:179], v[192:195], v[42:45]
	v_mfma_f32_16x16x32_bf16 v[46:49], v[126:129], v[200:203], v[46:49]
	v_mfma_f32_16x16x32_bf16 v[50:53], v[176:179], v[200:203], v[50:53]
	v_mfma_f32_16x16x32_bf16 v[54:57], v[126:129], v[208:211], v[54:57]
	v_mfma_f32_16x16x32_bf16 v[58:61], v[176:179], v[208:211], v[58:61]
	s_barrier
	s_add_i32 s63, s63, s13
	s_add_i32 s61, s63, 0x2000
	v_lshl_add_u64 v[212:213], v[212:213], 0, s[28:29]
	s_mov_b32 m0, s63
	s_add_u32 s64, s58, 0x10180
	ds_read_b128 v[180:183], v150 offset:49152
	ds_read_b128 v[184:187], v150 offset:50176
	ds_read_b128 v[188:191], v150 offset:51200
	ds_read_b128 v[192:195], v150 offset:52224
	ds_read_b128 v[196:199], v150 offset:53248
	ds_read_b128 v[200:203], v150 offset:54272
	ds_read_b128 v[204:207], v150 offset:55296
	ds_read_b128 v[208:211], v150 offset:56320
	global_load_lds_dwordx4 v[212:213], off
	v_lshl_add_u64 v[212:213], v[214:215], 0, s[28:29]
	s_mov_b32 m0, s61
	s_addc_u32 s65, s59, 0
	s_add_i32 s58, s66, s13
	global_load_lds_dwordx4 v[212:213], off
	v_lshl_add_u64 v[212:213], s[64:65], 0, v[132:133]
	s_mov_b32 m0, s58
	s_add_i32 s59, s58, 0x2000
	global_load_lds_dwordx4 v[212:213], off
	v_lshl_add_u64 v[212:213], s[64:65], 0, v[136:137]
	s_mov_b32 m0, s59
	s_nop 0
	global_load_lds_dwordx4 v[212:213], off
	v_lshl_add_u64 v[212:213], v[216:217], 0, s[28:29]
	s_mov_b32 m0, s43
	s_nop 0
	global_load_lds_dwordx4 v[212:213], off
	v_lshl_add_u64 v[212:213], v[218:219], 0, s[28:29]
	s_mov_b32 m0, s44
	s_nop 0
	global_load_lds_dwordx4 v[212:213], off
	s_waitcnt vmcnt(8) lgkmcnt(0)
	s_barrier
	v_mfma_f32_16x16x32_bf16 v[2:5], v[26:29], v[204:207], v[2:5]
	v_mfma_f32_16x16x32_bf16 v[6:9], v[114:117], v[204:207], v[6:9]
	v_mfma_f32_16x16x32_bf16 v[142:145], v[26:29], v[180:183], v[142:145]
	v_mfma_f32_16x16x32_bf16 v[152:155], v[114:117], v[180:183], v[152:155]
	v_mfma_f32_16x16x32_bf16 v[156:159], v[26:29], v[188:191], v[156:159]
	v_mfma_f32_16x16x32_bf16 v[160:163], v[114:117], v[188:191], v[160:163]
	v_mfma_f32_16x16x32_bf16 v[164:167], v[26:29], v[196:199], v[164:167]
	v_mfma_f32_16x16x32_bf16 v[168:171], v[114:117], v[196:199], v[168:171]
	v_mfma_f32_16x16x32_bf16 v[2:5], v[30:33], v[208:211], v[2:5]
	v_mfma_f32_16x16x32_bf16 v[6:9], v[118:121], v[208:211], v[6:9]
	v_mfma_f32_16x16x32_bf16 v[142:145], v[30:33], v[184:187], v[142:145]
	v_mfma_f32_16x16x32_bf16 v[152:155], v[118:121], v[184:187], v[152:155]
	v_mfma_f32_16x16x32_bf16 v[156:159], v[30:33], v[192:195], v[156:159]
	v_mfma_f32_16x16x32_bf16 v[160:163], v[118:121], v[192:195], v[160:163]
	v_mfma_f32_16x16x32_bf16 v[164:167], v[30:33], v[200:203], v[164:167]
	v_mfma_f32_16x16x32_bf16 v[168:171], v[118:121], v[200:203], v[168:171]
	v_mfma_f32_16x16x32_bf16 v[10:13], v[122:125], v[180:183], v[10:13]
	v_mfma_f32_16x16x32_bf16 v[14:17], v[172:175], v[180:183], v[14:17]
	v_mfma_f32_16x16x32_bf16 v[26:29], v[122:125], v[188:191], v[62:65]
	v_mfma_f32_16x16x32_bf16 v[30:33], v[172:175], v[188:191], v[102:105]
	v_mfma_f32_16x16x32_bf16 v[62:65], v[122:125], v[196:199], v[106:109]
	v_mfma_f32_16x16x32_bf16 v[102:105], v[172:175], v[196:199], v[110:113]
	v_mfma_f32_16x16x32_bf16 v[18:21], v[122:125], v[204:207], v[18:21]
	v_mfma_f32_16x16x32_bf16 v[22:25], v[172:175], v[204:207], v[22:25]
	v_mfma_f32_16x16x32_bf16 v[10:13], v[126:129], v[184:187], v[10:13]
	v_mfma_f32_16x16x32_bf16 v[14:17], v[176:179], v[184:187], v[14:17]
	v_mfma_f32_16x16x32_bf16 v[26:29], v[126:129], v[192:195], v[26:29]
	v_mfma_f32_16x16x32_bf16 v[30:33], v[176:179], v[192:195], v[30:33]
	v_mfma_f32_16x16x32_bf16 v[62:65], v[126:129], v[200:203], v[62:65]
	v_mfma_f32_16x16x32_bf16 v[102:105], v[176:179], v[200:203], v[102:105]
	v_mfma_f32_16x16x32_bf16 v[18:21], v[126:129], v[208:211], v[18:21]
	v_mfma_f32_16x16x32_bf16 v[22:25], v[176:179], v[208:211], v[22:25]
	s_barrier
	ds_read_b128 v[106:109], v148
	ds_read_b128 v[110:113], v148 offset:1024
	ds_read_b128 v[114:117], v148 offset:2048
	ds_read_b128 v[118:121], v148 offset:3072
	ds_read_b128 v[122:125], v149
	ds_read_b128 v[126:129], v149 offset:1024
	ds_read_b128 v[172:175], v149 offset:2048
	ds_read_b128 v[176:179], v149 offset:3072
	s_add_u32 s56, s56, 0x10180
	s_addc_u32 s57, s57, 0
	s_mov_b32 m0, s62
	v_lshl_add_u64 v[212:213], s[56:57], 0, v[130:131]
	ds_read_b128 v[180:183], v150
	ds_read_b128 v[184:187], v150 offset:1024
	ds_read_b128 v[188:191], v150 offset:2048
	ds_read_b128 v[192:195], v150 offset:3072
	ds_read_b128 v[196:199], v150 offset:4096
	ds_read_b128 v[200:203], v150 offset:5120
	ds_read_b128 v[204:207], v150 offset:6144
	ds_read_b128 v[208:211], v150 offset:7168
	global_load_lds_dwordx4 v[212:213], off
	v_lshl_add_u64 v[212:213], s[56:57], 0, v[134:135]
	s_mov_b32 m0, s2
	s_nop 0
	global_load_lds_dwordx4 v[212:213], off
	s_waitcnt vmcnt(8) lgkmcnt(0)
	s_barrier
	v_mfma_f32_16x16x32_bf16 v[90:93], v[106:109], v[204:207], v[90:93]
	v_mfma_f32_16x16x32_bf16 v[66:69], v[106:109], v[180:183], v[66:69]
	v_mfma_f32_16x16x32_bf16 v[70:73], v[114:117], v[180:183], v[70:73]
	v_mfma_f32_16x16x32_bf16 v[74:77], v[106:109], v[188:191], v[74:77]
	v_mfma_f32_16x16x32_bf16 v[78:81], v[114:117], v[188:191], v[78:81]
	v_mfma_f32_16x16x32_bf16 v[82:85], v[106:109], v[196:199], v[82:85]
	v_mfma_f32_16x16x32_bf16 v[86:89], v[114:117], v[196:199], v[86:89]
	v_mfma_f32_16x16x32_bf16 v[212:215], v[110:113], v[208:211], v[90:93]
	v_mfma_f32_16x16x32_bf16 v[90:93], v[114:117], v[204:207], v[94:97]
	v_mfma_f32_16x16x32_bf16 v[66:69], v[110:113], v[184:187], v[66:69]
	v_mfma_f32_16x16x32_bf16 v[70:73], v[118:121], v[184:187], v[70:73]
	v_mfma_f32_16x16x32_bf16 v[74:77], v[110:113], v[192:195], v[74:77]
	v_mfma_f32_16x16x32_bf16 v[78:81], v[118:121], v[192:195], v[78:81]
	v_mfma_f32_16x16x32_bf16 v[82:85], v[110:113], v[200:203], v[82:85]
	v_mfma_f32_16x16x32_bf16 v[86:89], v[118:121], v[200:203], v[86:89]
	v_mfma_f32_16x16x32_bf16 v[94:97], v[118:121], v[208:211], v[90:93]
	v_mfma_f32_16x16x32_bf16 v[34:37], v[172:175], v[180:183], v[34:37]
	v_mfma_f32_16x16x32_bf16 v[38:41], v[122:125], v[188:191], v[38:41]
	v_mfma_f32_16x16x32_bf16 v[42:45], v[172:175], v[188:191], v[42:45]
	v_mfma_f32_16x16x32_bf16 v[46:49], v[122:125], v[196:199], v[46:49]
	v_mfma_f32_16x16x32_bf16 v[50:53], v[172:175], v[196:199], v[50:53]
	v_mfma_f32_16x16x32_bf16 v[54:57], v[122:125], v[204:207], v[54:57]
	v_mfma_f32_16x16x32_bf16 v[58:61], v[172:175], v[204:207], v[58:61]
	v_mfma_f32_16x16x32_bf16 v[90:93], v[122:125], v[180:183], v[98:101]
	v_mfma_f32_16x16x32_bf16 v[34:37], v[176:179], v[184:187], v[34:37]
	v_mfma_f32_16x16x32_bf16 v[38:41], v[126:129], v[192:195], v[38:41]
	v_mfma_f32_16x16x32_bf16 v[42:45], v[176:179], v[192:195], v[42:45]
	v_mfma_f32_16x16x32_bf16 v[46:49], v[126:129], v[200:203], v[46:49]
	v_mfma_f32_16x16x32_bf16 v[50:53], v[176:179], v[200:203], v[50:53]
	v_mfma_f32_16x16x32_bf16 v[54:57], v[126:129], v[208:211], v[54:57]
	v_mfma_f32_16x16x32_bf16 v[58:61], v[176:179], v[208:211], v[58:61]
	v_mfma_f32_16x16x32_bf16 v[216:219], v[126:129], v[184:187], v[90:93]
	s_barrier
	s_mov_b32 m0, s55
	v_lshl_add_u64 v[224:225], s[6:7], 0, v[132:133]
	s_add_u32 s56, s6, 0x10000
	ds_read_b128 v[90:93], v150 offset:16384
	ds_read_b128 v[98:101], v150 offset:17408
	ds_read_b128 v[180:183], v150 offset:18432
	ds_read_b128 v[184:187], v150 offset:19456
	ds_read_b128 v[188:191], v150 offset:20480
	ds_read_b128 v[192:195], v150 offset:21504
	ds_read_b128 v[196:199], v150 offset:22528
	ds_read_b128 v[200:203], v150 offset:23552
	global_load_lds_dwordx4 v[224:225], off
	v_lshl_add_u64 v[226:227], s[6:7], 0, v[136:137]
	s_mov_b32 m0, s31
	s_addc_u32 s57, s7, 0
	global_load_lds_dwordx4 v[226:227], off
	v_lshl_add_u64 v[204:205], s[56:57], 0, v[132:133]
	s_mov_b32 m0, s47
	v_lshl_add_u64 v[248:249], s[48:49], 0, v[130:131]
	global_load_lds_dwordx4 v[204:205], off
	v_lshl_add_u64 v[204:205], s[56:57], 0, v[136:137]
	s_mov_b32 m0, s53
	v_lshl_add_u64 v[250:251], s[48:49], 0, v[134:135]
	global_load_lds_dwordx4 v[204:205], off
	s_mov_b32 m0, s14
	s_nop 0
	global_load_lds_dwordx4 v[248:249], off
	s_mov_b32 m0, s15
	s_nop 0
	global_load_lds_dwordx4 v[250:251], off
	s_waitcnt vmcnt(8) lgkmcnt(0)
	s_barrier
	v_mfma_f32_16x16x32_bf16 v[2:5], v[106:109], v[196:199], v[2:5]
	v_mfma_f32_16x16x32_bf16 v[6:9], v[114:117], v[196:199], v[6:9]
	v_mfma_f32_16x16x32_bf16 v[142:145], v[106:109], v[90:93], v[142:145]
	v_mfma_f32_16x16x32_bf16 v[152:155], v[114:117], v[90:93], v[152:155]
	v_mfma_f32_16x16x32_bf16 v[156:159], v[106:109], v[180:183], v[156:159]
	v_mfma_f32_16x16x32_bf16 v[160:163], v[114:117], v[180:183], v[160:163]
	v_mfma_f32_16x16x32_bf16 v[164:167], v[106:109], v[188:191], v[164:167]
	v_mfma_f32_16x16x32_bf16 v[168:171], v[114:117], v[188:191], v[168:171]
	v_mfma_f32_16x16x32_bf16 v[2:5], v[110:113], v[200:203], v[2:5]
	v_mfma_f32_16x16x32_bf16 v[6:9], v[118:121], v[200:203], v[6:9]
	v_mfma_f32_16x16x32_bf16 v[142:145], v[110:113], v[98:101], v[142:145]
	v_mfma_f32_16x16x32_bf16 v[152:155], v[118:121], v[98:101], v[152:155]
	v_mfma_f32_16x16x32_bf16 v[156:159], v[110:113], v[184:187], v[156:159]
	v_mfma_f32_16x16x32_bf16 v[160:163], v[118:121], v[184:187], v[160:163]
	v_mfma_f32_16x16x32_bf16 v[164:167], v[110:113], v[192:195], v[164:167]
	v_mfma_f32_16x16x32_bf16 v[168:171], v[118:121], v[192:195], v[168:171]
	v_mfma_f32_16x16x32_bf16 v[10:13], v[122:125], v[90:93], v[10:13]
	v_mfma_f32_16x16x32_bf16 v[204:207], v[126:129], v[98:101], v[10:13]
	v_mfma_f32_16x16x32_bf16 v[10:13], v[172:175], v[90:93], v[14:17]
	v_mfma_f32_16x16x32_bf16 v[14:17], v[176:179], v[98:101], v[10:13]
	v_mfma_f32_16x16x32_bf16 v[10:13], v[122:125], v[180:183], v[26:29]
	v_mfma_f32_16x16x32_bf16 v[208:211], v[126:129], v[184:187], v[10:13]
	v_mfma_f32_16x16x32_bf16 v[10:13], v[172:175], v[180:183], v[30:33]
	v_mfma_f32_16x16x32_bf16 v[30:33], v[176:179], v[184:187], v[10:13]
	v_mfma_f32_16x16x32_bf16 v[10:13], v[122:125], v[188:191], v[62:65]
	v_mfma_f32_16x16x32_bf16 v[180:183], v[126:129], v[192:195], v[10:13]
	v_mfma_f32_16x16x32_bf16 v[10:13], v[172:175], v[188:191], v[102:105]
	v_mfma_f32_16x16x32_bf16 v[184:187], v[176:179], v[192:195], v[10:13]
	v_mfma_f32_16x16x32_bf16 v[10:13], v[122:125], v[196:199], v[18:21]
	v_mfma_f32_16x16x32_bf16 v[188:191], v[126:129], v[200:203], v[10:13]
	v_mfma_f32_16x16x32_bf16 v[10:13], v[172:175], v[196:199], v[22:25]
	v_mfma_f32_16x16x32_bf16 v[172:175], v[176:179], v[200:203], v[10:13]
	s_barrier
	s_nop 4
	ds_read_b128 v[10:13], v151
	ds_read_b128 v[22:25], v151 offset:1024
	ds_read_b128 v[62:65], v151 offset:2048
	ds_read_b128 v[176:179], v151 offset:3072
	ds_read_b128 v[192:195], v222
	ds_read_b128 v[196:199], v222 offset:1024
	ds_read_b128 v[200:203], v222 offset:2048
	ds_read_b128 v[220:223], v222 offset:3072
	s_add_u32 s56, s48, 0x10000
	s_addc_u32 s57, s49, 0
	s_mov_b32 m0, s33
	v_lshl_add_u64 v[90:91], s[56:57], 0, v[130:131]
	ds_read_b128 v[18:21], v150 offset:32768
	ds_read_b128 v[26:29], v150 offset:33792
	ds_read_b128 v[102:105], v150 offset:34816
	ds_read_b128 v[228:231], v150 offset:35840
	ds_read_b128 v[232:235], v150 offset:36864
	ds_read_b128 v[236:239], v150 offset:37888
	ds_read_b128 v[240:243], v150 offset:38912
	ds_read_b128 v[244:247], v150 offset:39936
	global_load_lds_dwordx4 v[90:91], off
	v_lshl_add_u64 v[90:91], s[56:57], 0, v[134:135]
	s_mov_b32 m0, s40
	s_nop 0
	global_load_lds_dwordx4 v[90:91], off
	s_waitcnt vmcnt(8) lgkmcnt(0)
	s_barrier
	v_mfma_f32_16x16x32_bf16 v[66:69], v[10:13], v[18:21], v[66:69]
	v_mfma_f32_16x16x32_bf16 v[122:125], v[22:25], v[26:29], v[66:69]
	v_mfma_f32_16x16x32_bf16 v[66:69], v[62:65], v[18:21], v[70:73]
	v_mfma_f32_16x16x32_bf16 v[114:117], v[176:179], v[26:29], v[66:69]
	v_mfma_f32_16x16x32_bf16 v[66:69], v[10:13], v[102:105], v[74:77]
	v_mfma_f32_16x16x32_bf16 v[106:109], v[22:25], v[228:231], v[66:69]
	v_mfma_f32_16x16x32_bf16 v[66:69], v[62:65], v[102:105], v[78:81]
	v_mfma_f32_16x16x32_bf16 v[98:101], v[176:179], v[228:231], v[66:69]
	v_mfma_f32_16x16x32_bf16 v[66:69], v[10:13], v[232:235], v[82:85]
	v_mfma_f32_16x16x32_bf16 v[90:93], v[22:25], v[236:239], v[66:69]
	v_mfma_f32_16x16x32_bf16 v[66:69], v[62:65], v[232:235], v[86:89]
	v_mfma_f32_16x16x32_bf16 v[82:85], v[176:179], v[236:239], v[66:69]
	v_mfma_f32_16x16x32_bf16 v[66:69], v[10:13], v[240:243], v[212:215]
	v_mfma_f32_16x16x32_bf16 v[74:77], v[22:25], v[244:247], v[66:69]
	v_mfma_f32_16x16x32_bf16 v[66:69], v[62:65], v[240:243], v[94:97]
	v_mfma_f32_16x16x32_bf16 v[66:69], v[176:179], v[244:247], v[66:69]
	v_mfma_f32_16x16x32_bf16 v[70:73], v[192:195], v[18:21], v[216:219]
	v_mfma_f32_16x16x32_bf16 v[18:21], v[200:203], v[18:21], v[34:37]
	v_mfma_f32_16x16x32_bf16 v[118:121], v[220:223], v[26:29], v[18:21]
	v_mfma_f32_16x16x32_bf16 v[18:21], v[192:195], v[102:105], v[38:41]
	v_mfma_f32_16x16x32_bf16 v[110:113], v[196:199], v[228:231], v[18:21]
	v_mfma_f32_16x16x32_bf16 v[18:21], v[200:203], v[102:105], v[42:45]
	v_mfma_f32_16x16x32_bf16 v[102:105], v[220:223], v[228:231], v[18:21]
	v_mfma_f32_16x16x32_bf16 v[18:21], v[192:195], v[232:235], v[46:49]
	v_mfma_f32_16x16x32_bf16 v[94:97], v[196:199], v[236:239], v[18:21]
	v_mfma_f32_16x16x32_bf16 v[18:21], v[200:203], v[232:235], v[50:53]
	v_mfma_f32_16x16x32_bf16 v[86:89], v[220:223], v[236:239], v[18:21]
	v_mfma_f32_16x16x32_bf16 v[18:21], v[192:195], v[240:243], v[54:57]
	v_mfma_f32_16x16x32_bf16 v[78:81], v[196:199], v[244:247], v[18:21]
	v_mfma_f32_16x16x32_bf16 v[18:21], v[200:203], v[240:243], v[58:61]
	v_mfma_f32_16x16x32_bf16 v[126:129], v[196:199], v[26:29], v[70:73]
	v_mfma_f32_16x16x32_bf16 v[70:73], v[220:223], v[244:247], v[18:21]
	s_barrier
	s_mov_b32 m0, s63
	s_nop 2
	v_lshl_add_u64 v[18:19], v[224:225], 0, s[20:21]
	s_add_u32 s6, s6, 0x10080
	ds_read_b128 v[38:41], v150 offset:49152
	ds_read_b128 v[46:49], v150 offset:50176
	ds_read_b128 v[212:215], v150 offset:51200
	ds_read_b128 v[216:219], v150 offset:52224
	ds_read_b128 v[228:231], v150 offset:53248
	ds_read_b128 v[232:235], v150 offset:54272
	ds_read_b128 v[236:239], v150 offset:55296
	ds_read_b128 v[240:243], v150 offset:56320
	global_load_lds_dwordx4 v[18:19], off
	v_lshl_add_u64 v[18:19], v[226:227], 0, s[20:21]
	s_mov_b32 m0, s61
	s_addc_u32 s7, s7, 0
	global_load_lds_dwordx4 v[18:19], off
	v_lshl_add_u64 v[18:19], s[6:7], 0, v[132:133]
	s_mov_b32 m0, s58
	s_nop 0
	global_load_lds_dwordx4 v[18:19], off
	v_lshl_add_u64 v[18:19], s[6:7], 0, v[136:137]
	s_mov_b32 m0, s59
	s_nop 0
	global_load_lds_dwordx4 v[18:19], off
	v_lshl_add_u64 v[18:19], v[248:249], 0, s[20:21]
	s_mov_b32 m0, s43
	s_nop 0
	global_load_lds_dwordx4 v[18:19], off
	v_lshl_add_u64 v[18:19], v[250:251], 0, s[20:21]
	s_mov_b32 m0, s44
	s_nop 0
	global_load_lds_dwordx4 v[18:19], off
	s_waitcnt vmcnt(8) lgkmcnt(0)
	s_barrier
	v_mfma_f32_16x16x32_bf16 v[18:21], v[10:13], v[38:41], v[142:145]
	v_mfma_f32_16x16x32_bf16 v[58:61], v[22:25], v[46:49], v[18:21]
	v_mfma_f32_16x16x32_bf16 v[18:21], v[62:65], v[38:41], v[152:155]
	v_mfma_f32_16x16x32_bf16 v[50:53], v[176:179], v[46:49], v[18:21]
	v_mfma_f32_16x16x32_bf16 v[18:21], v[10:13], v[212:215], v[156:159]
	v_mfma_f32_16x16x32_bf16 v[42:45], v[22:25], v[216:219], v[18:21]
	v_mfma_f32_16x16x32_bf16 v[18:21], v[62:65], v[212:215], v[160:163]
	v_mfma_f32_16x16x32_bf16 v[34:37], v[176:179], v[216:219], v[18:21]
	v_mfma_f32_16x16x32_bf16 v[18:21], v[10:13], v[228:231], v[164:167]
	v_mfma_f32_16x16x32_bf16 v[2:5], v[10:13], v[236:239], v[2:5]
	v_mfma_f32_16x16x32_bf16 v[26:29], v[22:25], v[232:235], v[18:21]
	v_mfma_f32_16x16x32_bf16 v[18:21], v[62:65], v[228:231], v[168:171]
	v_mfma_f32_16x16x32_bf16 v[10:13], v[22:25], v[240:243], v[2:5]
	v_mfma_f32_16x16x32_bf16 v[2:5], v[62:65], v[236:239], v[6:9]
	v_mfma_f32_16x16x32_bf16 v[18:21], v[176:179], v[232:235], v[18:21]
	v_mfma_f32_16x16x32_bf16 v[2:5], v[176:179], v[240:243], v[2:5]
	v_mfma_f32_16x16x32_bf16 v[6:9], v[192:195], v[38:41], v[204:207]
	v_mfma_f32_16x16x32_bf16 v[62:65], v[196:199], v[46:49], v[6:9]
	v_mfma_f32_16x16x32_bf16 v[6:9], v[200:203], v[38:41], v[14:17]
	v_mfma_f32_16x16x32_bf16 v[54:57], v[220:223], v[46:49], v[6:9]
	v_mfma_f32_16x16x32_bf16 v[6:9], v[192:195], v[212:215], v[208:211]
	v_mfma_f32_16x16x32_bf16 v[46:49], v[196:199], v[216:219], v[6:9]
	v_mfma_f32_16x16x32_bf16 v[6:9], v[200:203], v[212:215], v[30:33]
	v_mfma_f32_16x16x32_bf16 v[38:41], v[220:223], v[216:219], v[6:9]
	v_mfma_f32_16x16x32_bf16 v[6:9], v[192:195], v[228:231], v[180:183]
	v_mfma_f32_16x16x32_bf16 v[30:33], v[196:199], v[232:235], v[6:9]
	v_mfma_f32_16x16x32_bf16 v[6:9], v[200:203], v[228:231], v[184:187]
	v_mfma_f32_16x16x32_bf16 v[22:25], v[220:223], v[232:235], v[6:9]
	v_mfma_f32_16x16x32_bf16 v[6:9], v[192:195], v[236:239], v[188:191]
	v_mfma_f32_16x16x32_bf16 v[14:17], v[196:199], v[240:243], v[6:9]
	v_mfma_f32_16x16x32_bf16 v[6:9], v[200:203], v[236:239], v[172:175]
	v_mfma_f32_16x16x32_bf16 v[6:9], v[220:223], v[240:243], v[6:9]
	s_barrier
	s_andn2_b64 vcc, exec, s[22:23]
	s_cbranch_vccnz .LBB0_1525
	s_barrier

.LBB0_1631:
	v_add_u32_e32 v153, s44, v151
	ds_read_b128 v[154:157], v153
	ds_read_b128 v[158:161], v153 offset:1024
	ds_read_b128 v[162:165], v153 offset:2048
	ds_read_b128 v[166:169], v153 offset:3072
	v_add_u32_e32 v153, s45, v151
	s_add_u32 s46, s18, s30
	ds_read_b128 v[170:173], v153
	ds_read_b128 v[174:177], v153 offset:1024
	ds_read_b128 v[178:181], v153 offset:2048
	ds_read_b128 v[182:185], v153 offset:3072
	s_addc_u32 s47, s19, s31
	s_add_u32 s46, s46, 0x100
	s_addc_u32 s47, s47, 0
	s_add_u32 s55, s50, s30
	s_addc_u32 s56, s51, s31
	s_cmpk_eq_i32 s30, 0x700
	s_cselect_b32 s49, s25, s47
	s_cselect_b32 s48, s52, s46
	s_cselect_b32 s47, s23, s56
	s_cselect_b32 s46, s53, s55
	v_lshl_add_u64 v[218:219], v[146:147], 0, s[30:31]
	s_add_i32 m0, s33, 0xc000
	ds_read_b128 v[186:189], v152
	ds_read_b128 v[190:193], v152 offset:1024
	ds_read_b128 v[194:197], v152 offset:2048
	ds_read_b128 v[198:201], v152 offset:3072
	ds_read_b128 v[202:205], v152 offset:4096
	ds_read_b128 v[206:209], v152 offset:5120
	ds_read_b128 v[210:213], v152 offset:6144
	ds_read_b128 v[214:217], v152 offset:7168
	global_load_lds_dwordx4 v[218:219], off
	v_lshl_add_u64 v[218:219], v[148:149], 0, s[30:31]
	s_add_i32 m0, s33, 0xe000
	s_nop 0
	global_load_lds_dwordx4 v[218:219], off
	s_waitcnt vmcnt(8) lgkmcnt(0)
	s_barrier
	v_mfma_f32_16x16x32_bf16 v[126:129], v[154:157], v[186:189], v[126:129]
	v_mfma_f32_16x16x32_bf16 v[122:125], v[162:165], v[186:189], v[122:125]
	v_mfma_f32_16x16x32_bf16 v[110:113], v[154:157], v[194:197], v[110:113]
	v_mfma_f32_16x16x32_bf16 v[106:109], v[162:165], v[194:197], v[106:109]
	v_mfma_f32_16x16x32_bf16 v[94:97], v[154:157], v[202:205], v[94:97]
	v_mfma_f32_16x16x32_bf16 v[90:93], v[162:165], v[202:205], v[90:93]
	v_mfma_f32_16x16x32_bf16 v[78:81], v[154:157], v[210:213], v[78:81]
	v_mfma_f32_16x16x32_bf16 v[74:77], v[162:165], v[210:213], v[74:77]
	v_mfma_f32_16x16x32_bf16 v[126:129], v[158:161], v[190:193], v[126:129]
	v_mfma_f32_16x16x32_bf16 v[122:125], v[166:169], v[190:193], v[122:125]
	v_mfma_f32_16x16x32_bf16 v[110:113], v[158:161], v[198:201], v[110:113]
	v_mfma_f32_16x16x32_bf16 v[106:109], v[166:169], v[198:201], v[106:109]
	v_mfma_f32_16x16x32_bf16 v[94:97], v[158:161], v[206:209], v[94:97]
	v_mfma_f32_16x16x32_bf16 v[90:93], v[166:169], v[206:209], v[90:93]
	v_mfma_f32_16x16x32_bf16 v[78:81], v[158:161], v[214:217], v[78:81]
	v_mfma_f32_16x16x32_bf16 v[74:77], v[166:169], v[214:217], v[74:77]
	v_mfma_f32_16x16x32_bf16 v[118:121], v[170:173], v[186:189], v[118:121]
	v_mfma_f32_16x16x32_bf16 v[114:117], v[178:181], v[186:189], v[114:117]
	v_mfma_f32_16x16x32_bf16 v[102:105], v[170:173], v[194:197], v[102:105]
	v_mfma_f32_16x16x32_bf16 v[98:101], v[178:181], v[194:197], v[98:101]
	v_mfma_f32_16x16x32_bf16 v[86:89], v[170:173], v[202:205], v[86:89]
	v_mfma_f32_16x16x32_bf16 v[82:85], v[178:181], v[202:205], v[82:85]
	v_mfma_f32_16x16x32_bf16 v[70:73], v[170:173], v[210:213], v[70:73]
	v_mfma_f32_16x16x32_bf16 v[66:69], v[178:181], v[210:213], v[66:69]
	v_mfma_f32_16x16x32_bf16 v[118:121], v[174:177], v[190:193], v[118:121]
	v_mfma_f32_16x16x32_bf16 v[114:117], v[182:185], v[190:193], v[114:117]
	v_mfma_f32_16x16x32_bf16 v[102:105], v[174:177], v[198:201], v[102:105]
	v_mfma_f32_16x16x32_bf16 v[98:101], v[182:185], v[198:201], v[98:101]
	v_mfma_f32_16x16x32_bf16 v[86:89], v[174:177], v[206:209], v[86:89]
	v_mfma_f32_16x16x32_bf16 v[82:85], v[182:185], v[206:209], v[82:85]
	v_mfma_f32_16x16x32_bf16 v[70:73], v[174:177], v[214:217], v[70:73]
	v_mfma_f32_16x16x32_bf16 v[66:69], v[182:185], v[214:217], v[66:69]
	s_barrier
	s_add_i32 s55, s44, s13
	s_add_u32 s98, s46, s20
	s_addc_u32 s99, s47, s21
	s_mov_b32 m0, s55
	ds_read_b128 v[186:189], v152 offset:16384
	ds_read_b128 v[190:193], v152 offset:17408
	ds_read_b128 v[194:197], v152 offset:18432
	ds_read_b128 v[198:201], v152 offset:19456
	ds_read_b128 v[202:205], v152 offset:20480
	ds_read_b128 v[206:209], v152 offset:21504
	ds_read_b128 v[210:213], v152 offset:22528
	ds_read_b128 v[214:217], v152 offset:23552
	global_load_lds_dwordx4 v132, s[46:47]
	s_add_i32 m0, s55, 0x2000
	s_add_u32 s56, s46, 0x40000
	s_addc_u32 s57, s47, 0
	s_add_i32 s55, s45, s13
	global_load_lds_dwordx4 v136, s[46:47]
	s_mov_b32 m0, s55
	s_nop 0
	global_load_lds_dwordx4 v132, s[56:57]
	s_add_i32 m0, s55, 0x2000
	s_nop 0
	global_load_lds_dwordx4 v136, s[56:57]
	s_add_u32 s100, s48, s20
	s_addc_u32 s101, s49, s21
	s_mov_b32 m0, s33
	s_nop 0
	global_load_lds_dwordx4 v130, s[48:49]
	s_mov_b32 m0, s14
	s_nop 0
	global_load_lds_dwordx4 v134, s[48:49]
	s_waitcnt vmcnt(8) lgkmcnt(0)
	s_barrier
	v_mfma_f32_16x16x32_bf16 v[62:65], v[154:157], v[186:189], v[62:65]
	v_mfma_f32_16x16x32_bf16 v[58:61], v[162:165], v[186:189], v[58:61]
	v_mfma_f32_16x16x32_bf16 v[46:49], v[154:157], v[194:197], v[46:49]
	v_mfma_f32_16x16x32_bf16 v[42:45], v[162:165], v[194:197], v[42:45]
	v_mfma_f32_16x16x32_bf16 v[30:33], v[154:157], v[202:205], v[30:33]
	v_mfma_f32_16x16x32_bf16 v[26:29], v[162:165], v[202:205], v[26:29]
	v_mfma_f32_16x16x32_bf16 v[14:17], v[154:157], v[210:213], v[14:17]
	v_mfma_f32_16x16x32_bf16 v[10:13], v[162:165], v[210:213], v[10:13]
	v_mfma_f32_16x16x32_bf16 v[62:65], v[158:161], v[190:193], v[62:65]
	v_mfma_f32_16x16x32_bf16 v[58:61], v[166:169], v[190:193], v[58:61]
	v_mfma_f32_16x16x32_bf16 v[46:49], v[158:161], v[198:201], v[46:49]
	v_mfma_f32_16x16x32_bf16 v[42:45], v[166:169], v[198:201], v[42:45]
	v_mfma_f32_16x16x32_bf16 v[30:33], v[158:161], v[206:209], v[30:33]
	v_mfma_f32_16x16x32_bf16 v[26:29], v[166:169], v[206:209], v[26:29]
	v_mfma_f32_16x16x32_bf16 v[14:17], v[158:161], v[214:217], v[14:17]
	v_mfma_f32_16x16x32_bf16 v[10:13], v[166:169], v[214:217], v[10:13]
	v_mfma_f32_16x16x32_bf16 v[54:57], v[170:173], v[186:189], v[54:57]
	v_mfma_f32_16x16x32_bf16 v[50:53], v[178:181], v[186:189], v[50:53]
	v_mfma_f32_16x16x32_bf16 v[38:41], v[170:173], v[194:197], v[38:41]
	v_mfma_f32_16x16x32_bf16 v[34:37], v[178:181], v[194:197], v[34:37]
	v_mfma_f32_16x16x32_bf16 v[22:25], v[170:173], v[202:205], v[22:25]
	v_mfma_f32_16x16x32_bf16 v[18:21], v[178:181], v[202:205], v[18:21]
	v_mfma_f32_16x16x32_bf16 v[6:9], v[170:173], v[210:213], v[6:9]
	v_mfma_f32_16x16x32_bf16 v[2:5], v[178:181], v[210:213], v[2:5]
	v_mfma_f32_16x16x32_bf16 v[54:57], v[174:177], v[190:193], v[54:57]
	v_mfma_f32_16x16x32_bf16 v[50:53], v[182:185], v[190:193], v[50:53]
	v_mfma_f32_16x16x32_bf16 v[38:41], v[174:177], v[198:201], v[38:41]
	v_mfma_f32_16x16x32_bf16 v[34:37], v[182:185], v[198:201], v[34:37]
	v_mfma_f32_16x16x32_bf16 v[22:25], v[174:177], v[206:209], v[22:25]
	v_mfma_f32_16x16x32_bf16 v[18:21], v[182:185], v[206:209], v[18:21]
	v_mfma_f32_16x16x32_bf16 v[6:9], v[174:177], v[214:217], v[6:9]
	v_mfma_f32_16x16x32_bf16 v[2:5], v[182:185], v[214:217], v[2:5]
	s_barrier
	s_add_i32 s55, 0, 0x18000
	v_add_u32_e32 v153, s55, v151
	s_add_i32 s56, 0, 0x1c000
	ds_read_b128 v[154:157], v153
	ds_read_b128 v[158:161], v153 offset:1024
	ds_read_b128 v[162:165], v153 offset:2048
	ds_read_b128 v[166:169], v153 offset:3072
	v_add_u32_e32 v153, s56, v151
	ds_read_b128 v[170:173], v153
	ds_read_b128 v[174:177], v153 offset:1024
	ds_read_b128 v[178:181], v153 offset:2048
	ds_read_b128 v[182:185], v153 offset:3072
	s_add_u32 s48, s48, 0x40000
	s_addc_u32 s49, s49, 0
	s_mov_b32 m0, s15
	ds_read_b128 v[186:189], v152 offset:32768
	ds_read_b128 v[190:193], v152 offset:33792
	ds_read_b128 v[194:197], v152 offset:34816
	ds_read_b128 v[198:201], v152 offset:35840
	ds_read_b128 v[202:205], v152 offset:36864
	ds_read_b128 v[206:209], v152 offset:37888
	ds_read_b128 v[210:213], v152 offset:38912
	ds_read_b128 v[214:217], v152 offset:39936
	global_load_lds_dwordx4 v130, s[48:49]
	s_mov_b32 m0, s40
	s_nop 0
	global_load_lds_dwordx4 v134, s[48:49]
	s_waitcnt vmcnt(8) lgkmcnt(0)
	s_barrier
	v_mfma_f32_16x16x32_bf16 v[126:129], v[154:157], v[186:189], v[126:129]
	v_mfma_f32_16x16x32_bf16 v[122:125], v[162:165], v[186:189], v[122:125]
	v_mfma_f32_16x16x32_bf16 v[110:113], v[154:157], v[194:197], v[110:113]
	v_mfma_f32_16x16x32_bf16 v[106:109], v[162:165], v[194:197], v[106:109]
	v_mfma_f32_16x16x32_bf16 v[94:97], v[154:157], v[202:205], v[94:97]
	v_mfma_f32_16x16x32_bf16 v[90:93], v[162:165], v[202:205], v[90:93]
	v_mfma_f32_16x16x32_bf16 v[78:81], v[154:157], v[210:213], v[78:81]
	v_mfma_f32_16x16x32_bf16 v[74:77], v[162:165], v[210:213], v[74:77]
	v_mfma_f32_16x16x32_bf16 v[126:129], v[158:161], v[190:193], v[126:129]
	v_mfma_f32_16x16x32_bf16 v[122:125], v[166:169], v[190:193], v[122:125]
	v_mfma_f32_16x16x32_bf16 v[110:113], v[158:161], v[198:201], v[110:113]
	v_mfma_f32_16x16x32_bf16 v[106:109], v[166:169], v[198:201], v[106:109]
	v_mfma_f32_16x16x32_bf16 v[94:97], v[158:161], v[206:209], v[94:97]
	v_mfma_f32_16x16x32_bf16 v[90:93], v[166:169], v[206:209], v[90:93]
	v_mfma_f32_16x16x32_bf16 v[78:81], v[158:161], v[214:217], v[78:81]
	v_mfma_f32_16x16x32_bf16 v[74:77], v[166:169], v[214:217], v[74:77]
	v_mfma_f32_16x16x32_bf16 v[118:121], v[170:173], v[186:189], v[118:121]
	v_mfma_f32_16x16x32_bf16 v[114:117], v[178:181], v[186:189], v[114:117]
	v_mfma_f32_16x16x32_bf16 v[102:105], v[170:173], v[194:197], v[102:105]
	v_mfma_f32_16x16x32_bf16 v[98:101], v[178:181], v[194:197], v[98:101]
	v_mfma_f32_16x16x32_bf16 v[86:89], v[170:173], v[202:205], v[86:89]
	v_mfma_f32_16x16x32_bf16 v[82:85], v[178:181], v[202:205], v[82:85]
	v_mfma_f32_16x16x32_bf16 v[70:73], v[170:173], v[210:213], v[70:73]
	v_mfma_f32_16x16x32_bf16 v[66:69], v[178:181], v[210:213], v[66:69]
	v_mfma_f32_16x16x32_bf16 v[118:121], v[174:177], v[190:193], v[118:121]
	v_mfma_f32_16x16x32_bf16 v[114:117], v[182:185], v[190:193], v[114:117]
	v_mfma_f32_16x16x32_bf16 v[102:105], v[174:177], v[198:201], v[102:105]
	v_mfma_f32_16x16x32_bf16 v[98:101], v[182:185], v[198:201], v[98:101]
	v_mfma_f32_16x16x32_bf16 v[86:89], v[174:177], v[206:209], v[86:89]
	v_mfma_f32_16x16x32_bf16 v[82:85], v[182:185], v[206:209], v[82:85]
	v_mfma_f32_16x16x32_bf16 v[70:73], v[174:177], v[214:217], v[70:73]
	v_mfma_f32_16x16x32_bf16 v[66:69], v[182:185], v[214:217], v[66:69]
	s_barrier
	s_add_i32 s48, s55, s13
	s_mov_b32 m0, s48
	ds_read_b128 v[186:189], v152 offset:49152
	ds_read_b128 v[190:193], v152 offset:50176
	ds_read_b128 v[194:197], v152 offset:51200
	ds_read_b128 v[198:201], v152 offset:52224
	ds_read_b128 v[202:205], v152 offset:53248
	ds_read_b128 v[206:209], v152 offset:54272
	ds_read_b128 v[210:213], v152 offset:55296
	ds_read_b128 v[214:217], v152 offset:56320
	global_load_lds_dwordx4 v132, s[98:99]
	s_add_i32 m0, s48, 0x2000
	s_add_u32 s46, s46, 0x40080
	s_addc_u32 s47, s47, 0
	s_add_i32 s48, s56, s13
	global_load_lds_dwordx4 v136, s[98:99]
	s_mov_b32 m0, s48
	s_nop 0
	global_load_lds_dwordx4 v132, s[46:47]
	s_add_i32 m0, s48, 0x2000
	s_nop 0
	global_load_lds_dwordx4 v136, s[46:47]
	s_mov_b32 m0, s42
	s_nop 0
	global_load_lds_dwordx4 v130, s[100:101]
	s_mov_b32 m0, s43
	s_nop 0
	global_load_lds_dwordx4 v134, s[100:101]
	s_waitcnt vmcnt(8) lgkmcnt(0)
	s_barrier
	v_mfma_f32_16x16x32_bf16 v[62:65], v[154:157], v[186:189], v[62:65]
	v_mfma_f32_16x16x32_bf16 v[58:61], v[162:165], v[186:189], v[58:61]
	v_mfma_f32_16x16x32_bf16 v[46:49], v[154:157], v[194:197], v[46:49]
	v_mfma_f32_16x16x32_bf16 v[42:45], v[162:165], v[194:197], v[42:45]
	v_mfma_f32_16x16x32_bf16 v[30:33], v[154:157], v[202:205], v[30:33]
	v_mfma_f32_16x16x32_bf16 v[26:29], v[162:165], v[202:205], v[26:29]
	v_mfma_f32_16x16x32_bf16 v[14:17], v[154:157], v[210:213], v[14:17]
	v_mfma_f32_16x16x32_bf16 v[10:13], v[162:165], v[210:213], v[10:13]
	v_mfma_f32_16x16x32_bf16 v[62:65], v[158:161], v[190:193], v[62:65]
	v_mfma_f32_16x16x32_bf16 v[58:61], v[166:169], v[190:193], v[58:61]
	v_mfma_f32_16x16x32_bf16 v[46:49], v[158:161], v[198:201], v[46:49]
	v_mfma_f32_16x16x32_bf16 v[42:45], v[166:169], v[198:201], v[42:45]
	v_mfma_f32_16x16x32_bf16 v[30:33], v[158:161], v[206:209], v[30:33]
	v_mfma_f32_16x16x32_bf16 v[26:29], v[166:169], v[206:209], v[26:29]
	v_mfma_f32_16x16x32_bf16 v[14:17], v[158:161], v[214:217], v[14:17]
	v_mfma_f32_16x16x32_bf16 v[10:13], v[166:169], v[214:217], v[10:13]
	v_mfma_f32_16x16x32_bf16 v[54:57], v[170:173], v[186:189], v[54:57]
	v_mfma_f32_16x16x32_bf16 v[50:53], v[178:181], v[186:189], v[50:53]
	v_mfma_f32_16x16x32_bf16 v[38:41], v[170:173], v[194:197], v[38:41]
	v_mfma_f32_16x16x32_bf16 v[34:37], v[178:181], v[194:197], v[34:37]
	v_mfma_f32_16x16x32_bf16 v[22:25], v[170:173], v[202:205], v[22:25]
	v_mfma_f32_16x16x32_bf16 v[18:21], v[178:181], v[202:205], v[18:21]
	v_mfma_f32_16x16x32_bf16 v[6:9], v[170:173], v[210:213], v[6:9]
	v_mfma_f32_16x16x32_bf16 v[2:5], v[178:181], v[210:213], v[2:5]
	v_mfma_f32_16x16x32_bf16 v[54:57], v[174:177], v[190:193], v[54:57]
	v_mfma_f32_16x16x32_bf16 v[50:53], v[182:185], v[190:193], v[50:53]
	v_mfma_f32_16x16x32_bf16 v[38:41], v[174:177], v[198:201], v[38:41]
	v_mfma_f32_16x16x32_bf16 v[34:37], v[182:185], v[198:201], v[34:37]
	v_mfma_f32_16x16x32_bf16 v[22:25], v[174:177], v[206:209], v[22:25]
	v_mfma_f32_16x16x32_bf16 v[18:21], v[182:185], v[206:209], v[18:21]
	v_mfma_f32_16x16x32_bf16 v[6:9], v[174:177], v[214:217], v[6:9]
	v_mfma_f32_16x16x32_bf16 v[2:5], v[182:185], v[214:217], v[2:5]
	s_barrier
	s_add_i32 s54, s54, 2
	s_add_u32 s30, s30, 0x100
	s_addc_u32 s31, s31, 0
	s_cmp_gt_u32 s54, 13
	s_cbranch_scc0 .LBB0_1631
	s_add_u32 s30, s50, 0xffffff00
	s_addc_u32 s31, s51, -1
	s_andn2_b64 vcc, exec, s[6:7]
	s_cbranch_vccnz .LBB0_1634
	v_mov_b32_e32 v2, 0
	s_mov_b32 s10, s22
	s_mov_b32 s16, s24
	s_mov_b64 s[18:19], s[28:29]
	s_mov_b32 s41, s2
	v_mov_b32_e32 v3, v2
	v_mov_b32_e32 v4, v2
	v_mov_b32_e32 v5, v2
	v_mov_b32_e32 v6, v2
	v_mov_b32_e32 v7, v2
	v_mov_b32_e32 v8, v2
	v_mov_b32_e32 v9, v2
	v_mov_b32_e32 v18, v2
	v_mov_b32_e32 v19, v2
	v_mov_b32_e32 v20, v2
	v_mov_b32_e32 v21, v2
	v_mov_b32_e32 v22, v2
	v_mov_b32_e32 v23, v2
	v_mov_b32_e32 v24, v2
	v_mov_b32_e32 v25, v2
	v_mov_b32_e32 v34, v2
	v_mov_b32_e32 v35, v2
	v_mov_b32_e32 v36, v2
	v_mov_b32_e32 v37, v2
	v_mov_b32_e32 v38, v2
	v_mov_b32_e32 v39, v2
	v_mov_b32_e32 v40, v2
	v_mov_b32_e32 v41, v2
	v_mov_b32_e32 v50, v2
	v_mov_b32_e32 v51, v2
	v_mov_b32_e32 v52, v2
	v_mov_b32_e32 v53, v2
	v_mov_b32_e32 v54, v2
	v_mov_b32_e32 v55, v2
	v_mov_b32_e32 v56, v2
	v_mov_b32_e32 v57, v2
	v_mov_b32_e32 v10, v2
	v_mov_b32_e32 v11, v2
	v_mov_b32_e32 v12, v2
	v_mov_b32_e32 v13, v2
	v_mov_b32_e32 v14, v2
	v_mov_b32_e32 v15, v2
	v_mov_b32_e32 v16, v2
	v_mov_b32_e32 v17, v2
	v_mov_b32_e32 v26, v2
	v_mov_b32_e32 v27, v2
	v_mov_b32_e32 v28, v2
	v_mov_b32_e32 v29, v2
	v_mov_b32_e32 v30, v2
	v_mov_b32_e32 v31, v2
	v_mov_b32_e32 v32, v2
	v_mov_b32_e32 v33, v2
	v_mov_b32_e32 v42, v2
	v_mov_b32_e32 v43, v2
	v_mov_b32_e32 v44, v2
	v_mov_b32_e32 v45, v2
	v_mov_b32_e32 v46, v2
	v_mov_b32_e32 v47, v2
	v_mov_b32_e32 v48, v2
	v_mov_b32_e32 v49, v2
	v_mov_b32_e32 v58, v2
	v_mov_b32_e32 v59, v2
	v_mov_b32_e32 v60, v2
	v_mov_b32_e32 v61, v2
	v_mov_b32_e32 v62, v2
	v_mov_b32_e32 v63, v2
	v_mov_b32_e32 v64, v2
	v_mov_b32_e32 v65, v2
	v_mov_b32_e32 v66, v2
	v_mov_b32_e32 v67, v2
	v_mov_b32_e32 v68, v2
	v_mov_b32_e32 v69, v2
	v_mov_b32_e32 v70, v2
	v_mov_b32_e32 v71, v2
	v_mov_b32_e32 v72, v2
	v_mov_b32_e32 v73, v2
	v_mov_b32_e32 v82, v2
	v_mov_b32_e32 v83, v2
	v_mov_b32_e32 v84, v2
	v_mov_b32_e32 v85, v2
	v_mov_b32_e32 v86, v2
	v_mov_b32_e32 v87, v2
	v_mov_b32_e32 v88, v2
	v_mov_b32_e32 v89, v2
	v_mov_b32_e32 v98, v2
	v_mov_b32_e32 v99, v2
	v_mov_b32_e32 v100, v2
	v_mov_b32_e32 v101, v2
	v_mov_b32_e32 v102, v2
	v_mov_b32_e32 v103, v2
	v_mov_b32_e32 v104, v2
	v_mov_b32_e32 v105, v2
	v_mov_b32_e32 v114, v2
	v_mov_b32_e32 v115, v2
	v_mov_b32_e32 v116, v2
	v_mov_b32_e32 v117, v2
	v_mov_b32_e32 v118, v2
	v_mov_b32_e32 v119, v2
	v_mov_b32_e32 v120, v2
	v_mov_b32_e32 v121, v2
	v_mov_b32_e32 v74, v2
	v_mov_b32_e32 v75, v2
	v_mov_b32_e32 v76, v2
	v_mov_b32_e32 v77, v2
	v_mov_b32_e32 v78, v2
	v_mov_b32_e32 v79, v2
	v_mov_b32_e32 v80, v2
	v_mov_b32_e32 v81, v2
	v_mov_b32_e32 v90, v2
	v_mov_b32_e32 v91, v2
	v_mov_b32_e32 v92, v2
	v_mov_b32_e32 v93, v2
	v_mov_b32_e32 v94, v2
	v_mov_b32_e32 v95, v2
	v_mov_b32_e32 v96, v2
	v_mov_b32_e32 v97, v2
	v_mov_b32_e32 v106, v2
	v_mov_b32_e32 v107, v2
	v_mov_b32_e32 v108, v2
	v_mov_b32_e32 v109, v2
	v_mov_b32_e32 v110, v2
	v_mov_b32_e32 v111, v2
	v_mov_b32_e32 v112, v2
	v_mov_b32_e32 v113, v2
	v_mov_b32_e32 v122, v2
	v_mov_b32_e32 v123, v2
	v_mov_b32_e32 v124, v2
	v_mov_b32_e32 v125, v2
	v_mov_b32_e32 v126, v2
	v_mov_b32_e32 v127, v2
	v_mov_b32_e32 v128, v2
	v_mov_b32_e32 v129, v2
	s_andn2_b64 vcc, exec, s[4:5]
	s_cbranch_vccnz .LBB0_1635
	s_branch .LBB0_1636

.LBB0_1765:
	s_waitcnt lgkmcnt(0)
	s_barrier
	v_mfma_f32_16x16x32_bf16 v[66:69], v[150:153], v[190:193], v[66:69]
	v_mfma_f32_16x16x32_bf16 v[58:61], v[158:161], v[190:193], v[58:61]
	v_mfma_f32_16x16x32_bf16 v[50:53], v[150:153], v[182:185], v[50:53]
	v_mfma_f32_16x16x32_bf16 v[42:45], v[158:161], v[182:185], v[42:45]
	v_mfma_f32_16x16x32_bf16 v[34:37], v[150:153], v[174:177], v[34:37]
	v_mfma_f32_16x16x32_bf16 v[26:29], v[158:161], v[174:177], v[26:29]
	v_mfma_f32_16x16x32_bf16 v[18:21], v[150:153], v[166:169], v[18:21]
	v_mfma_f32_16x16x32_bf16 v[10:13], v[158:161], v[166:169], v[10:13]
	v_mfma_f32_16x16x32_bf16 v[66:69], v[154:157], v[194:197], v[66:69]
	v_mfma_f32_16x16x32_bf16 v[58:61], v[162:165], v[194:197], v[58:61]
	v_mfma_f32_16x16x32_bf16 v[50:53], v[154:157], v[186:189], v[50:53]
	v_mfma_f32_16x16x32_bf16 v[42:45], v[162:165], v[186:189], v[42:45]
	v_mfma_f32_16x16x32_bf16 v[34:37], v[154:157], v[178:181], v[34:37]
	v_mfma_f32_16x16x32_bf16 v[26:29], v[162:165], v[178:181], v[26:29]
	v_mfma_f32_16x16x32_bf16 v[18:21], v[154:157], v[170:173], v[18:21]
	v_mfma_f32_16x16x32_bf16 v[10:13], v[162:165], v[170:173], v[10:13]
	v_mfma_f32_16x16x32_bf16 v[62:65], v[134:137], v[190:193], v[62:65]
	v_mfma_f32_16x16x32_bf16 v[54:57], v[142:145], v[190:193], v[54:57]
	v_mfma_f32_16x16x32_bf16 v[46:49], v[134:137], v[182:185], v[46:49]
	v_mfma_f32_16x16x32_bf16 v[38:41], v[142:145], v[182:185], v[38:41]
	v_mfma_f32_16x16x32_bf16 v[30:33], v[134:137], v[174:177], v[30:33]
	v_mfma_f32_16x16x32_bf16 v[22:25], v[142:145], v[174:177], v[22:25]
	v_mfma_f32_16x16x32_bf16 v[14:17], v[134:137], v[166:169], v[14:17]
	v_mfma_f32_16x16x32_bf16 v[6:9], v[142:145], v[166:169], v[6:9]
	v_mfma_f32_16x16x32_bf16 v[62:65], v[138:141], v[194:197], v[62:65]
	v_mfma_f32_16x16x32_bf16 v[54:57], v[146:149], v[194:197], v[54:57]
	v_mfma_f32_16x16x32_bf16 v[46:49], v[138:141], v[186:189], v[46:49]
	v_mfma_f32_16x16x32_bf16 v[38:41], v[146:149], v[186:189], v[38:41]
	v_mfma_f32_16x16x32_bf16 v[30:33], v[138:141], v[178:181], v[30:33]
	v_mfma_f32_16x16x32_bf16 v[22:25], v[146:149], v[178:181], v[22:25]
	v_mfma_f32_16x16x32_bf16 v[14:17], v[138:141], v[170:173], v[14:17]
	v_mfma_f32_16x16x32_bf16 v[6:9], v[146:149], v[170:173], v[6:9]
	s_barrier
	s_add_i32 s61, s61, 2
	s_add_u32 s28, s28, 0x100
	s_addc_u32 s29, s29, 0
	s_add_u32 s59, s59, 0x100
	s_addc_u32 s60, s60, 0
	s_cmp_gt_u32 s61, 13
	s_cbranch_scc1 .LBB0_1771

.LBB0_1768:
	v_add_u32_e32 v146, s53, v217
	v_add_u32_e32 v162, s54, v217
	ds_read_b128 v[134:137], v146
	ds_read_b128 v[138:141], v146 offset:1024
	ds_read_b128 v[142:145], v146 offset:2048
	ds_read_b128 v[146:149], v146 offset:3072
	ds_read_b128 v[150:153], v162
	ds_read_b128 v[154:157], v162 offset:1024
	ds_read_b128 v[158:161], v162 offset:2048
	ds_read_b128 v[162:165], v162 offset:3072
	s_add_u32 s48, s28, 0xfffc0080
	s_addc_u32 s49, s29, -1
	s_and_b64 s[46:47], s[30:31], exec
	s_cselect_b32 s49, s23, s49
	s_cselect_b32 s48, s56, s48
	s_cselect_b32 s47, s57, s60
	s_cselect_b32 s46, s58, s59
	s_add_i32 m0, s40, 0xc000
	ds_read_b128 v[166:169], v220
	ds_read_b128 v[170:173], v220 offset:1024
	ds_read_b128 v[174:177], v220 offset:2048
	ds_read_b128 v[178:181], v220 offset:3072
	ds_read_b128 v[182:185], v220 offset:4096
	ds_read_b128 v[186:189], v220 offset:5120
	ds_read_b128 v[190:193], v220 offset:6144
	ds_read_b128 v[194:197], v220 offset:7168
	global_load_lds_dwordx4 v206, s[28:29]
	s_add_i32 m0, s40, 0xe000
	s_nop 0
	global_load_lds_dwordx4 v208, s[28:29]
	s_waitcnt vmcnt(8) lgkmcnt(0)
	s_barrier
	v_mfma_f32_16x16x32_bf16 v[130:133], v[134:137], v[166:169], v[130:133]
	v_mfma_f32_16x16x32_bf16 v[122:125], v[142:145], v[166:169], v[122:125]
	v_mfma_f32_16x16x32_bf16 v[114:117], v[134:137], v[174:177], v[114:117]
	v_mfma_f32_16x16x32_bf16 v[106:109], v[142:145], v[174:177], v[106:109]
	v_mfma_f32_16x16x32_bf16 v[98:101], v[134:137], v[182:185], v[98:101]
	v_mfma_f32_16x16x32_bf16 v[90:93], v[142:145], v[182:185], v[90:93]
	v_mfma_f32_16x16x32_bf16 v[82:85], v[134:137], v[190:193], v[82:85]
	v_mfma_f32_16x16x32_bf16 v[74:77], v[142:145], v[190:193], v[74:77]
	v_mfma_f32_16x16x32_bf16 v[130:133], v[138:141], v[170:173], v[130:133]
	v_mfma_f32_16x16x32_bf16 v[122:125], v[146:149], v[170:173], v[122:125]
	v_mfma_f32_16x16x32_bf16 v[114:117], v[138:141], v[178:181], v[114:117]
	v_mfma_f32_16x16x32_bf16 v[106:109], v[146:149], v[178:181], v[106:109]
	v_mfma_f32_16x16x32_bf16 v[98:101], v[138:141], v[186:189], v[98:101]
	v_mfma_f32_16x16x32_bf16 v[90:93], v[146:149], v[186:189], v[90:93]
	v_mfma_f32_16x16x32_bf16 v[82:85], v[138:141], v[194:197], v[82:85]
	v_mfma_f32_16x16x32_bf16 v[74:77], v[146:149], v[194:197], v[74:77]
	v_mfma_f32_16x16x32_bf16 v[126:129], v[150:153], v[166:169], v[126:129]
	v_mfma_f32_16x16x32_bf16 v[118:121], v[158:161], v[166:169], v[118:121]
	v_mfma_f32_16x16x32_bf16 v[110:113], v[150:153], v[174:177], v[110:113]
	v_mfma_f32_16x16x32_bf16 v[102:105], v[158:161], v[174:177], v[102:105]
	v_mfma_f32_16x16x32_bf16 v[94:97], v[150:153], v[182:185], v[94:97]
	v_mfma_f32_16x16x32_bf16 v[86:89], v[158:161], v[182:185], v[86:89]
	v_mfma_f32_16x16x32_bf16 v[78:81], v[150:153], v[190:193], v[78:81]
	v_mfma_f32_16x16x32_bf16 v[70:73], v[158:161], v[190:193], v[70:73]
	v_mfma_f32_16x16x32_bf16 v[126:129], v[154:157], v[170:173], v[126:129]
	v_mfma_f32_16x16x32_bf16 v[118:121], v[162:165], v[170:173], v[118:121]
	v_mfma_f32_16x16x32_bf16 v[110:113], v[154:157], v[178:181], v[110:113]
	v_mfma_f32_16x16x32_bf16 v[102:105], v[162:165], v[178:181], v[102:105]
	v_mfma_f32_16x16x32_bf16 v[94:97], v[154:157], v[186:189], v[94:97]
	v_mfma_f32_16x16x32_bf16 v[86:89], v[162:165], v[186:189], v[86:89]
	v_mfma_f32_16x16x32_bf16 v[78:81], v[154:157], v[194:197], v[78:81]
	v_mfma_f32_16x16x32_bf16 v[70:73], v[162:165], v[194:197], v[70:73]
	s_barrier
	s_add_i32 s62, s53, s12
	s_add_u32 s98, s46, s16
	s_addc_u32 s99, s47, s17
	s_mov_b32 m0, s62
	ds_read_b128 v[166:169], v220 offset:16384
	ds_read_b128 v[170:173], v220 offset:17408
	ds_read_b128 v[174:177], v220 offset:18432
	ds_read_b128 v[178:181], v220 offset:19456
	ds_read_b128 v[182:185], v220 offset:20480
	ds_read_b128 v[186:189], v220 offset:21504
	ds_read_b128 v[190:193], v220 offset:22528
	ds_read_b128 v[194:197], v220 offset:23552
	global_load_lds_dwordx4 v202, s[46:47]
	s_add_i32 m0, s62, 0x2000
	s_add_u32 s62, s46, 0x40000
	s_addc_u32 s63, s47, 0
	s_add_i32 s64, s54, s12
	global_load_lds_dwordx4 v198, s[46:47]
	s_mov_b32 m0, s64
	s_nop 0
	global_load_lds_dwordx4 v202, s[62:63]
	s_add_i32 m0, s64, 0x2000
	s_nop 0
	global_load_lds_dwordx4 v198, s[62:63]
	s_add_u32 s100, s48, s16
	s_addc_u32 s101, s49, s17
	s_mov_b32 m0, s40
	s_nop 0
	global_load_lds_dwordx4 v204, s[48:49]
	s_mov_b32 m0, s41
	s_nop 0
	global_load_lds_dwordx4 v200, s[48:49]
	s_waitcnt vmcnt(8) lgkmcnt(0)
	s_barrier
	v_mfma_f32_16x16x32_bf16 v[66:69], v[134:137], v[166:169], v[66:69]
	v_mfma_f32_16x16x32_bf16 v[58:61], v[142:145], v[166:169], v[58:61]
	v_mfma_f32_16x16x32_bf16 v[50:53], v[134:137], v[174:177], v[50:53]
	v_mfma_f32_16x16x32_bf16 v[42:45], v[142:145], v[174:177], v[42:45]
	v_mfma_f32_16x16x32_bf16 v[34:37], v[134:137], v[182:185], v[34:37]
	v_mfma_f32_16x16x32_bf16 v[26:29], v[142:145], v[182:185], v[26:29]
	v_mfma_f32_16x16x32_bf16 v[18:21], v[134:137], v[190:193], v[18:21]
	v_mfma_f32_16x16x32_bf16 v[10:13], v[142:145], v[190:193], v[10:13]
	v_mfma_f32_16x16x32_bf16 v[66:69], v[138:141], v[170:173], v[66:69]
	v_mfma_f32_16x16x32_bf16 v[58:61], v[146:149], v[170:173], v[58:61]
	v_mfma_f32_16x16x32_bf16 v[50:53], v[138:141], v[178:181], v[50:53]
	v_mfma_f32_16x16x32_bf16 v[42:45], v[146:149], v[178:181], v[42:45]
	v_mfma_f32_16x16x32_bf16 v[34:37], v[138:141], v[186:189], v[34:37]
	v_mfma_f32_16x16x32_bf16 v[26:29], v[146:149], v[186:189], v[26:29]
	v_mfma_f32_16x16x32_bf16 v[18:21], v[138:141], v[194:197], v[18:21]
	v_mfma_f32_16x16x32_bf16 v[10:13], v[146:149], v[194:197], v[10:13]
	v_mfma_f32_16x16x32_bf16 v[62:65], v[150:153], v[166:169], v[62:65]
	v_mfma_f32_16x16x32_bf16 v[54:57], v[158:161], v[166:169], v[54:57]
	v_mfma_f32_16x16x32_bf16 v[46:49], v[150:153], v[174:177], v[46:49]
	v_mfma_f32_16x16x32_bf16 v[38:41], v[158:161], v[174:177], v[38:41]
	v_mfma_f32_16x16x32_bf16 v[30:33], v[150:153], v[182:185], v[30:33]
	v_mfma_f32_16x16x32_bf16 v[22:25], v[158:161], v[182:185], v[22:25]
	v_mfma_f32_16x16x32_bf16 v[14:17], v[150:153], v[190:193], v[14:17]
	v_mfma_f32_16x16x32_bf16 v[6:9], v[158:161], v[190:193], v[6:9]
	v_mfma_f32_16x16x32_bf16 v[62:65], v[154:157], v[170:173], v[62:65]
	v_mfma_f32_16x16x32_bf16 v[54:57], v[162:165], v[170:173], v[54:57]
	v_mfma_f32_16x16x32_bf16 v[46:49], v[154:157], v[178:181], v[46:49]
	v_mfma_f32_16x16x32_bf16 v[38:41], v[162:165], v[178:181], v[38:41]
	v_mfma_f32_16x16x32_bf16 v[30:33], v[154:157], v[186:189], v[30:33]
	v_mfma_f32_16x16x32_bf16 v[22:25], v[162:165], v[186:189], v[22:25]
	v_mfma_f32_16x16x32_bf16 v[14:17], v[154:157], v[194:197], v[14:17]
	v_mfma_f32_16x16x32_bf16 v[6:9], v[162:165], v[194:197], v[6:9]
	s_barrier
	s_add_i32 s62, 0, 0x18000
	s_add_i32 s63, 0, 0x1c000
	v_add_u32_e32 v134, s62, v217
	v_add_u32_e32 v146, s63, v217
	ds_read_b128 v[150:153], v134
	ds_read_b128 v[154:157], v134 offset:1024
	ds_read_b128 v[158:161], v134 offset:2048
	ds_read_b128 v[162:165], v134 offset:3072
	ds_read_b128 v[134:137], v146
	ds_read_b128 v[138:141], v146 offset:1024
	ds_read_b128 v[142:145], v146 offset:2048
	ds_read_b128 v[146:149], v146 offset:3072
	s_add_u32 s48, s48, 0x40000
	s_addc_u32 s49, s49, 0
	s_mov_b32 m0, s42
	ds_read_b128 v[166:169], v220 offset:32768
	ds_read_b128 v[170:173], v220 offset:33792
	ds_read_b128 v[174:177], v220 offset:34816
	ds_read_b128 v[178:181], v220 offset:35840
	ds_read_b128 v[182:185], v220 offset:36864
	ds_read_b128 v[186:189], v220 offset:37888
	ds_read_b128 v[190:193], v220 offset:38912
	ds_read_b128 v[194:197], v220 offset:39936
	global_load_lds_dwordx4 v204, s[48:49]
	s_mov_b32 m0, s43
	s_nop 0
	global_load_lds_dwordx4 v200, s[48:49]
	s_waitcnt vmcnt(8) lgkmcnt(0)
	s_barrier
	v_mfma_f32_16x16x32_bf16 v[130:133], v[150:153], v[166:169], v[130:133]
	v_mfma_f32_16x16x32_bf16 v[122:125], v[158:161], v[166:169], v[122:125]
	v_mfma_f32_16x16x32_bf16 v[114:117], v[150:153], v[174:177], v[114:117]
	v_mfma_f32_16x16x32_bf16 v[106:109], v[158:161], v[174:177], v[106:109]
	v_mfma_f32_16x16x32_bf16 v[98:101], v[150:153], v[182:185], v[98:101]
	v_mfma_f32_16x16x32_bf16 v[90:93], v[158:161], v[182:185], v[90:93]
	v_mfma_f32_16x16x32_bf16 v[82:85], v[150:153], v[190:193], v[82:85]
	v_mfma_f32_16x16x32_bf16 v[74:77], v[158:161], v[190:193], v[74:77]
	v_mfma_f32_16x16x32_bf16 v[130:133], v[154:157], v[170:173], v[130:133]
	v_mfma_f32_16x16x32_bf16 v[122:125], v[162:165], v[170:173], v[122:125]
	v_mfma_f32_16x16x32_bf16 v[114:117], v[154:157], v[178:181], v[114:117]
	v_mfma_f32_16x16x32_bf16 v[106:109], v[162:165], v[178:181], v[106:109]
	v_mfma_f32_16x16x32_bf16 v[98:101], v[154:157], v[186:189], v[98:101]
	v_mfma_f32_16x16x32_bf16 v[90:93], v[162:165], v[186:189], v[90:93]
	v_mfma_f32_16x16x32_bf16 v[82:85], v[154:157], v[194:197], v[82:85]
	v_mfma_f32_16x16x32_bf16 v[74:77], v[162:165], v[194:197], v[74:77]
	v_mfma_f32_16x16x32_bf16 v[126:129], v[134:137], v[166:169], v[126:129]
	v_mfma_f32_16x16x32_bf16 v[118:121], v[142:145], v[166:169], v[118:121]
	v_mfma_f32_16x16x32_bf16 v[110:113], v[134:137], v[174:177], v[110:113]
	v_mfma_f32_16x16x32_bf16 v[102:105], v[142:145], v[174:177], v[102:105]
	v_mfma_f32_16x16x32_bf16 v[94:97], v[134:137], v[182:185], v[94:97]
	v_mfma_f32_16x16x32_bf16 v[86:89], v[142:145], v[182:185], v[86:89]
	v_mfma_f32_16x16x32_bf16 v[78:81], v[134:137], v[190:193], v[78:81]
	v_mfma_f32_16x16x32_bf16 v[70:73], v[142:145], v[190:193], v[70:73]
	v_mfma_f32_16x16x32_bf16 v[126:129], v[138:141], v[170:173], v[126:129]
	v_mfma_f32_16x16x32_bf16 v[118:121], v[146:149], v[170:173], v[118:121]
	v_mfma_f32_16x16x32_bf16 v[110:113], v[138:141], v[178:181], v[110:113]
	v_mfma_f32_16x16x32_bf16 v[102:105], v[146:149], v[178:181], v[102:105]
	v_mfma_f32_16x16x32_bf16 v[94:97], v[138:141], v[186:189], v[94:97]
	v_mfma_f32_16x16x32_bf16 v[86:89], v[146:149], v[186:189], v[86:89]
	v_mfma_f32_16x16x32_bf16 v[78:81], v[138:141], v[194:197], v[78:81]
	v_mfma_f32_16x16x32_bf16 v[70:73], v[146:149], v[194:197], v[70:73]
	s_barrier
	s_add_i32 s48, s62, s12
	s_mov_b32 m0, s48
	ds_read_b128 v[190:193], v220 offset:49152
	ds_read_b128 v[194:197], v220 offset:50176
	ds_read_b128 v[182:185], v220 offset:51200
	ds_read_b128 v[186:189], v220 offset:52224
	ds_read_b128 v[174:177], v220 offset:53248
	ds_read_b128 v[178:181], v220 offset:54272
	ds_read_b128 v[166:169], v220 offset:55296
	ds_read_b128 v[170:173], v220 offset:56320
	global_load_lds_dwordx4 v202, s[98:99]
	s_add_i32 m0, s48, 0x2000
	s_add_u32 s46, s46, 0x40080
	s_addc_u32 s47, s47, 0
	s_add_i32 s48, s63, s12
	global_load_lds_dwordx4 v198, s[98:99]
	s_mov_b32 m0, s48
	s_andn2_b64 vcc, exec, s[30:31]
	global_load_lds_dwordx4 v202, s[46:47]
	s_add_i32 m0, s48, 0x2000
	s_nop 0
	global_load_lds_dwordx4 v198, s[46:47]
	s_mov_b32 m0, s51
	s_nop 0
	global_load_lds_dwordx4 v204, s[100:101]
	s_mov_b32 m0, s52
	s_nop 0
	global_load_lds_dwordx4 v200, s[100:101]
	s_waitcnt vmcnt(8)
	s_cbranch_vccnz .LBB0_1765
	s_and_saveexec_b64 s[30:31], s[4:5]
	s_cbranch_execz .LBB0_1764
	v_mov_b32_e32 v222, v3
	v_mov_b32_e32 v223, v4
	v_mov_b32_e32 v224, v2
	v_mov_b32_e32 v225, v5
	v_pk_add_f32 v[222:223], v[222:223], v[224:225]
	s_nop 0
	v_add_f32_e32 v222, v222, v223
	v_fmamk_f32 v222, v222, 0x3a800000, v221
	ds_write_b32 v219, v222
	s_branch .LBB0_1764

.LBB0_1894:
	v_add_u32_e32 v153, s44, v151
	ds_read_b128 v[154:157], v153
	ds_read_b128 v[158:161], v153 offset:1024
	ds_read_b128 v[162:165], v153 offset:2048
	ds_read_b128 v[166:169], v153 offset:3072
	v_add_u32_e32 v153, s45, v151
	s_add_u32 s26, s18, s24
	ds_read_b128 v[170:173], v153
	ds_read_b128 v[174:177], v153 offset:1024
	ds_read_b128 v[178:181], v153 offset:2048
	ds_read_b128 v[182:185], v153 offset:3072
	s_addc_u32 s27, s19, s25
	s_add_u32 s26, s26, 0x100
	s_addc_u32 s27, s27, 0
	s_add_u32 s51, s48, s24
	s_addc_u32 s52, s49, s25
	s_cmpk_eq_i32 s24, 0x1500
	s_cselect_b32 s29, s23, s27
	s_cselect_b32 s28, s22, s26
	s_cselect_b32 s27, s9, s52
	s_cselect_b32 s26, s8, s51
	v_lshl_add_u64 v[218:219], v[146:147], 0, s[24:25]
	s_add_i32 m0, s33, 0xc000
	ds_read_b128 v[186:189], v152
	ds_read_b128 v[190:193], v152 offset:1024
	ds_read_b128 v[194:197], v152 offset:2048
	ds_read_b128 v[198:201], v152 offset:3072
	ds_read_b128 v[202:205], v152 offset:4096
	ds_read_b128 v[206:209], v152 offset:5120
	ds_read_b128 v[210:213], v152 offset:6144
	ds_read_b128 v[214:217], v152 offset:7168
	global_load_lds_dwordx4 v[218:219], off
	v_lshl_add_u64 v[218:219], v[148:149], 0, s[24:25]
	s_add_i32 m0, s33, 0xe000
	s_nop 0
	global_load_lds_dwordx4 v[218:219], off
	s_waitcnt vmcnt(8) lgkmcnt(0)
	s_barrier
	v_mfma_f32_16x16x32_bf16 v[126:129], v[154:157], v[186:189], v[126:129]
	v_mfma_f32_16x16x32_bf16 v[122:125], v[162:165], v[186:189], v[122:125]
	v_mfma_f32_16x16x32_bf16 v[110:113], v[154:157], v[194:197], v[110:113]
	v_mfma_f32_16x16x32_bf16 v[106:109], v[162:165], v[194:197], v[106:109]
	v_mfma_f32_16x16x32_bf16 v[94:97], v[154:157], v[202:205], v[94:97]
	v_mfma_f32_16x16x32_bf16 v[90:93], v[162:165], v[202:205], v[90:93]
	v_mfma_f32_16x16x32_bf16 v[78:81], v[154:157], v[210:213], v[78:81]
	v_mfma_f32_16x16x32_bf16 v[74:77], v[162:165], v[210:213], v[74:77]
	v_mfma_f32_16x16x32_bf16 v[126:129], v[158:161], v[190:193], v[126:129]
	v_mfma_f32_16x16x32_bf16 v[122:125], v[166:169], v[190:193], v[122:125]
	v_mfma_f32_16x16x32_bf16 v[110:113], v[158:161], v[198:201], v[110:113]
	v_mfma_f32_16x16x32_bf16 v[106:109], v[166:169], v[198:201], v[106:109]
	v_mfma_f32_16x16x32_bf16 v[94:97], v[158:161], v[206:209], v[94:97]
	v_mfma_f32_16x16x32_bf16 v[90:93], v[166:169], v[206:209], v[90:93]
	v_mfma_f32_16x16x32_bf16 v[78:81], v[158:161], v[214:217], v[78:81]
	v_mfma_f32_16x16x32_bf16 v[74:77], v[166:169], v[214:217], v[74:77]
	v_mfma_f32_16x16x32_bf16 v[118:121], v[170:173], v[186:189], v[118:121]
	v_mfma_f32_16x16x32_bf16 v[114:117], v[178:181], v[186:189], v[114:117]
	v_mfma_f32_16x16x32_bf16 v[102:105], v[170:173], v[194:197], v[102:105]
	v_mfma_f32_16x16x32_bf16 v[98:101], v[178:181], v[194:197], v[98:101]
	v_mfma_f32_16x16x32_bf16 v[86:89], v[170:173], v[202:205], v[86:89]
	v_mfma_f32_16x16x32_bf16 v[82:85], v[178:181], v[202:205], v[82:85]
	v_mfma_f32_16x16x32_bf16 v[70:73], v[170:173], v[210:213], v[70:73]
	v_mfma_f32_16x16x32_bf16 v[66:69], v[178:181], v[210:213], v[66:69]
	v_mfma_f32_16x16x32_bf16 v[118:121], v[174:177], v[190:193], v[118:121]
	v_mfma_f32_16x16x32_bf16 v[114:117], v[182:185], v[190:193], v[114:117]
	v_mfma_f32_16x16x32_bf16 v[102:105], v[174:177], v[198:201], v[102:105]
	v_mfma_f32_16x16x32_bf16 v[98:101], v[182:185], v[198:201], v[98:101]
	v_mfma_f32_16x16x32_bf16 v[86:89], v[174:177], v[206:209], v[86:89]
	v_mfma_f32_16x16x32_bf16 v[82:85], v[182:185], v[206:209], v[82:85]
	v_mfma_f32_16x16x32_bf16 v[70:73], v[174:177], v[214:217], v[70:73]
	v_mfma_f32_16x16x32_bf16 v[66:69], v[182:185], v[214:217], v[66:69]
	s_barrier
	s_add_i32 s51, s44, s13
	s_add_u32 s98, s26, s20
	s_addc_u32 s99, s27, s21
	s_mov_b32 m0, s51
	ds_read_b128 v[186:189], v152 offset:16384
	ds_read_b128 v[190:193], v152 offset:17408
	ds_read_b128 v[194:197], v152 offset:18432
	ds_read_b128 v[198:201], v152 offset:19456
	ds_read_b128 v[202:205], v152 offset:20480
	ds_read_b128 v[206:209], v152 offset:21504
	ds_read_b128 v[210:213], v152 offset:22528
	ds_read_b128 v[214:217], v152 offset:23552
	global_load_lds_dwordx4 v132, s[26:27]
	s_add_i32 m0, s51, 0x2000
	s_add_u32 s52, s26, 0xb0000
	s_addc_u32 s53, s27, 0
	s_add_i32 s51, s45, s13
	global_load_lds_dwordx4 v136, s[26:27]
	s_mov_b32 m0, s51
	s_nop 0
	global_load_lds_dwordx4 v132, s[52:53]
	s_add_i32 m0, s51, 0x2000
	s_nop 0
	global_load_lds_dwordx4 v136, s[52:53]
	s_add_u32 s100, s28, s20
	s_addc_u32 s101, s29, s21
	s_mov_b32 m0, s33
	s_nop 0
	global_load_lds_dwordx4 v130, s[28:29]
	s_mov_b32 m0, s14
	s_nop 0
	global_load_lds_dwordx4 v134, s[28:29]
	s_waitcnt vmcnt(8) lgkmcnt(0)
	s_barrier
	v_mfma_f32_16x16x32_bf16 v[62:65], v[154:157], v[186:189], v[62:65]
	v_mfma_f32_16x16x32_bf16 v[58:61], v[162:165], v[186:189], v[58:61]
	v_mfma_f32_16x16x32_bf16 v[46:49], v[154:157], v[194:197], v[46:49]
	v_mfma_f32_16x16x32_bf16 v[42:45], v[162:165], v[194:197], v[42:45]
	v_mfma_f32_16x16x32_bf16 v[30:33], v[154:157], v[202:205], v[30:33]
	v_mfma_f32_16x16x32_bf16 v[26:29], v[162:165], v[202:205], v[26:29]
	v_mfma_f32_16x16x32_bf16 v[14:17], v[154:157], v[210:213], v[14:17]
	v_mfma_f32_16x16x32_bf16 v[10:13], v[162:165], v[210:213], v[10:13]
	v_mfma_f32_16x16x32_bf16 v[62:65], v[158:161], v[190:193], v[62:65]
	v_mfma_f32_16x16x32_bf16 v[58:61], v[166:169], v[190:193], v[58:61]
	v_mfma_f32_16x16x32_bf16 v[46:49], v[158:161], v[198:201], v[46:49]
	v_mfma_f32_16x16x32_bf16 v[42:45], v[166:169], v[198:201], v[42:45]
	v_mfma_f32_16x16x32_bf16 v[30:33], v[158:161], v[206:209], v[30:33]
	v_mfma_f32_16x16x32_bf16 v[26:29], v[166:169], v[206:209], v[26:29]
	v_mfma_f32_16x16x32_bf16 v[14:17], v[158:161], v[214:217], v[14:17]
	v_mfma_f32_16x16x32_bf16 v[10:13], v[166:169], v[214:217], v[10:13]
	v_mfma_f32_16x16x32_bf16 v[54:57], v[170:173], v[186:189], v[54:57]
	v_mfma_f32_16x16x32_bf16 v[50:53], v[178:181], v[186:189], v[50:53]
	v_mfma_f32_16x16x32_bf16 v[38:41], v[170:173], v[194:197], v[38:41]
	v_mfma_f32_16x16x32_bf16 v[34:37], v[178:181], v[194:197], v[34:37]
	v_mfma_f32_16x16x32_bf16 v[22:25], v[170:173], v[202:205], v[22:25]
	v_mfma_f32_16x16x32_bf16 v[18:21], v[178:181], v[202:205], v[18:21]
	v_mfma_f32_16x16x32_bf16 v[6:9], v[170:173], v[210:213], v[6:9]
	v_mfma_f32_16x16x32_bf16 v[2:5], v[178:181], v[210:213], v[2:5]
	v_mfma_f32_16x16x32_bf16 v[54:57], v[174:177], v[190:193], v[54:57]
	v_mfma_f32_16x16x32_bf16 v[50:53], v[182:185], v[190:193], v[50:53]
	v_mfma_f32_16x16x32_bf16 v[38:41], v[174:177], v[198:201], v[38:41]
	v_mfma_f32_16x16x32_bf16 v[34:37], v[182:185], v[198:201], v[34:37]
	v_mfma_f32_16x16x32_bf16 v[22:25], v[174:177], v[206:209], v[22:25]
	v_mfma_f32_16x16x32_bf16 v[18:21], v[182:185], v[206:209], v[18:21]
	v_mfma_f32_16x16x32_bf16 v[6:9], v[174:177], v[214:217], v[6:9]
	v_mfma_f32_16x16x32_bf16 v[2:5], v[182:185], v[214:217], v[2:5]
	s_barrier
	s_add_i32 s51, 0, 0x18000
	v_add_u32_e32 v153, s51, v151
	s_add_i32 s52, 0, 0x1c000
	ds_read_b128 v[154:157], v153
	ds_read_b128 v[158:161], v153 offset:1024
	ds_read_b128 v[162:165], v153 offset:2048
	ds_read_b128 v[166:169], v153 offset:3072
	v_add_u32_e32 v153, s52, v151
	ds_read_b128 v[170:173], v153
	ds_read_b128 v[174:177], v153 offset:1024
	ds_read_b128 v[178:181], v153 offset:2048
	ds_read_b128 v[182:185], v153 offset:3072
	s_add_u32 s28, s28, 0xb0000
	s_addc_u32 s29, s29, 0
	s_mov_b32 m0, s15
	ds_read_b128 v[186:189], v152 offset:32768
	ds_read_b128 v[190:193], v152 offset:33792
	ds_read_b128 v[194:197], v152 offset:34816
	ds_read_b128 v[198:201], v152 offset:35840
	ds_read_b128 v[202:205], v152 offset:36864
	ds_read_b128 v[206:209], v152 offset:37888
	ds_read_b128 v[210:213], v152 offset:38912
	ds_read_b128 v[214:217], v152 offset:39936
	global_load_lds_dwordx4 v130, s[28:29]
	s_mov_b32 m0, s40
	s_nop 0
	global_load_lds_dwordx4 v134, s[28:29]
	s_waitcnt vmcnt(8) lgkmcnt(0)
	s_barrier
	v_mfma_f32_16x16x32_bf16 v[126:129], v[154:157], v[186:189], v[126:129]
	v_mfma_f32_16x16x32_bf16 v[122:125], v[162:165], v[186:189], v[122:125]
	v_mfma_f32_16x16x32_bf16 v[110:113], v[154:157], v[194:197], v[110:113]
	v_mfma_f32_16x16x32_bf16 v[106:109], v[162:165], v[194:197], v[106:109]
	v_mfma_f32_16x16x32_bf16 v[94:97], v[154:157], v[202:205], v[94:97]
	v_mfma_f32_16x16x32_bf16 v[90:93], v[162:165], v[202:205], v[90:93]
	v_mfma_f32_16x16x32_bf16 v[78:81], v[154:157], v[210:213], v[78:81]
	v_mfma_f32_16x16x32_bf16 v[74:77], v[162:165], v[210:213], v[74:77]
	v_mfma_f32_16x16x32_bf16 v[126:129], v[158:161], v[190:193], v[126:129]
	v_mfma_f32_16x16x32_bf16 v[122:125], v[166:169], v[190:193], v[122:125]
	v_mfma_f32_16x16x32_bf16 v[110:113], v[158:161], v[198:201], v[110:113]
	v_mfma_f32_16x16x32_bf16 v[106:109], v[166:169], v[198:201], v[106:109]
	v_mfma_f32_16x16x32_bf16 v[94:97], v[158:161], v[206:209], v[94:97]
	v_mfma_f32_16x16x32_bf16 v[90:93], v[166:169], v[206:209], v[90:93]
	v_mfma_f32_16x16x32_bf16 v[78:81], v[158:161], v[214:217], v[78:81]
	v_mfma_f32_16x16x32_bf16 v[74:77], v[166:169], v[214:217], v[74:77]
	v_mfma_f32_16x16x32_bf16 v[118:121], v[170:173], v[186:189], v[118:121]
	v_mfma_f32_16x16x32_bf16 v[114:117], v[178:181], v[186:189], v[114:117]
	v_mfma_f32_16x16x32_bf16 v[102:105], v[170:173], v[194:197], v[102:105]
	v_mfma_f32_16x16x32_bf16 v[98:101], v[178:181], v[194:197], v[98:101]
	v_mfma_f32_16x16x32_bf16 v[86:89], v[170:173], v[202:205], v[86:89]
	v_mfma_f32_16x16x32_bf16 v[82:85], v[178:181], v[202:205], v[82:85]
	v_mfma_f32_16x16x32_bf16 v[70:73], v[170:173], v[210:213], v[70:73]
	v_mfma_f32_16x16x32_bf16 v[66:69], v[178:181], v[210:213], v[66:69]
	v_mfma_f32_16x16x32_bf16 v[118:121], v[174:177], v[190:193], v[118:121]
	v_mfma_f32_16x16x32_bf16 v[114:117], v[182:185], v[190:193], v[114:117]
	v_mfma_f32_16x16x32_bf16 v[102:105], v[174:177], v[198:201], v[102:105]
	v_mfma_f32_16x16x32_bf16 v[98:101], v[182:185], v[198:201], v[98:101]
	v_mfma_f32_16x16x32_bf16 v[86:89], v[174:177], v[206:209], v[86:89]
	v_mfma_f32_16x16x32_bf16 v[82:85], v[182:185], v[206:209], v[82:85]
	v_mfma_f32_16x16x32_bf16 v[70:73], v[174:177], v[214:217], v[70:73]
	v_mfma_f32_16x16x32_bf16 v[66:69], v[182:185], v[214:217], v[66:69]
	s_barrier
	s_add_i32 s28, s51, s13
	s_mov_b32 m0, s28
	ds_read_b128 v[186:189], v152 offset:49152
	ds_read_b128 v[190:193], v152 offset:50176
	ds_read_b128 v[194:197], v152 offset:51200
	ds_read_b128 v[198:201], v152 offset:52224
	ds_read_b128 v[202:205], v152 offset:53248
	ds_read_b128 v[206:209], v152 offset:54272
	ds_read_b128 v[210:213], v152 offset:55296
	ds_read_b128 v[214:217], v152 offset:56320
	global_load_lds_dwordx4 v132, s[98:99]
	s_add_i32 m0, s28, 0x2000
	s_add_u32 s26, s26, 0xb0080
	s_addc_u32 s27, s27, 0
	s_add_i32 s28, s52, s13
	global_load_lds_dwordx4 v136, s[98:99]
	s_mov_b32 m0, s28
	s_nop 0
	global_load_lds_dwordx4 v132, s[26:27]
	s_add_i32 m0, s28, 0x2000
	s_nop 0
	global_load_lds_dwordx4 v136, s[26:27]
	s_mov_b32 m0, s42
	s_nop 0
	global_load_lds_dwordx4 v130, s[100:101]
	s_mov_b32 m0, s43
	s_nop 0
	global_load_lds_dwordx4 v134, s[100:101]
	s_waitcnt vmcnt(8) lgkmcnt(0)
	s_barrier
	v_mfma_f32_16x16x32_bf16 v[62:65], v[154:157], v[186:189], v[62:65]
	v_mfma_f32_16x16x32_bf16 v[58:61], v[162:165], v[186:189], v[58:61]
	v_mfma_f32_16x16x32_bf16 v[46:49], v[154:157], v[194:197], v[46:49]
	v_mfma_f32_16x16x32_bf16 v[42:45], v[162:165], v[194:197], v[42:45]
	v_mfma_f32_16x16x32_bf16 v[30:33], v[154:157], v[202:205], v[30:33]
	v_mfma_f32_16x16x32_bf16 v[26:29], v[162:165], v[202:205], v[26:29]
	v_mfma_f32_16x16x32_bf16 v[14:17], v[154:157], v[210:213], v[14:17]
	v_mfma_f32_16x16x32_bf16 v[10:13], v[162:165], v[210:213], v[10:13]
	v_mfma_f32_16x16x32_bf16 v[62:65], v[158:161], v[190:193], v[62:65]
	v_mfma_f32_16x16x32_bf16 v[58:61], v[166:169], v[190:193], v[58:61]
	v_mfma_f32_16x16x32_bf16 v[46:49], v[158:161], v[198:201], v[46:49]
	v_mfma_f32_16x16x32_bf16 v[42:45], v[166:169], v[198:201], v[42:45]
	v_mfma_f32_16x16x32_bf16 v[30:33], v[158:161], v[206:209], v[30:33]
	v_mfma_f32_16x16x32_bf16 v[26:29], v[166:169], v[206:209], v[26:29]
	v_mfma_f32_16x16x32_bf16 v[14:17], v[158:161], v[214:217], v[14:17]
	v_mfma_f32_16x16x32_bf16 v[10:13], v[166:169], v[214:217], v[10:13]
	v_mfma_f32_16x16x32_bf16 v[54:57], v[170:173], v[186:189], v[54:57]
	v_mfma_f32_16x16x32_bf16 v[50:53], v[178:181], v[186:189], v[50:53]
	v_mfma_f32_16x16x32_bf16 v[38:41], v[170:173], v[194:197], v[38:41]
	v_mfma_f32_16x16x32_bf16 v[34:37], v[178:181], v[194:197], v[34:37]
	v_mfma_f32_16x16x32_bf16 v[22:25], v[170:173], v[202:205], v[22:25]
	v_mfma_f32_16x16x32_bf16 v[18:21], v[178:181], v[202:205], v[18:21]
	v_mfma_f32_16x16x32_bf16 v[6:9], v[170:173], v[210:213], v[6:9]
	v_mfma_f32_16x16x32_bf16 v[2:5], v[178:181], v[210:213], v[2:5]
	v_mfma_f32_16x16x32_bf16 v[54:57], v[174:177], v[190:193], v[54:57]
	v_mfma_f32_16x16x32_bf16 v[50:53], v[182:185], v[190:193], v[50:53]
	v_mfma_f32_16x16x32_bf16 v[38:41], v[174:177], v[198:201], v[38:41]
	v_mfma_f32_16x16x32_bf16 v[34:37], v[182:185], v[198:201], v[34:37]
	v_mfma_f32_16x16x32_bf16 v[22:25], v[174:177], v[206:209], v[22:25]
	v_mfma_f32_16x16x32_bf16 v[18:21], v[182:185], v[206:209], v[18:21]
	v_mfma_f32_16x16x32_bf16 v[6:9], v[174:177], v[214:217], v[6:9]
	v_mfma_f32_16x16x32_bf16 v[2:5], v[182:185], v[214:217], v[2:5]
	s_barrier
	s_add_i32 s50, s50, 2
	s_add_u32 s24, s24, 0x100
	s_addc_u32 s25, s25, 0
	s_cmp_gt_u32 s50, 41
	s_cbranch_scc0 .LBB0_1894
	s_add_u32 s24, s48, 0xffffff00
	s_addc_u32 s25, s49, -1
	s_and_b64 vcc, exec, s[6:7]
	s_cbranch_vccnz .LBB0_1897
	v_mov_b32_e32 v2, 0
	s_mov_b32 s16, s46
	s_mov_b32 s31, s47
	s_mov_b64 s[18:19], s[22:23]
	s_mov_b32 s41, s2
	v_mov_b32_e32 v3, v2
	v_mov_b32_e32 v4, v2
	v_mov_b32_e32 v5, v2
	v_mov_b32_e32 v6, v2
	v_mov_b32_e32 v7, v2
	v_mov_b32_e32 v8, v2
	v_mov_b32_e32 v9, v2
	v_mov_b32_e32 v18, v2
	v_mov_b32_e32 v19, v2
	v_mov_b32_e32 v20, v2
	v_mov_b32_e32 v21, v2
	v_mov_b32_e32 v22, v2
	v_mov_b32_e32 v23, v2
	v_mov_b32_e32 v24, v2
	v_mov_b32_e32 v25, v2
	v_mov_b32_e32 v34, v2
	v_mov_b32_e32 v35, v2
	v_mov_b32_e32 v36, v2
	v_mov_b32_e32 v37, v2
	v_mov_b32_e32 v38, v2
	v_mov_b32_e32 v39, v2
	v_mov_b32_e32 v40, v2
	v_mov_b32_e32 v41, v2
	v_mov_b32_e32 v50, v2
	v_mov_b32_e32 v51, v2
	v_mov_b32_e32 v52, v2
	v_mov_b32_e32 v53, v2
	v_mov_b32_e32 v54, v2
	v_mov_b32_e32 v55, v2
	v_mov_b32_e32 v56, v2
	v_mov_b32_e32 v57, v2
	v_mov_b32_e32 v10, v2
	v_mov_b32_e32 v11, v2
	v_mov_b32_e32 v12, v2
	v_mov_b32_e32 v13, v2
	v_mov_b32_e32 v14, v2
	v_mov_b32_e32 v15, v2
	v_mov_b32_e32 v16, v2
	v_mov_b32_e32 v17, v2
	v_mov_b32_e32 v26, v2
	v_mov_b32_e32 v27, v2
	v_mov_b32_e32 v28, v2
	v_mov_b32_e32 v29, v2
	v_mov_b32_e32 v30, v2
	v_mov_b32_e32 v31, v2
	v_mov_b32_e32 v32, v2
	v_mov_b32_e32 v33, v2
	v_mov_b32_e32 v42, v2
	v_mov_b32_e32 v43, v2
	v_mov_b32_e32 v44, v2
	v_mov_b32_e32 v45, v2
	v_mov_b32_e32 v46, v2
	v_mov_b32_e32 v47, v2
	v_mov_b32_e32 v48, v2
	v_mov_b32_e32 v49, v2
	v_mov_b32_e32 v58, v2
	v_mov_b32_e32 v59, v2
	v_mov_b32_e32 v60, v2
	v_mov_b32_e32 v61, v2
	v_mov_b32_e32 v62, v2
	v_mov_b32_e32 v63, v2
	v_mov_b32_e32 v64, v2
	v_mov_b32_e32 v65, v2
	v_mov_b32_e32 v66, v2
	v_mov_b32_e32 v67, v2
	v_mov_b32_e32 v68, v2
	v_mov_b32_e32 v69, v2
	v_mov_b32_e32 v70, v2
	v_mov_b32_e32 v71, v2
	v_mov_b32_e32 v72, v2
	v_mov_b32_e32 v73, v2
	v_mov_b32_e32 v82, v2
	v_mov_b32_e32 v83, v2
	v_mov_b32_e32 v84, v2
	v_mov_b32_e32 v85, v2
	v_mov_b32_e32 v86, v2
	v_mov_b32_e32 v87, v2
	v_mov_b32_e32 v88, v2
	v_mov_b32_e32 v89, v2
	v_mov_b32_e32 v98, v2
	v_mov_b32_e32 v99, v2
	v_mov_b32_e32 v100, v2
	v_mov_b32_e32 v101, v2
	v_mov_b32_e32 v102, v2
	v_mov_b32_e32 v103, v2
	v_mov_b32_e32 v104, v2
	v_mov_b32_e32 v105, v2
	v_mov_b32_e32 v114, v2
	v_mov_b32_e32 v115, v2
	v_mov_b32_e32 v116, v2
	v_mov_b32_e32 v117, v2
	v_mov_b32_e32 v118, v2
	v_mov_b32_e32 v119, v2
	v_mov_b32_e32 v120, v2
	v_mov_b32_e32 v121, v2
	v_mov_b32_e32 v74, v2
	v_mov_b32_e32 v75, v2
	v_mov_b32_e32 v76, v2
	v_mov_b32_e32 v77, v2
	v_mov_b32_e32 v78, v2
	v_mov_b32_e32 v79, v2
	v_mov_b32_e32 v80, v2
	v_mov_b32_e32 v81, v2
	v_mov_b32_e32 v90, v2
	v_mov_b32_e32 v91, v2
	v_mov_b32_e32 v92, v2
	v_mov_b32_e32 v93, v2
	v_mov_b32_e32 v94, v2
	v_mov_b32_e32 v95, v2
	v_mov_b32_e32 v96, v2
	v_mov_b32_e32 v97, v2
	v_mov_b32_e32 v106, v2
	v_mov_b32_e32 v107, v2
	v_mov_b32_e32 v108, v2
	v_mov_b32_e32 v109, v2
	v_mov_b32_e32 v110, v2
	v_mov_b32_e32 v111, v2
	v_mov_b32_e32 v112, v2
	v_mov_b32_e32 v113, v2
	v_mov_b32_e32 v122, v2
	v_mov_b32_e32 v123, v2
	v_mov_b32_e32 v124, v2
	v_mov_b32_e32 v125, v2
	v_mov_b32_e32 v126, v2
	v_mov_b32_e32 v127, v2
	v_mov_b32_e32 v128, v2
	v_mov_b32_e32 v129, v2
	s_andn2_b64 vcc, exec, s[4:5]
	s_cbranch_vccnz .LBB0_1898
	s_branch .LBB0_1899

.LBB0_2031:
	ds_read_b128 v[36:39], v203
	ds_read_b128 v[44:47], v203 offset:1024
	ds_read_b128 v[48:51], v203 offset:2048
	ds_read_b128 v[56:59], v203 offset:3072
	ds_read_b128 v[144:147], v207
	ds_read_b128 v[148:151], v207 offset:1024
	ds_read_b128 v[152:155], v207 offset:2048
	ds_read_b128 v[156:159], v207 offset:3072
	s_add_u32 s34, s30, 0xfffc0080
	s_addc_u32 s35, s31, -1
	s_cmp_eq_u32 s63, 12
	s_cselect_b32 s39, s14, s35
	s_cselect_b32 s38, s15, s34
	s_cselect_b32 s35, s21, s62
	s_cselect_b32 s34, s23, s61
	s_add_i32 m0, s29, 0xc000
	ds_read_b128 v[172:175], v209
	ds_read_b128 v[176:179], v209 offset:1024
	ds_read_b128 v[180:183], v209 offset:2048
	ds_read_b128 v[184:187], v209 offset:3072
	ds_read_b128 v[188:191], v209 offset:4096
	ds_read_b128 v[192:195], v209 offset:5120
	ds_read_b128 v[196:199], v209 offset:6144
	ds_read_b128 v[214:217], v209 offset:7168
	global_load_lds_dwordx4 v168, s[30:31]
	s_add_i32 m0, s29, 0xe000
	s_nop 0
	global_load_lds_dwordx4 v170, s[30:31]
	s_waitcnt vmcnt(8) lgkmcnt(0)
	s_barrier
	v_mfma_f32_16x16x32_bf16 v[140:143], v[36:39], v[172:175], v[140:143]
	v_mfma_f32_16x16x32_bf16 v[136:139], v[48:51], v[172:175], v[136:139]
	v_mfma_f32_16x16x32_bf16 v[124:127], v[36:39], v[180:183], v[124:127]
	v_mfma_f32_16x16x32_bf16 v[120:123], v[48:51], v[180:183], v[120:123]
	v_mfma_f32_16x16x32_bf16 v[108:111], v[36:39], v[188:191], v[108:111]
	v_mfma_f32_16x16x32_bf16 v[104:107], v[48:51], v[188:191], v[104:107]
	v_mfma_f32_16x16x32_bf16 v[92:95], v[36:39], v[196:199], v[92:95]
	v_mfma_f32_16x16x32_bf16 v[88:91], v[48:51], v[196:199], v[88:91]
	v_mfma_f32_16x16x32_bf16 v[140:143], v[44:47], v[176:179], v[140:143]
	v_mfma_f32_16x16x32_bf16 v[136:139], v[56:59], v[176:179], v[136:139]
	v_mfma_f32_16x16x32_bf16 v[124:127], v[44:47], v[184:187], v[124:127]
	v_mfma_f32_16x16x32_bf16 v[120:123], v[56:59], v[184:187], v[120:123]
	v_mfma_f32_16x16x32_bf16 v[108:111], v[44:47], v[192:195], v[108:111]
	v_mfma_f32_16x16x32_bf16 v[104:107], v[56:59], v[192:195], v[104:107]
	v_mfma_f32_16x16x32_bf16 v[92:95], v[44:47], v[214:217], v[92:95]
	v_mfma_f32_16x16x32_bf16 v[88:91], v[56:59], v[214:217], v[88:91]
	v_mfma_f32_16x16x32_bf16 v[132:135], v[144:147], v[172:175], v[132:135]
	v_mfma_f32_16x16x32_bf16 v[128:131], v[152:155], v[172:175], v[128:131]
	v_mfma_f32_16x16x32_bf16 v[116:119], v[144:147], v[180:183], v[116:119]
	v_mfma_f32_16x16x32_bf16 v[112:115], v[152:155], v[180:183], v[112:115]
	v_mfma_f32_16x16x32_bf16 v[100:103], v[144:147], v[188:191], v[100:103]
	v_mfma_f32_16x16x32_bf16 v[96:99], v[152:155], v[188:191], v[96:99]
	v_mfma_f32_16x16x32_bf16 v[84:87], v[144:147], v[196:199], v[84:87]
	v_mfma_f32_16x16x32_bf16 v[80:83], v[152:155], v[196:199], v[80:83]
	v_mfma_f32_16x16x32_bf16 v[132:135], v[148:151], v[176:179], v[132:135]
	v_mfma_f32_16x16x32_bf16 v[128:131], v[156:159], v[176:179], v[128:131]
	v_mfma_f32_16x16x32_bf16 v[116:119], v[148:151], v[184:187], v[116:119]
	v_mfma_f32_16x16x32_bf16 v[112:115], v[156:159], v[184:187], v[112:115]
	v_mfma_f32_16x16x32_bf16 v[100:103], v[148:151], v[192:195], v[100:103]
	v_mfma_f32_16x16x32_bf16 v[96:99], v[156:159], v[192:195], v[96:99]
	v_mfma_f32_16x16x32_bf16 v[84:87], v[148:151], v[214:217], v[84:87]
	v_mfma_f32_16x16x32_bf16 v[80:83], v[156:159], v[214:217], v[80:83]
	s_barrier
	s_add_i32 s64, s55, s42
	s_add_u32 s98, s34, s16
	s_addc_u32 s99, s35, s17
	s_mov_b32 m0, s64
	ds_read_b128 v[172:175], v209 offset:16384
	ds_read_b128 v[176:179], v209 offset:17408
	ds_read_b128 v[180:183], v209 offset:18432
	ds_read_b128 v[184:187], v209 offset:19456
	ds_read_b128 v[188:191], v209 offset:20480
	ds_read_b128 v[192:195], v209 offset:21504
	ds_read_b128 v[196:199], v209 offset:22528
	ds_read_b128 v[214:217], v209 offset:23552
	global_load_lds_dwordx4 v162, s[34:35]
	s_add_i32 m0, s64, 0x2000
	s_add_u32 s64, s34, 0x40000
	s_addc_u32 s65, s35, 0
	s_add_i32 s66, s56, s42
	global_load_lds_dwordx4 v166, s[34:35]
	s_mov_b32 m0, s66
	s_nop 0
	global_load_lds_dwordx4 v162, s[64:65]
	s_add_i32 m0, s66, 0x2000
	s_nop 0
	global_load_lds_dwordx4 v166, s[64:65]
	s_add_u32 s100, s38, s16
	s_addc_u32 s101, s39, s17
	s_mov_b32 m0, s29
	s_nop 0
	global_load_lds_dwordx4 v160, s[38:39]
	s_mov_b32 m0, s43
	s_nop 0
	global_load_lds_dwordx4 v164, s[38:39]
	s_waitcnt vmcnt(8) lgkmcnt(0)
	s_barrier
	v_mfma_f32_16x16x32_bf16 v[76:79], v[36:39], v[172:175], v[76:79]
	v_mfma_f32_16x16x32_bf16 v[72:75], v[48:51], v[172:175], v[72:75]
	v_mfma_f32_16x16x32_bf16 v[60:63], v[36:39], v[180:183], v[60:63]
	v_mfma_f32_16x16x32_bf16 v[52:55], v[48:51], v[180:183], v[52:55]
	v_mfma_f32_16x16x32_bf16 v[28:31], v[36:39], v[188:191], v[28:31]
	v_mfma_f32_16x16x32_bf16 v[24:27], v[48:51], v[188:191], v[24:27]
	v_mfma_f32_16x16x32_bf16 v[12:15], v[36:39], v[196:199], v[12:15]
	v_mfma_f32_16x16x32_bf16 v[8:11], v[48:51], v[196:199], v[8:11]
	v_mfma_f32_16x16x32_bf16 v[76:79], v[44:47], v[176:179], v[76:79]
	v_mfma_f32_16x16x32_bf16 v[72:75], v[56:59], v[176:179], v[72:75]
	v_mfma_f32_16x16x32_bf16 v[60:63], v[44:47], v[184:187], v[60:63]
	v_mfma_f32_16x16x32_bf16 v[52:55], v[56:59], v[184:187], v[52:55]
	v_mfma_f32_16x16x32_bf16 v[28:31], v[44:47], v[192:195], v[28:31]
	v_mfma_f32_16x16x32_bf16 v[24:27], v[56:59], v[192:195], v[24:27]
	v_mfma_f32_16x16x32_bf16 v[12:15], v[44:47], v[214:217], v[12:15]
	v_mfma_f32_16x16x32_bf16 v[8:11], v[56:59], v[214:217], v[8:11]
	v_mfma_f32_16x16x32_bf16 v[40:43], v[144:147], v[180:183], v[40:43]
	v_mfma_f32_16x16x32_bf16 v[32:35], v[152:155], v[180:183], v[32:35]
	v_mfma_f32_16x16x32_bf16 v[20:23], v[144:147], v[188:191], v[20:23]
	v_mfma_f32_16x16x32_bf16 v[16:19], v[152:155], v[188:191], v[16:19]
	v_mfma_f32_16x16x32_bf16 v[4:7], v[144:147], v[196:199], v[4:7]
	v_mfma_f32_16x16x32_bf16 v[0:3], v[152:155], v[196:199], v[0:3]
	v_mfma_f32_16x16x32_bf16 v[36:39], v[144:147], v[172:175], v[68:71]
	v_mfma_f32_16x16x32_bf16 v[44:47], v[152:155], v[172:175], v[64:67]
	v_mfma_f32_16x16x32_bf16 v[40:43], v[148:151], v[184:187], v[40:43]
	v_mfma_f32_16x16x32_bf16 v[32:35], v[156:159], v[184:187], v[32:35]
	v_mfma_f32_16x16x32_bf16 v[20:23], v[148:151], v[192:195], v[20:23]
	v_mfma_f32_16x16x32_bf16 v[16:19], v[156:159], v[192:195], v[16:19]
	v_mfma_f32_16x16x32_bf16 v[4:7], v[148:151], v[214:217], v[4:7]
	v_mfma_f32_16x16x32_bf16 v[0:3], v[156:159], v[214:217], v[0:3]
	v_mfma_f32_16x16x32_bf16 v[36:39], v[148:151], v[176:179], v[36:39]
	v_mfma_f32_16x16x32_bf16 v[44:47], v[156:159], v[176:179], v[44:47]
	s_barrier
	s_add_i32 s64, 0, 0x18000
	s_add_i32 s65, 0, 0x1c000
	v_add_u32_e32 v68, s64, v201
	v_add_u32_e32 v156, s65, v201
	ds_read_b128 v[48:51], v68
	ds_read_b128 v[56:59], v68 offset:1024
	ds_read_b128 v[64:67], v68 offset:2048
	ds_read_b128 v[68:71], v68 offset:3072
	ds_read_b128 v[144:147], v156
	ds_read_b128 v[148:151], v156 offset:1024
	ds_read_b128 v[152:155], v156 offset:2048
	ds_read_b128 v[156:159], v156 offset:3072
	s_add_u32 s38, s38, 0x40000
	s_addc_u32 s39, s39, 0
	s_mov_b32 m0, s44
	ds_read_b128 v[172:175], v209 offset:32768
	ds_read_b128 v[176:179], v209 offset:33792
	ds_read_b128 v[180:183], v209 offset:34816
	ds_read_b128 v[184:187], v209 offset:35840
	ds_read_b128 v[188:191], v209 offset:36864
	ds_read_b128 v[192:195], v209 offset:37888
	ds_read_b128 v[196:199], v209 offset:38912
	ds_read_b128 v[214:217], v209 offset:39936
	global_load_lds_dwordx4 v160, s[38:39]
	s_mov_b32 m0, s45
	s_nop 0
	global_load_lds_dwordx4 v164, s[38:39]
	s_waitcnt vmcnt(8) lgkmcnt(0)
	s_barrier
	v_mfma_f32_16x16x32_bf16 v[140:143], v[48:51], v[172:175], v[140:143]
	v_mfma_f32_16x16x32_bf16 v[136:139], v[64:67], v[172:175], v[136:139]
	v_mfma_f32_16x16x32_bf16 v[124:127], v[48:51], v[180:183], v[124:127]
	v_mfma_f32_16x16x32_bf16 v[120:123], v[64:67], v[180:183], v[120:123]
	v_mfma_f32_16x16x32_bf16 v[108:111], v[48:51], v[188:191], v[108:111]
	v_mfma_f32_16x16x32_bf16 v[104:107], v[64:67], v[188:191], v[104:107]
	v_mfma_f32_16x16x32_bf16 v[92:95], v[48:51], v[196:199], v[92:95]
	v_mfma_f32_16x16x32_bf16 v[88:91], v[64:67], v[196:199], v[88:91]
	v_mfma_f32_16x16x32_bf16 v[140:143], v[56:59], v[176:179], v[140:143]
	v_mfma_f32_16x16x32_bf16 v[136:139], v[68:71], v[176:179], v[136:139]
	v_mfma_f32_16x16x32_bf16 v[124:127], v[56:59], v[184:187], v[124:127]
	v_mfma_f32_16x16x32_bf16 v[120:123], v[68:71], v[184:187], v[120:123]
	v_mfma_f32_16x16x32_bf16 v[108:111], v[56:59], v[192:195], v[108:111]
	v_mfma_f32_16x16x32_bf16 v[104:107], v[68:71], v[192:195], v[104:107]
	v_mfma_f32_16x16x32_bf16 v[92:95], v[56:59], v[214:217], v[92:95]
	v_mfma_f32_16x16x32_bf16 v[88:91], v[68:71], v[214:217], v[88:91]
	v_mfma_f32_16x16x32_bf16 v[132:135], v[144:147], v[172:175], v[132:135]
	v_mfma_f32_16x16x32_bf16 v[128:131], v[152:155], v[172:175], v[128:131]
	v_mfma_f32_16x16x32_bf16 v[116:119], v[144:147], v[180:183], v[116:119]
	v_mfma_f32_16x16x32_bf16 v[112:115], v[152:155], v[180:183], v[112:115]
	v_mfma_f32_16x16x32_bf16 v[100:103], v[144:147], v[188:191], v[100:103]
	v_mfma_f32_16x16x32_bf16 v[96:99], v[152:155], v[188:191], v[96:99]
	v_mfma_f32_16x16x32_bf16 v[84:87], v[144:147], v[196:199], v[84:87]
	v_mfma_f32_16x16x32_bf16 v[80:83], v[152:155], v[196:199], v[80:83]
	v_mfma_f32_16x16x32_bf16 v[132:135], v[148:151], v[176:179], v[132:135]
	v_mfma_f32_16x16x32_bf16 v[128:131], v[156:159], v[176:179], v[128:131]
	v_mfma_f32_16x16x32_bf16 v[116:119], v[148:151], v[184:187], v[116:119]
	v_mfma_f32_16x16x32_bf16 v[112:115], v[156:159], v[184:187], v[112:115]
	v_mfma_f32_16x16x32_bf16 v[100:103], v[148:151], v[192:195], v[100:103]
	v_mfma_f32_16x16x32_bf16 v[96:99], v[156:159], v[192:195], v[96:99]
	v_mfma_f32_16x16x32_bf16 v[84:87], v[148:151], v[214:217], v[84:87]
	v_mfma_f32_16x16x32_bf16 v[80:83], v[156:159], v[214:217], v[80:83]
	s_barrier
	s_add_i32 s38, s64, s42
	s_mov_b32 m0, s38
	ds_read_b128 v[172:175], v209 offset:49152
	ds_read_b128 v[176:179], v209 offset:50176
	ds_read_b128 v[180:183], v209 offset:51200
	ds_read_b128 v[184:187], v209 offset:52224
	ds_read_b128 v[188:191], v209 offset:53248
	ds_read_b128 v[192:195], v209 offset:54272
	ds_read_b128 v[196:199], v209 offset:55296
	ds_read_b128 v[214:217], v209 offset:56320
	global_load_lds_dwordx4 v162, s[98:99]
	s_add_i32 m0, s38, 0x2000
	s_add_u32 s34, s34, 0x40080
	s_addc_u32 s35, s35, 0
	s_add_i32 s38, s65, s42
	global_load_lds_dwordx4 v166, s[98:99]
	s_mov_b32 m0, s38
	s_nop 0
	global_load_lds_dwordx4 v162, s[34:35]
	s_add_i32 m0, s38, 0x2000
	s_nop 0
	global_load_lds_dwordx4 v166, s[34:35]
	s_mov_b32 m0, s50
	s_nop 0
	global_load_lds_dwordx4 v160, s[100:101]
	s_mov_b32 m0, s51
	s_nop 0
	global_load_lds_dwordx4 v164, s[100:101]
	s_waitcnt vmcnt(8) lgkmcnt(0)
	s_barrier
	v_mfma_f32_16x16x32_bf16 v[76:79], v[48:51], v[172:175], v[76:79]
	v_mfma_f32_16x16x32_bf16 v[72:75], v[64:67], v[172:175], v[72:75]
	v_mfma_f32_16x16x32_bf16 v[60:63], v[48:51], v[180:183], v[60:63]
	v_mfma_f32_16x16x32_bf16 v[52:55], v[64:67], v[180:183], v[52:55]
	v_mfma_f32_16x16x32_bf16 v[28:31], v[48:51], v[188:191], v[28:31]
	v_mfma_f32_16x16x32_bf16 v[24:27], v[64:67], v[188:191], v[24:27]
	v_mfma_f32_16x16x32_bf16 v[12:15], v[48:51], v[196:199], v[12:15]
	v_mfma_f32_16x16x32_bf16 v[8:11], v[64:67], v[196:199], v[8:11]
	v_mfma_f32_16x16x32_bf16 v[76:79], v[56:59], v[176:179], v[76:79]
	v_mfma_f32_16x16x32_bf16 v[72:75], v[68:71], v[176:179], v[72:75]
	v_mfma_f32_16x16x32_bf16 v[60:63], v[56:59], v[184:187], v[60:63]
	v_mfma_f32_16x16x32_bf16 v[52:55], v[68:71], v[184:187], v[52:55]
	v_mfma_f32_16x16x32_bf16 v[28:31], v[56:59], v[192:195], v[28:31]
	v_mfma_f32_16x16x32_bf16 v[24:27], v[68:71], v[192:195], v[24:27]
	v_mfma_f32_16x16x32_bf16 v[12:15], v[56:59], v[214:217], v[12:15]
	v_mfma_f32_16x16x32_bf16 v[8:11], v[68:71], v[214:217], v[8:11]
	v_mfma_f32_16x16x32_bf16 v[36:39], v[144:147], v[172:175], v[36:39]
	v_mfma_f32_16x16x32_bf16 v[68:71], v[148:151], v[176:179], v[36:39]
	v_mfma_f32_16x16x32_bf16 v[36:39], v[152:155], v[172:175], v[44:47]
	v_mfma_f32_16x16x32_bf16 v[64:67], v[156:159], v[176:179], v[36:39]
	v_mfma_f32_16x16x32_bf16 v[36:39], v[144:147], v[180:183], v[40:43]
	v_mfma_f32_16x16x32_bf16 v[32:35], v[152:155], v[180:183], v[32:35]
	v_mfma_f32_16x16x32_bf16 v[20:23], v[144:147], v[188:191], v[20:23]
	v_mfma_f32_16x16x32_bf16 v[16:19], v[152:155], v[188:191], v[16:19]
	v_mfma_f32_16x16x32_bf16 v[4:7], v[144:147], v[196:199], v[4:7]
	v_mfma_f32_16x16x32_bf16 v[0:3], v[152:155], v[196:199], v[0:3]
	v_mfma_f32_16x16x32_bf16 v[40:43], v[148:151], v[184:187], v[36:39]
	v_mfma_f32_16x16x32_bf16 v[32:35], v[156:159], v[184:187], v[32:35]
	v_mfma_f32_16x16x32_bf16 v[20:23], v[148:151], v[192:195], v[20:23]
	v_mfma_f32_16x16x32_bf16 v[16:19], v[156:159], v[192:195], v[16:19]
	v_mfma_f32_16x16x32_bf16 v[4:7], v[148:151], v[214:217], v[4:7]
	v_mfma_f32_16x16x32_bf16 v[0:3], v[156:159], v[214:217], v[0:3]
	s_barrier
	s_add_i32 s63, s63, 2
	s_add_u32 s30, s30, 0x100
	s_addc_u32 s31, s31, 0
	s_add_u32 s61, s61, 0x100
	s_addc_u32 s62, s62, 0
	s_cmp_gt_u32 s63, 13
	s_cbranch_scc0 .LBB0_2031
	s_lshl_b32 s2, s2, 8
	v_mov_b32_e32 v154, v229
	v_mov_b32_e32 v155, v231
	s_or_b32 s2, s2, s49
	s_mov_b64 s[34:35], s[26:27]
	v_lshl_add_u32 v144, v155, 3, s2
	v_ashrrev_i32_e32 v145, 31, v144
	v_lshlrev_b64 v[188:189], 2, v[144:145]
	v_lshl_add_u64 v[150:151], s[4:5], 0, v[188:189]
	global_load_dwordx4 v[36:39], v[150:151], off offset:16
	global_load_dwordx4 v[44:47], v[150:151], off
	v_lshl_add_u64 v[152:153], s[6:7], 0, v[188:189]
	global_load_dwordx4 v[48:51], v[152:153], off offset:16
	global_load_dwordx4 v[56:59], v[152:153], off
	s_lshl_b32 s2, s28, 8
	s_add_i32 s2, s2, s48
	s_mov_b32 s28, s22
	s_mov_b64 s[30:31], s[24:25]
	s_waitcnt vmcnt(0)
	v_pk_mul_f32 v[184:185], v[38:39], s[18:19] op_sel_hi:[1,0]
	v_pk_mul_f32 v[186:187], v[36:37], s[18:19] op_sel_hi:[1,0]
	global_load_dwordx4 v[146:149], v[150:151], off offset:528
	global_load_dwordx4 v[36:39], v[150:151], off offset:512
	v_pk_mul_f32 v[190:191], v[46:47], s[18:19] op_sel_hi:[1,0]
	v_pk_mul_f32 v[192:193], v[44:45], s[18:19] op_sel_hi:[1,0]
	s_waitcnt vmcnt(1)
	v_pk_mul_f32 v[176:177], v[148:149], s[18:19] op_sel_hi:[1,0]
	v_pk_mul_f32 v[178:179], v[146:147], s[18:19] op_sel_hi:[1,0]
	v_add_u32_e32 v146, s2, v154
	v_lshlrev_b32_e32 v148, 2, v155
	v_ashrrev_i32_e32 v149, 31, v148
	v_ashrrev_i32_e32 v147, 31, v146
	v_lshl_add_u64 v[194:195], v[148:149], 2, s[12:13]
	v_lshl_add_u64 v[148:149], v[146:147], 4, s[10:11]
	s_waitcnt vmcnt(0)
	v_pk_mul_f32 v[180:181], v[38:39], s[18:19] op_sel_hi:[1,0]
	v_pk_mul_f32 v[182:183], v[36:37], s[18:19] op_sel_hi:[1,0]
	global_load_dwordx4 v[36:39], v[152:153], off offset:528
	global_load_dwordx4 v[44:47], v[152:153], off offset:512
	v_lshlrev_b64 v[152:153], 6, v[146:147]
	global_load_dwordx4 v[148:151], v[148:149], off
	v_lshl_add_u64 v[152:153], v[194:195], 0, v[152:153]
	global_load_dwordx4 v[152:155], v[152:153], off
	v_add_u32_e32 v238, 16, v146
	v_ashrrev_i32_e32 v239, 31, v238
	v_lshl_add_u64 v[156:157], v[238:239], 4, s[10:11]
	global_load_dwordx4 v[156:159], v[156:157], off
	v_lshlrev_b64 v[172:173], 6, v[238:239]
	v_lshl_add_u64 v[172:173], v[194:195], 0, v[172:173]
	global_load_dwordx4 v[214:217], v[172:173], off
	v_add_u32_e32 v232, 32, v146
	v_ashrrev_i32_e32 v233, 31, v232
	v_lshl_add_u64 v[172:173], v[232:233], 4, s[10:11]
	global_load_dwordx4 v[218:221], v[172:173], off
	v_lshlrev_b64 v[172:173], 6, v[232:233]
	v_lshl_add_u64 v[172:173], v[194:195], 0, v[172:173]
	global_load_dwordx4 v[222:225], v[172:173], off
	v_add_u32_e32 v226, 48, v146
	v_ashrrev_i32_e32 v227, 31, v226
	v_lshl_add_u64 v[172:173], v[226:227], 4, s[10:11]
	global_load_dwordx4 v[244:247], v[172:173], off
	v_lshlrev_b64 v[172:173], 6, v[226:227]
	v_lshl_add_u64 v[172:173], v[194:195], 0, v[172:173]
	global_load_dwordx4 v[248:251], v[172:173], off
	v_add_u32_e32 v210, 0x90, v146
	v_ashrrev_i32_e32 v211, 31, v210
	v_add_u32_e32 v204, 0xa0, v146
	v_ashrrev_i32_e32 v205, 31, v204
	v_add_u32_e32 v198, 0xb0, v146
	v_ashrrev_i32_e32 v199, 31, v198
	v_lshlrev_b64 v[196:197], 6, v[198:199]
	s_mov_b32 s2, s20
	s_waitcnt vmcnt(7)
	v_mov_b32_e32 v172, v149
	v_mov_b32_e32 v173, v150
	v_mov_b32_e32 v149, v151
	v_pk_add_f32 v[148:149], v[172:173], v[148:149]
	v_lshlrev_b64 v[172:173], 6, v[210:211]
	v_add_f32_e32 v148, v148, v149
	v_fmamk_f32 v148, v148, 0x3a800000, v213
	v_rsq_f32_e32 v148, v148
	s_waitcnt vmcnt(6)
	v_add_f32_e32 v149, v154, v155
	v_lshl_add_u64 v[172:173], v[194:195], 0, v[172:173]
	v_mul_f32_e32 v242, 0xbfb8aa3b, v148
	v_add_f32_e32 v148, v152, v153
	v_add_f32_e32 v148, v148, v149
	v_mov_b32_e32 v149, v148
	s_nop 1
	v_permlane16_swap_b32_e32 v148, v149
	v_add_f32_e32 v148, v148, v149
	v_mov_b32_e32 v149, v148
	s_nop 1
	v_permlane32_swap_b32_e32 v148, v149
	v_add_f32_e32 v148, v148, v149
	v_fmamk_f32 v148, v148, 0x3a800000, v213
	v_rsq_f32_e32 v240, v148
	s_waitcnt vmcnt(5)
	v_mov_b32_e32 v148, v157
	v_mov_b32_e32 v149, v158
	v_mov_b32_e32 v157, v159
	v_pk_add_f32 v[148:149], v[148:149], v[156:157]
	v_lshl_add_u64 v[156:157], v[210:211], 4, s[10:11]
	v_add_f32_e32 v148, v148, v149
	v_fmamk_f32 v148, v148, 0x3a800000, v213
	v_rsq_f32_e32 v148, v148
	s_waitcnt vmcnt(4)
	v_add_f32_e32 v149, v216, v217
	global_load_dwordx4 v[156:159], v[156:157], off
	v_pk_fma_f32 v[142:143], v[142:143], v[242:243], v[190:191] op_sel_hi:[1,0,1]
	v_mul_f32_e32 v236, 0xbfb8aa3b, v148
	v_add_f32_e32 v148, v214, v215
	v_add_f32_e32 v148, v148, v149
	v_mov_b32_e32 v149, v148
	s_nop 1
	v_permlane16_swap_b32_e32 v148, v149
	v_add_f32_e32 v148, v148, v149
	v_mov_b32_e32 v149, v148
	s_nop 1
	v_permlane32_swap_b32_e32 v148, v149
	v_add_f32_e32 v148, v148, v149
	v_fmamk_f32 v148, v148, 0x3a800000, v213
	v_rsq_f32_e32 v234, v148
	s_waitcnt vmcnt(4)
	v_mov_b32_e32 v148, v219
	v_mov_b32_e32 v149, v220
	v_mov_b32_e32 v219, v221
	v_pk_add_f32 v[148:149], v[148:149], v[218:219]
	v_add_u32_e32 v220, 0x80, v146
	v_add_f32_e32 v148, v148, v149
	v_fmamk_f32 v148, v148, 0x3a800000, v213
	v_rsq_f32_e32 v148, v148
	s_waitcnt vmcnt(3)
	v_add_f32_e32 v149, v224, v225
	v_ashrrev_i32_e32 v221, 31, v220
	v_lshlrev_b64 v[152:153], 6, v[220:221]
	v_mul_f32_e32 v230, 0xbfb8aa3b, v148
	v_add_f32_e32 v148, v222, v223
	v_add_f32_e32 v148, v148, v149
	v_mov_b32_e32 v149, v148
	s_nop 1
	v_permlane16_swap_b32_e32 v148, v149
	v_add_f32_e32 v148, v148, v149
	v_mov_b32_e32 v149, v148
	s_nop 1
	v_permlane32_swap_b32_e32 v148, v149
	v_add_f32_e32 v148, v148, v149
	v_fmamk_f32 v148, v148, 0x3a800000, v213
	v_rsq_f32_e32 v228, v148
	s_waitcnt vmcnt(2)
	v_mov_b32_e32 v148, v245
	v_mov_b32_e32 v149, v246
	v_mov_b32_e32 v245, v247
	v_pk_add_f32 v[148:149], v[148:149], v[244:245]
	v_lshl_add_u64 v[152:153], v[194:195], 0, v[152:153]
	v_add_f32_e32 v148, v148, v149
	v_fmamk_f32 v148, v148, 0x3a800000, v213
	v_rsq_f32_e32 v148, v148
	s_waitcnt vmcnt(1)
	v_add_f32_e32 v149, v250, v251
	global_load_dwordx4 v[152:155], v[152:153], off
	v_pk_fma_f32 v[140:141], v[140:141], v[242:243], v[192:193] op_sel_hi:[1,0,1]
	v_mul_f32_e32 v224, 0xbfb8aa3b, v148
	v_add_f32_e32 v148, v248, v249
	v_add_f32_e32 v148, v148, v149
	v_mov_b32_e32 v149, v148
	s_nop 1
	v_permlane16_swap_b32_e32 v148, v149
	v_add_f32_e32 v148, v148, v149
	v_mov_b32_e32 v149, v148
	s_nop 1
	v_permlane32_swap_b32_e32 v148, v149
	v_add_f32_e32 v148, v148, v149
	v_fmamk_f32 v148, v148, 0x3a800000, v213
	v_rsq_f32_e32 v222, v148
	v_lshl_add_u64 v[148:149], v[220:221], 4, s[10:11]
	global_load_dwordx4 v[148:151], v[148:149], off
	v_exp_f32_e32 v142, v142
	global_load_dwordx4 v[216:219], v[172:173], off
	v_lshl_add_u64 v[172:173], v[204:205], 4, s[10:11]
	global_load_dwordx4 v[244:247], v[172:173], off
	v_lshlrev_b64 v[172:173], 6, v[204:205]
	v_lshl_add_u64 v[172:173], v[194:195], 0, v[172:173]
	global_load_dwordx4 v[248:251], v[172:173], off
	v_lshl_add_u64 v[194:195], v[194:195], 0, v[196:197]
	global_load_dwordx4 v[194:197], v[194:195], off
	v_lshl_add_u64 v[172:173], v[198:199], 4, s[10:11]
	global_load_dwordx4 v[172:175], v[172:173], off
	v_exp_f32_e32 v143, v143
	v_exp_f32_e32 v140, v140
	v_exp_f32_e32 v141, v141
	v_pk_fma_f32 v[138:139], v[138:139], v[242:243], v[184:185] op_sel_hi:[1,0,1]
	v_pk_add_f32 v[142:143], v[142:143], 1.0 op_sel_hi:[1,0]
	v_exp_f32_e32 v138, v138
	v_exp_f32_e32 v139, v139
	v_pk_fma_f32 v[136:137], v[136:137], v[242:243], v[186:187] op_sel_hi:[1,0,1]
	v_pk_add_f32 v[140:141], v[140:141], 1.0 op_sel_hi:[1,0]
	v_rcp_f32_e32 v142, v142
	v_rcp_f32_e32 v143, v143
	v_exp_f32_e32 v136, v136
	v_exp_f32_e32 v137, v137
	v_rcp_f32_e32 v140, v140
	v_rcp_f32_e32 v141, v141
	v_pk_add_f32 v[138:139], v[138:139], 1.0 op_sel_hi:[1,0]
	v_pk_add_f32 v[136:137], v[136:137], 1.0 op_sel_hi:[1,0]
	v_rcp_f32_e32 v138, v138
	v_rcp_f32_e32 v139, v139
	v_rcp_f32_e32 v136, v136
	v_rcp_f32_e32 v137, v137
	v_pk_fma_f32 v[132:133], v[132:133], v[242:243], v[182:183] op_sel_hi:[1,0,1]
	v_pk_fma_f32 v[134:135], v[134:135], v[242:243], v[180:181] op_sel_hi:[1,0,1]
	v_exp_f32_e32 v132, v132
	v_exp_f32_e32 v133, v133
	v_exp_f32_e32 v134, v134
	v_exp_f32_e32 v135, v135
	v_pk_fma_f32 v[128:129], v[128:129], v[242:243], v[178:179] op_sel_hi:[1,0,1]
	v_pk_fma_f32 v[130:131], v[130:131], v[242:243], v[176:177] op_sel_hi:[1,0,1]
	v_pk_add_f32 v[132:133], v[132:133], 1.0 op_sel_hi:[1,0]
	v_pk_add_f32 v[134:135], v[134:135], 1.0 op_sel_hi:[1,0]
	v_exp_f32_e32 v128, v128
	v_exp_f32_e32 v129, v129
	v_exp_f32_e32 v130, v130
	v_exp_f32_e32 v131, v131
	v_rcp_f32_e32 v132, v132
	v_rcp_f32_e32 v133, v133
	v_rcp_f32_e32 v134, v134
	v_rcp_f32_e32 v135, v135
	v_pk_add_f32 v[128:129], v[128:129], 1.0 op_sel_hi:[1,0]
	v_pk_add_f32 v[130:131], v[130:131], 1.0 op_sel_hi:[1,0]
	v_rcp_f32_e32 v128, v128
	v_rcp_f32_e32 v129, v129
	v_rcp_f32_e32 v130, v130
	v_rcp_f32_e32 v131, v131
	v_pk_fma_f32 v[126:127], v[126:127], v[236:237], v[190:191] op_sel_hi:[1,0,1]
	v_pk_fma_f32 v[124:125], v[124:125], v[236:237], v[192:193] op_sel_hi:[1,0,1]
	v_exp_f32_e32 v126, v126
	v_exp_f32_e32 v127, v127
	v_exp_f32_e32 v124, v124
	v_exp_f32_e32 v125, v125
	v_pk_fma_f32 v[122:123], v[122:123], v[236:237], v[184:185] op_sel_hi:[1,0,1]
	v_pk_add_f32 v[126:127], v[126:127], 1.0 op_sel_hi:[1,0]
	v_exp_f32_e32 v122, v122
	v_exp_f32_e32 v123, v123
	v_pk_fma_f32 v[120:121], v[120:121], v[236:237], v[186:187] op_sel_hi:[1,0,1]
	v_pk_add_f32 v[124:125], v[124:125], 1.0 op_sel_hi:[1,0]
	v_rcp_f32_e32 v126, v126
	v_rcp_f32_e32 v127, v127
	v_exp_f32_e32 v120, v120
	v_exp_f32_e32 v121, v121
	v_rcp_f32_e32 v124, v124
	v_rcp_f32_e32 v125, v125
	v_pk_add_f32 v[122:123], v[122:123], 1.0 op_sel_hi:[1,0]
	v_pk_add_f32 v[120:121], v[120:121], 1.0 op_sel_hi:[1,0]
	v_rcp_f32_e32 v122, v122
	v_rcp_f32_e32 v123, v123
	v_rcp_f32_e32 v120, v120
	s_waitcnt vmcnt(5)
	v_mov_b32_e32 v214, v149
	v_mov_b32_e32 v215, v150
	v_mov_b32_e32 v149, v151
	v_pk_add_f32 v[148:149], v[214:215], v[148:149]
	v_rcp_f32_e32 v121, v121
	v_add_f32_e32 v148, v148, v149
	v_fmamk_f32 v148, v148, 0x3a800000, v213
	v_rsq_f32_e32 v148, v148
	v_add_f32_e32 v149, v154, v155
	v_pk_fma_f32 v[116:117], v[116:117], v[236:237], v[182:183] op_sel_hi:[1,0,1]
	v_pk_fma_f32 v[118:119], v[118:119], v[236:237], v[180:181] op_sel_hi:[1,0,1]
	v_mul_f32_e32 v214, 0xbfb8aa3b, v148
	v_add_f32_e32 v148, v152, v153
	v_add_f32_e32 v148, v148, v149
	v_mov_b32_e32 v149, v148
	s_nop 1
	v_permlane16_swap_b32_e32 v148, v149
	v_add_f32_e32 v148, v148, v149
	v_mov_b32_e32 v149, v148
	s_nop 1
	v_permlane32_swap_b32_e32 v148, v149
	v_add_f32_e32 v148, v148, v149
	v_fmamk_f32 v148, v148, 0x3a800000, v213
	v_rsq_f32_e32 v212, v148
	v_mov_b32_e32 v148, v157
	v_mov_b32_e32 v149, v158
	v_mov_b32_e32 v157, v159
	v_pk_add_f32 v[148:149], v[148:149], v[156:157]
	v_exp_f32_e32 v116, v116
	v_add_f32_e32 v148, v148, v149
	v_fmamk_f32 v148, v148, 0x3a800000, v213
	v_rsq_f32_e32 v148, v148
	s_waitcnt vmcnt(4)
	v_add_f32_e32 v149, v218, v219
	v_exp_f32_e32 v117, v117
	v_exp_f32_e32 v118, v118
	v_mul_f32_e32 v208, 0xbfb8aa3b, v148
	v_add_f32_e32 v148, v216, v217
	v_add_f32_e32 v148, v148, v149
	v_mov_b32_e32 v149, v148
	s_nop 1
	v_permlane16_swap_b32_e32 v148, v149
	v_add_f32_e32 v148, v148, v149
	v_mov_b32_e32 v149, v148
	s_nop 1
	v_permlane32_swap_b32_e32 v148, v149
	v_add_f32_e32 v148, v148, v149
	v_fmamk_f32 v148, v148, 0x3a800000, v213
	v_rsq_f32_e32 v206, v148
	s_waitcnt vmcnt(3)
	v_mov_b32_e32 v148, v245
	v_mov_b32_e32 v149, v246
	v_mov_b32_e32 v245, v247
	v_pk_add_f32 v[148:149], v[148:149], v[244:245]
	v_lshlrev_b64 v[244:245], 12, v[146:147]
	v_add_f32_e32 v148, v148, v149
	v_fmamk_f32 v148, v148, 0x3a800000, v213
	v_rsq_f32_e32 v148, v148
	s_waitcnt vmcnt(2)
	v_add_f32_e32 v149, v250, v251
	v_exp_f32_e32 v119, v119
	v_pk_fma_f32 v[112:113], v[112:113], v[236:237], v[178:179] op_sel_hi:[1,0,1]
	v_mul_f32_e32 v202, 0xbfb8aa3b, v148
	v_add_f32_e32 v148, v248, v249
	v_add_f32_e32 v148, v148, v149
	v_mov_b32_e32 v149, v148
	s_nop 1
	v_permlane16_swap_b32_e32 v148, v149
	v_add_f32_e32 v148, v148, v149
	v_mov_b32_e32 v149, v148
	s_nop 1
	v_permlane32_swap_b32_e32 v148, v149
	v_add_f32_e32 v148, v148, v149
	v_fmamk_f32 v148, v148, 0x3a800000, v213
	v_rsq_f32_e32 v200, v148
	s_waitcnt vmcnt(0)
	v_mov_b32_e32 v148, v173
	v_mov_b32_e32 v149, v174
	v_mov_b32_e32 v173, v175
	v_pk_add_f32 v[148:149], v[148:149], v[172:173]
	v_pk_fma_f32 v[114:115], v[114:115], v[236:237], v[176:177] op_sel_hi:[1,0,1]
	v_add_f32_e32 v148, v148, v149
	v_fmamk_f32 v148, v148, 0x3a800000, v213
	v_rsq_f32_e32 v148, v148
	v_add_f32_e32 v149, v196, v197
	v_pk_add_f32 v[116:117], v[116:117], 1.0 op_sel_hi:[1,0]
	v_pk_add_f32 v[118:119], v[118:119], 1.0 op_sel_hi:[1,0]
	v_mul_f32_e32 v172, 0xbfb8aa3b, v148
	v_add_f32_e32 v148, v194, v195
	v_add_f32_e32 v148, v148, v149
	v_mov_b32_e32 v149, v148
	s_nop 1
	v_permlane16_swap_b32_e32 v148, v149
	v_add_f32_e32 v148, v148, v149
	v_mov_b32_e32 v149, v148
	s_nop 1
	v_permlane32_swap_b32_e32 v148, v149
	v_add_f32_e32 v148, v148, v149
	v_fmamk_f32 v148, v148, 0x3a800000, v213
	v_rsq_f32_e32 v194, v148
	v_lshlrev_b64 v[148:149], 10, v[146:147]
	v_lshl_add_u64 v[144:145], v[148:149], 0, v[144:145]
	v_lshlrev_b64 v[144:145], 1, v[144:145]
	v_lshl_add_u64 v[216:217], s[68:69], 0, v[144:145]
	v_lshl_add_u64 v[218:219], s[8:9], 0, v[144:145]
	global_load_dwordx4 v[152:155], v[216:217], off
	global_load_dwordx4 v[156:159], v[218:219], off
	global_load_dwordx4 v[148:151], v[216:217], off offset:256
	global_load_dwordx4 v[144:147], v[218:219], off offset:256
	v_exp_f32_e32 v112, v112
	v_exp_f32_e32 v113, v113
	v_exp_f32_e32 v114, v114
	v_exp_f32_e32 v115, v115
	v_rcp_f32_e32 v116, v116
	v_rcp_f32_e32 v117, v117
	v_rcp_f32_e32 v118, v118
	v_rcp_f32_e32 v119, v119
	v_pk_add_f32 v[112:113], v[112:113], 1.0 op_sel_hi:[1,0]
	v_pk_add_f32 v[114:115], v[114:115], 1.0 op_sel_hi:[1,0]
	v_rcp_f32_e32 v112, v112
	v_rcp_f32_e32 v113, v113
	v_rcp_f32_e32 v114, v114
	v_rcp_f32_e32 v115, v115
	v_pk_fma_f32 v[110:111], v[110:111], v[230:231], v[190:191] op_sel_hi:[1,0,1]
	v_pk_fma_f32 v[108:109], v[108:109], v[230:231], v[192:193] op_sel_hi:[1,0,1]
	v_exp_f32_e32 v110, v110
	v_exp_f32_e32 v111, v111
	v_exp_f32_e32 v108, v108
	v_exp_f32_e32 v109, v109
	v_pk_fma_f32 v[106:107], v[106:107], v[230:231], v[184:185] op_sel_hi:[1,0,1]
	v_pk_add_f32 v[110:111], v[110:111], 1.0 op_sel_hi:[1,0]
	v_exp_f32_e32 v106, v106
	v_exp_f32_e32 v107, v107
	v_pk_fma_f32 v[104:105], v[104:105], v[230:231], v[186:187] op_sel_hi:[1,0,1]
	v_pk_add_f32 v[108:109], v[108:109], 1.0 op_sel_hi:[1,0]
	v_rcp_f32_e32 v110, v110
	v_rcp_f32_e32 v111, v111
	v_exp_f32_e32 v104, v104
	v_exp_f32_e32 v105, v105
	v_rcp_f32_e32 v108, v108
	v_rcp_f32_e32 v109, v109
	v_pk_add_f32 v[106:107], v[106:107], 1.0 op_sel_hi:[1,0]
	v_pk_add_f32 v[104:105], v[104:105], 1.0 op_sel_hi:[1,0]
	v_rcp_f32_e32 v106, v106
	v_rcp_f32_e32 v107, v107
	v_rcp_f32_e32 v104, v104
	v_rcp_f32_e32 v105, v105
	v_pk_fma_f32 v[100:101], v[100:101], v[230:231], v[182:183] op_sel_hi:[1,0,1]
	v_pk_fma_f32 v[102:103], v[102:103], v[230:231], v[180:181] op_sel_hi:[1,0,1]
	v_exp_f32_e32 v100, v100
	v_exp_f32_e32 v101, v101
	v_exp_f32_e32 v102, v102
	v_exp_f32_e32 v103, v103
	v_pk_fma_f32 v[96:97], v[96:97], v[230:231], v[178:179] op_sel_hi:[1,0,1]
	v_pk_fma_f32 v[98:99], v[98:99], v[230:231], v[176:177] op_sel_hi:[1,0,1]
	v_pk_add_f32 v[100:101], v[100:101], 1.0 op_sel_hi:[1,0]
	v_pk_add_f32 v[102:103], v[102:103], 1.0 op_sel_hi:[1,0]
	v_exp_f32_e32 v96, v96
	v_exp_f32_e32 v97, v97
	v_exp_f32_e32 v98, v98
	v_exp_f32_e32 v99, v99
	v_rcp_f32_e32 v100, v100
	v_rcp_f32_e32 v101, v101
	v_rcp_f32_e32 v102, v102
	v_rcp_f32_e32 v103, v103
	v_pk_add_f32 v[96:97], v[96:97], 1.0 op_sel_hi:[1,0]
	v_pk_add_f32 v[98:99], v[98:99], 1.0 op_sel_hi:[1,0]
	v_rcp_f32_e32 v96, v96
	v_rcp_f32_e32 v97, v97
	v_rcp_f32_e32 v98, v98
	v_rcp_f32_e32 v99, v99
	v_pk_fma_f32 v[94:95], v[94:95], v[224:225], v[190:191] op_sel_hi:[1,0,1]
	v_pk_fma_f32 v[92:93], v[92:93], v[224:225], v[192:193] op_sel_hi:[1,0,1]
	v_exp_f32_e32 v94, v94
	v_exp_f32_e32 v95, v95
	v_exp_f32_e32 v92, v92
	v_exp_f32_e32 v93, v93
	v_pk_fma_f32 v[90:91], v[90:91], v[224:225], v[184:185] op_sel_hi:[1,0,1]
	v_pk_add_f32 v[94:95], v[94:95], 1.0 op_sel_hi:[1,0]
	v_exp_f32_e32 v90, v90
	v_exp_f32_e32 v91, v91
	v_pk_fma_f32 v[88:89], v[88:89], v[224:225], v[186:187] op_sel_hi:[1,0,1]
	v_pk_add_f32 v[92:93], v[92:93], 1.0 op_sel_hi:[1,0]
	v_rcp_f32_e32 v94, v94
	v_rcp_f32_e32 v95, v95
	s_waitcnt vmcnt(3)
	v_lshlrev_b32_e32 v246, 16, v152
	s_waitcnt vmcnt(2)
	v_lshlrev_b32_e32 v174, 16, v156
	v_and_b32_e32 v175, 0xffff0000, v156
	v_lshlrev_b32_e32 v156, 16, v157
	v_and_b32_e32 v157, 0xffff0000, v157
	v_pk_mul_f32 v[156:157], v[240:241], v[156:157] op_sel_hi:[0,1]
	v_and_b32_e32 v247, 0xffff0000, v152
	v_lshlrev_b32_e32 v152, 16, v153
	v_and_b32_e32 v153, 0xffff0000, v153
	v_pk_mul_f32 v[174:175], v[240:241], v[174:175] op_sel_hi:[0,1]
	v_pk_mul_f32 v[156:157], v[58:59], v[156:157]
	v_pk_mul_f32 v[174:175], v[56:57], v[174:175]
	v_pk_fma_f32 v[142:143], v[142:143], v[156:157], v[152:153]
	v_lshl_add_u64 v[152:153], s[36:37], 0, v[244:245]
	v_lshlrev_b32_e32 v156, 16, v159
	v_and_b32_e32 v157, 0xffff0000, v159
	v_pk_fma_f32 v[140:141], v[140:141], v[174:175], v[246:247]
	v_lshl_add_u64 v[152:153], v[152:153], 0, v[188:189]
	v_pk_mul_f32 v[156:157], v[240:241], v[156:157] op_sel_hi:[0,1]
	global_store_dwordx4 v[152:153], v[140:143], off nt
	v_pk_mul_f32 v[156:157], v[50:51], v[156:157]
	s_waitcnt vmcnt(1)
	v_lshlrev_b32_e32 v174, 16, v144
	v_lshlrev_b32_e32 v140, 16, v154
	v_and_b32_e32 v141, 0xffff0000, v154
	v_lshlrev_b32_e32 v142, 16, v158
	v_and_b32_e32 v143, 0xffff0000, v158
	v_lshlrev_b32_e32 v154, 16, v155
	v_and_b32_e32 v155, 0xffff0000, v155
	v_pk_mul_f32 v[142:143], v[240:241], v[142:143] op_sel_hi:[0,1]
	v_pk_fma_f32 v[138:139], v[138:139], v[156:157], v[154:155]
	v_add_co_u32_e32 v154, vcc, s53, v216
	v_pk_mul_f32 v[142:143], v[48:49], v[142:143]
	s_nop 0
	v_addc_co_u32_e32 v155, vcc, 0, v217, vcc
	v_pk_fma_f32 v[136:137], v[136:137], v[142:143], v[140:141]
	v_add_co_u32_e32 v156, vcc, s53, v218
	global_store_dwordx4 v[152:153], v[136:139], off offset:16 nt
	s_nop 0
	v_addc_co_u32_e32 v157, vcc, 0, v219, vcc
	global_load_dwordx4 v[136:139], v[154:155], off
	global_load_dwordx4 v[140:143], v[156:157], off
	v_and_b32_e32 v175, 0xffff0000, v144
	v_lshlrev_b32_e32 v144, 16, v145
	v_and_b32_e32 v145, 0xffff0000, v145
	v_pk_mul_f32 v[144:145], v[240:241], v[144:145] op_sel_hi:[0,1]
	v_pk_mul_f32 v[174:175], v[240:241], v[174:175] op_sel_hi:[0,1]
	v_lshlrev_b32_e32 v158, 16, v148
	v_and_b32_e32 v159, 0xffff0000, v148
	v_lshlrev_b32_e32 v148, 16, v149
	v_and_b32_e32 v149, 0xffff0000, v149
	v_pk_mul_f32 v[174:175], v[44:45], v[174:175]
	v_pk_mul_f32 v[144:145], v[46:47], v[144:145]
	v_pk_fma_f32 v[132:133], v[132:133], v[174:175], v[158:159]
	v_pk_fma_f32 v[134:135], v[134:135], v[144:145], v[148:149]
	global_store_dwordx4 v[152:153], v[132:135], off offset:512 nt
	v_lshlrev_b32_e32 v144, 16, v151
	v_and_b32_e32 v145, 0xffff0000, v151
	v_lshlrev_b32_e32 v134, 16, v146
	v_and_b32_e32 v135, 0xffff0000, v146
	v_lshlrev_b32_e32 v146, 16, v147
	v_and_b32_e32 v147, 0xffff0000, v147
	v_pk_mul_f32 v[146:147], v[240:241], v[146:147] op_sel_hi:[0,1]
	v_pk_mul_f32 v[134:135], v[240:241], v[134:135] op_sel_hi:[0,1]
	v_lshlrev_b32_e32 v132, 16, v150
	v_and_b32_e32 v133, 0xffff0000, v150
	v_pk_mul_f32 v[134:135], v[36:37], v[134:135]
	v_pk_mul_f32 v[146:147], v[38:39], v[146:147]
	v_pk_fma_f32 v[128:129], v[128:129], v[134:135], v[132:133]
	v_pk_fma_f32 v[130:131], v[130:131], v[146:147], v[144:145]
	global_store_dwordx4 v[152:153], v[128:131], off offset:528 nt
	global_load_dwordx4 v[132:135], v[154:155], off offset:256
	s_nop 0
	global_load_dwordx4 v[128:131], v[156:157], off offset:256
	v_lshlrev_b64 v[144:145], 12, v[238:239]
	v_exp_f32_e32 v88, v88
	v_exp_f32_e32 v89, v89
	v_rcp_f32_e32 v92, v92
	v_rcp_f32_e32 v93, v93
	v_pk_add_f32 v[90:91], v[90:91], 1.0 op_sel_hi:[1,0]
	v_pk_add_f32 v[88:89], v[88:89], 1.0 op_sel_hi:[1,0]
	v_rcp_f32_e32 v90, v90
	v_rcp_f32_e32 v91, v91
	v_rcp_f32_e32 v88, v88
	v_rcp_f32_e32 v89, v89
	v_pk_fma_f32 v[84:85], v[84:85], v[224:225], v[182:183] op_sel_hi:[1,0,1]
	v_pk_fma_f32 v[86:87], v[86:87], v[224:225], v[180:181] op_sel_hi:[1,0,1]
	v_exp_f32_e32 v84, v84
	v_exp_f32_e32 v85, v85
	v_exp_f32_e32 v86, v86
	v_exp_f32_e32 v87, v87
	v_pk_fma_f32 v[80:81], v[80:81], v[224:225], v[178:179] op_sel_hi:[1,0,1]
	v_pk_fma_f32 v[82:83], v[82:83], v[224:225], v[176:177] op_sel_hi:[1,0,1]
	v_pk_add_f32 v[84:85], v[84:85], 1.0 op_sel_hi:[1,0]
	v_pk_add_f32 v[86:87], v[86:87], 1.0 op_sel_hi:[1,0]
	v_exp_f32_e32 v80, v80
	v_exp_f32_e32 v81, v81
	v_exp_f32_e32 v82, v82
	v_exp_f32_e32 v83, v83
	v_rcp_f32_e32 v84, v84
	v_rcp_f32_e32 v85, v85
	v_rcp_f32_e32 v86, v86
	v_rcp_f32_e32 v87, v87
	v_pk_add_f32 v[80:81], v[80:81], 1.0 op_sel_hi:[1,0]
	v_pk_add_f32 v[82:83], v[82:83], 1.0 op_sel_hi:[1,0]
	v_rcp_f32_e32 v80, v80
	v_rcp_f32_e32 v81, v81
	v_rcp_f32_e32 v82, v82
	v_rcp_f32_e32 v83, v83
	v_pk_fma_f32 v[78:79], v[78:79], v[214:215], v[190:191] op_sel_hi:[1,0,1]
	v_pk_fma_f32 v[76:77], v[76:77], v[214:215], v[192:193] op_sel_hi:[1,0,1]
	v_exp_f32_e32 v78, v78
	v_exp_f32_e32 v79, v79
	v_exp_f32_e32 v76, v76
	v_exp_f32_e32 v77, v77
	v_pk_fma_f32 v[74:75], v[74:75], v[214:215], v[184:185] op_sel_hi:[1,0,1]
	v_pk_add_f32 v[78:79], v[78:79], 1.0 op_sel_hi:[1,0]
	v_exp_f32_e32 v74, v74
	v_exp_f32_e32 v75, v75
	v_pk_fma_f32 v[72:73], v[72:73], v[214:215], v[186:187] op_sel_hi:[1,0,1]
	s_waitcnt vmcnt(5)
	v_lshlrev_b32_e32 v146, 16, v136
	s_waitcnt vmcnt(4)
	v_lshlrev_b32_e32 v148, 16, v140
	v_and_b32_e32 v149, 0xffff0000, v140
	v_lshlrev_b32_e32 v140, 16, v141
	v_and_b32_e32 v141, 0xffff0000, v141
	v_pk_mul_f32 v[140:141], v[234:235], v[140:141] op_sel_hi:[0,1]
	v_and_b32_e32 v147, 0xffff0000, v136
	v_lshlrev_b32_e32 v136, 16, v137
	v_and_b32_e32 v137, 0xffff0000, v137
	v_pk_mul_f32 v[148:149], v[234:235], v[148:149] op_sel_hi:[0,1]
	v_pk_mul_f32 v[140:141], v[58:59], v[140:141]
	v_pk_mul_f32 v[148:149], v[56:57], v[148:149]
	v_pk_fma_f32 v[126:127], v[126:127], v[140:141], v[136:137]
	v_lshl_add_u64 v[136:137], s[36:37], 0, v[144:145]
	v_lshlrev_b32_e32 v140, 16, v143
	v_and_b32_e32 v141, 0xffff0000, v143
	v_pk_fma_f32 v[124:125], v[124:125], v[148:149], v[146:147]
	v_lshl_add_u64 v[136:137], v[136:137], 0, v[188:189]
	v_pk_mul_f32 v[140:141], v[234:235], v[140:141] op_sel_hi:[0,1]
	global_store_dwordx4 v[136:137], v[124:127], off nt
	v_pk_mul_f32 v[140:141], v[50:51], v[140:141]
	v_pk_add_f32 v[76:77], v[76:77], 1.0 op_sel_hi:[1,0]
	v_lshlrev_b32_e32 v124, 16, v138
	v_and_b32_e32 v125, 0xffff0000, v138
	v_lshlrev_b32_e32 v126, 16, v142
	v_and_b32_e32 v127, 0xffff0000, v142
	v_lshlrev_b32_e32 v138, 16, v139
	v_and_b32_e32 v139, 0xffff0000, v139
	v_pk_mul_f32 v[126:127], v[234:235], v[126:127] op_sel_hi:[0,1]
	v_pk_fma_f32 v[122:123], v[122:123], v[140:141], v[138:139]
	v_add_co_u32_e32 v138, vcc, s47, v216
	v_pk_mul_f32 v[126:127], v[48:49], v[126:127]
	s_nop 0
	v_addc_co_u32_e32 v139, vcc, 0, v217, vcc
	v_pk_fma_f32 v[120:121], v[120:121], v[126:127], v[124:125]
	v_add_co_u32_e32 v140, vcc, s47, v218
	global_store_dwordx4 v[136:137], v[120:123], off offset:16 nt
	s_nop 0
	v_addc_co_u32_e32 v141, vcc, 0, v219, vcc
	global_load_dwordx4 v[120:123], v[138:139], off
	global_load_dwordx4 v[124:127], v[140:141], off
	s_waitcnt vmcnt(4)
	v_lshlrev_b32_e32 v144, 16, v128
	v_and_b32_e32 v145, 0xffff0000, v128
	v_lshlrev_b32_e32 v128, 16, v129
	v_and_b32_e32 v129, 0xffff0000, v129
	v_pk_mul_f32 v[128:129], v[234:235], v[128:129] op_sel_hi:[0,1]
	v_pk_mul_f32 v[144:145], v[234:235], v[144:145] op_sel_hi:[0,1]
	v_lshlrev_b32_e32 v142, 16, v132
	v_and_b32_e32 v143, 0xffff0000, v132
	v_lshlrev_b32_e32 v132, 16, v133
	v_and_b32_e32 v133, 0xffff0000, v133
	v_pk_mul_f32 v[144:145], v[44:45], v[144:145]
	v_pk_mul_f32 v[128:129], v[46:47], v[128:129]
	v_pk_fma_f32 v[116:117], v[116:117], v[144:145], v[142:143]
	v_pk_fma_f32 v[118:119], v[118:119], v[128:129], v[132:133]
	global_store_dwordx4 v[136:137], v[116:119], off offset:512 nt
	v_lshlrev_b32_e32 v128, 16, v135
	v_and_b32_e32 v129, 0xffff0000, v135
	v_lshlrev_b32_e32 v118, 16, v130
	v_and_b32_e32 v119, 0xffff0000, v130
	v_lshlrev_b32_e32 v130, 16, v131
	v_and_b32_e32 v131, 0xffff0000, v131
	v_pk_mul_f32 v[130:131], v[234:235], v[130:131] op_sel_hi:[0,1]
	v_pk_mul_f32 v[118:119], v[234:235], v[118:119] op_sel_hi:[0,1]
	v_lshlrev_b32_e32 v116, 16, v134
	v_and_b32_e32 v117, 0xffff0000, v134
	v_pk_mul_f32 v[118:119], v[36:37], v[118:119]
	v_pk_mul_f32 v[130:131], v[38:39], v[130:131]
	v_pk_fma_f32 v[112:113], v[112:113], v[118:119], v[116:117]
	v_pk_fma_f32 v[114:115], v[114:115], v[130:131], v[128:129]
	global_store_dwordx4 v[136:137], v[112:115], off offset:528 nt
	global_load_dwordx4 v[116:119], v[138:139], off offset:256
	s_nop 0
	global_load_dwordx4 v[112:115], v[140:141], off offset:256
	v_lshlrev_b64 v[128:129], 12, v[232:233]
	v_rcp_f32_e32 v78, v78
	v_rcp_f32_e32 v79, v79
	v_exp_f32_e32 v72, v72
	v_exp_f32_e32 v73, v73
	v_rcp_f32_e32 v76, v76
	v_rcp_f32_e32 v77, v77
	v_pk_add_f32 v[74:75], v[74:75], 1.0 op_sel_hi:[1,0]
	v_pk_add_f32 v[72:73], v[72:73], 1.0 op_sel_hi:[1,0]
	v_rcp_f32_e32 v74, v74
	v_rcp_f32_e32 v75, v75
	v_pk_fma_f32 v[68:69], v[68:69], v[214:215], v[182:183] op_sel_hi:[1,0,1]
	v_pk_fma_f32 v[70:71], v[70:71], v[214:215], v[180:181] op_sel_hi:[1,0,1]
	v_rcp_f32_e32 v72, v72
	v_rcp_f32_e32 v73, v73
	v_exp_f32_e32 v68, v68
	v_exp_f32_e32 v69, v69
	v_exp_f32_e32 v70, v70
	v_exp_f32_e32 v71, v71
	v_pk_fma_f32 v[64:65], v[64:65], v[214:215], v[178:179] op_sel_hi:[1,0,1]
	v_pk_fma_f32 v[66:67], v[66:67], v[214:215], v[176:177] op_sel_hi:[1,0,1]
	v_pk_add_f32 v[68:69], v[68:69], 1.0 op_sel_hi:[1,0]
	v_pk_add_f32 v[70:71], v[70:71], 1.0 op_sel_hi:[1,0]
	v_exp_f32_e32 v64, v64
	v_exp_f32_e32 v65, v65
	v_exp_f32_e32 v66, v66
	v_exp_f32_e32 v67, v67
	v_rcp_f32_e32 v68, v68
	v_rcp_f32_e32 v69, v69
	v_rcp_f32_e32 v70, v70
	v_rcp_f32_e32 v71, v71
	v_pk_add_f32 v[64:65], v[64:65], 1.0 op_sel_hi:[1,0]
	v_pk_add_f32 v[66:67], v[66:67], 1.0 op_sel_hi:[1,0]
	v_rcp_f32_e32 v64, v64
	v_rcp_f32_e32 v65, v65
	v_rcp_f32_e32 v66, v66
	v_rcp_f32_e32 v67, v67
	v_pk_fma_f32 v[62:63], v[62:63], v[208:209], v[190:191] op_sel_hi:[1,0,1]
	v_pk_fma_f32 v[60:61], v[60:61], v[208:209], v[192:193] op_sel_hi:[1,0,1]
	v_exp_f32_e32 v62, v62
	v_exp_f32_e32 v63, v63
	v_exp_f32_e32 v60, v60
	v_exp_f32_e32 v61, v61
	v_pk_fma_f32 v[54:55], v[54:55], v[208:209], v[184:185] op_sel_hi:[1,0,1]
	v_pk_add_f32 v[62:63], v[62:63], 1.0 op_sel_hi:[1,0]
	s_waitcnt vmcnt(5)
	v_lshlrev_b32_e32 v130, 16, v120
	s_waitcnt vmcnt(4)
	v_lshlrev_b32_e32 v132, 16, v124
	v_and_b32_e32 v133, 0xffff0000, v124
	v_lshlrev_b32_e32 v124, 16, v125
	v_and_b32_e32 v125, 0xffff0000, v125
	v_pk_mul_f32 v[124:125], v[228:229], v[124:125] op_sel_hi:[0,1]
	v_and_b32_e32 v131, 0xffff0000, v120
	v_lshlrev_b32_e32 v120, 16, v121
	v_and_b32_e32 v121, 0xffff0000, v121
	v_pk_mul_f32 v[132:133], v[228:229], v[132:133] op_sel_hi:[0,1]
	v_pk_mul_f32 v[124:125], v[58:59], v[124:125]
	v_pk_mul_f32 v[132:133], v[56:57], v[132:133]
	v_pk_fma_f32 v[110:111], v[110:111], v[124:125], v[120:121]
	v_lshl_add_u64 v[120:121], s[36:37], 0, v[128:129]
	v_lshlrev_b32_e32 v124, 16, v127
	v_and_b32_e32 v125, 0xffff0000, v127
	v_pk_fma_f32 v[108:109], v[108:109], v[132:133], v[130:131]
	v_lshl_add_u64 v[120:121], v[120:121], 0, v[188:189]
	v_pk_mul_f32 v[124:125], v[228:229], v[124:125] op_sel_hi:[0,1]
	global_store_dwordx4 v[120:121], v[108:111], off nt
	v_pk_mul_f32 v[124:125], v[50:51], v[124:125]
	v_exp_f32_e32 v54, v54
	v_lshlrev_b32_e32 v108, 16, v122
	v_and_b32_e32 v109, 0xffff0000, v122
	v_lshlrev_b32_e32 v110, 16, v126
	v_and_b32_e32 v111, 0xffff0000, v126
	v_lshlrev_b32_e32 v122, 16, v123
	v_and_b32_e32 v123, 0xffff0000, v123
	v_pk_mul_f32 v[110:111], v[228:229], v[110:111] op_sel_hi:[0,1]
	v_pk_fma_f32 v[106:107], v[106:107], v[124:125], v[122:123]
	v_add_co_u32_e32 v122, vcc, s52, v216
	v_pk_mul_f32 v[110:111], v[48:49], v[110:111]
	s_nop 0
	v_addc_co_u32_e32 v123, vcc, 0, v217, vcc
	v_pk_fma_f32 v[104:105], v[104:105], v[110:111], v[108:109]
	v_add_co_u32_e32 v124, vcc, s52, v218
	global_store_dwordx4 v[120:121], v[104:107], off offset:16 nt
	s_nop 0
	v_addc_co_u32_e32 v125, vcc, 0, v219, vcc
	global_load_dwordx4 v[104:107], v[122:123], off
	global_load_dwordx4 v[108:111], v[124:125], off
	s_waitcnt vmcnt(4)
	v_lshlrev_b32_e32 v128, 16, v112
	v_and_b32_e32 v129, 0xffff0000, v112
	v_lshlrev_b32_e32 v112, 16, v113
	v_and_b32_e32 v113, 0xffff0000, v113
	v_pk_mul_f32 v[112:113], v[228:229], v[112:113] op_sel_hi:[0,1]
	v_pk_mul_f32 v[128:129], v[228:229], v[128:129] op_sel_hi:[0,1]
	v_lshlrev_b32_e32 v126, 16, v116
	v_and_b32_e32 v127, 0xffff0000, v116
	v_lshlrev_b32_e32 v116, 16, v117
	v_and_b32_e32 v117, 0xffff0000, v117
	v_pk_mul_f32 v[128:129], v[44:45], v[128:129]
	v_pk_mul_f32 v[112:113], v[46:47], v[112:113]
	v_pk_fma_f32 v[100:101], v[100:101], v[128:129], v[126:127]
	v_pk_fma_f32 v[102:103], v[102:103], v[112:113], v[116:117]
	global_store_dwordx4 v[120:121], v[100:103], off offset:512 nt
	v_lshlrev_b32_e32 v112, 16, v119
	v_and_b32_e32 v113, 0xffff0000, v119
	v_lshlrev_b32_e32 v102, 16, v114
	v_and_b32_e32 v103, 0xffff0000, v114
	v_lshlrev_b32_e32 v114, 16, v115
	v_and_b32_e32 v115, 0xffff0000, v115
	v_pk_mul_f32 v[114:115], v[228:229], v[114:115] op_sel_hi:[0,1]
	v_pk_mul_f32 v[102:103], v[228:229], v[102:103] op_sel_hi:[0,1]
	v_lshlrev_b32_e32 v100, 16, v118
	v_and_b32_e32 v101, 0xffff0000, v118
	v_pk_mul_f32 v[102:103], v[36:37], v[102:103]
	v_pk_mul_f32 v[114:115], v[38:39], v[114:115]
	v_pk_fma_f32 v[96:97], v[96:97], v[102:103], v[100:101]
	v_pk_fma_f32 v[98:99], v[98:99], v[114:115], v[112:113]
	global_store_dwordx4 v[120:121], v[96:99], off offset:528 nt
	global_load_dwordx4 v[100:103], v[122:123], off offset:256
	s_nop 0
	global_load_dwordx4 v[96:99], v[124:125], off offset:256
	v_lshlrev_b64 v[112:113], 12, v[226:227]
	v_exp_f32_e32 v55, v55
	v_pk_fma_f32 v[52:53], v[52:53], v[208:209], v[186:187] op_sel_hi:[1,0,1]
	v_pk_add_f32 v[60:61], v[60:61], 1.0 op_sel_hi:[1,0]
	v_rcp_f32_e32 v62, v62
	v_rcp_f32_e32 v63, v63
	v_exp_f32_e32 v52, v52
	v_exp_f32_e32 v53, v53
	v_rcp_f32_e32 v60, v60
	v_rcp_f32_e32 v61, v61
	v_pk_add_f32 v[54:55], v[54:55], 1.0 op_sel_hi:[1,0]
	v_pk_fma_f32 v[40:41], v[40:41], v[208:209], v[182:183] op_sel_hi:[1,0,1]
	v_rcp_f32_e32 v54, v54
	v_rcp_f32_e32 v55, v55
	v_pk_fma_f32 v[42:43], v[42:43], v[208:209], v[180:181] op_sel_hi:[1,0,1]
	v_pk_add_f32 v[52:53], v[52:53], 1.0 op_sel_hi:[1,0]
	v_exp_f32_e32 v40, v40
	v_exp_f32_e32 v41, v41
	v_exp_f32_e32 v42, v42
	v_exp_f32_e32 v43, v43
	v_rcp_f32_e32 v52, v52
	v_rcp_f32_e32 v53, v53
	v_pk_fma_f32 v[32:33], v[32:33], v[208:209], v[178:179] op_sel_hi:[1,0,1]
	v_pk_fma_f32 v[34:35], v[34:35], v[208:209], v[176:177] op_sel_hi:[1,0,1]
	v_pk_add_f32 v[40:41], v[40:41], 1.0 op_sel_hi:[1,0]
	v_pk_add_f32 v[42:43], v[42:43], 1.0 op_sel_hi:[1,0]
	v_exp_f32_e32 v32, v32
	v_exp_f32_e32 v33, v33
	v_exp_f32_e32 v34, v34
	v_exp_f32_e32 v35, v35
	v_rcp_f32_e32 v40, v40
	v_rcp_f32_e32 v41, v41
	v_rcp_f32_e32 v42, v42
	v_rcp_f32_e32 v43, v43
	v_pk_add_f32 v[32:33], v[32:33], 1.0 op_sel_hi:[1,0]
	v_pk_add_f32 v[34:35], v[34:35], 1.0 op_sel_hi:[1,0]
	v_rcp_f32_e32 v32, v32
	v_rcp_f32_e32 v33, v33
	v_rcp_f32_e32 v34, v34
	v_rcp_f32_e32 v35, v35
	v_pk_fma_f32 v[30:31], v[30:31], v[202:203], v[190:191] op_sel_hi:[1,0,1]
	v_pk_fma_f32 v[28:29], v[28:29], v[202:203], v[192:193] op_sel_hi:[1,0,1]
	v_exp_f32_e32 v30, v30
	v_exp_f32_e32 v31, v31
	v_exp_f32_e32 v28, v28
	s_waitcnt vmcnt(5)
	v_lshlrev_b32_e32 v114, 16, v104
	s_waitcnt vmcnt(4)
	v_lshlrev_b32_e32 v116, 16, v108
	v_and_b32_e32 v117, 0xffff0000, v108
	v_lshlrev_b32_e32 v108, 16, v109
	v_and_b32_e32 v109, 0xffff0000, v109
	v_pk_mul_f32 v[108:109], v[222:223], v[108:109] op_sel_hi:[0,1]
	v_and_b32_e32 v115, 0xffff0000, v104
	v_lshlrev_b32_e32 v104, 16, v105
	v_and_b32_e32 v105, 0xffff0000, v105
	v_pk_mul_f32 v[116:117], v[222:223], v[116:117] op_sel_hi:[0,1]
	v_pk_mul_f32 v[108:109], v[58:59], v[108:109]
	v_pk_mul_f32 v[116:117], v[56:57], v[116:117]
	v_pk_fma_f32 v[94:95], v[94:95], v[108:109], v[104:105]
	v_lshl_add_u64 v[104:105], s[36:37], 0, v[112:113]
	v_lshlrev_b32_e32 v108, 16, v111
	v_and_b32_e32 v109, 0xffff0000, v111
	v_pk_fma_f32 v[92:93], v[92:93], v[116:117], v[114:115]
	v_lshl_add_u64 v[104:105], v[104:105], 0, v[188:189]
	v_pk_mul_f32 v[108:109], v[222:223], v[108:109] op_sel_hi:[0,1]
	global_store_dwordx4 v[104:105], v[92:95], off nt
	v_pk_mul_f32 v[108:109], v[50:51], v[108:109]
	v_exp_f32_e32 v29, v29
	v_lshlrev_b32_e32 v92, 16, v106
	v_and_b32_e32 v93, 0xffff0000, v106
	v_lshlrev_b32_e32 v94, 16, v110
	v_and_b32_e32 v95, 0xffff0000, v110
	v_lshlrev_b32_e32 v106, 16, v107
	v_and_b32_e32 v107, 0xffff0000, v107
	v_pk_mul_f32 v[94:95], v[222:223], v[94:95] op_sel_hi:[0,1]
	v_pk_fma_f32 v[90:91], v[90:91], v[108:109], v[106:107]
	v_add_co_u32_e32 v106, vcc, s57, v216
	v_pk_mul_f32 v[94:95], v[48:49], v[94:95]
	s_nop 0
	v_addc_co_u32_e32 v107, vcc, 0, v217, vcc
	v_pk_fma_f32 v[88:89], v[88:89], v[94:95], v[92:93]
	v_add_co_u32_e32 v108, vcc, s57, v218
	global_store_dwordx4 v[104:105], v[88:91], off offset:16 nt
	s_nop 0
	v_addc_co_u32_e32 v109, vcc, 0, v219, vcc
	global_load_dwordx4 v[88:91], v[106:107], off
	global_load_dwordx4 v[92:95], v[108:109], off
	s_waitcnt vmcnt(4)
	v_lshlrev_b32_e32 v112, 16, v96
	v_and_b32_e32 v113, 0xffff0000, v96
	v_lshlrev_b32_e32 v96, 16, v97
	v_and_b32_e32 v97, 0xffff0000, v97
	v_pk_mul_f32 v[96:97], v[222:223], v[96:97] op_sel_hi:[0,1]
	v_pk_mul_f32 v[112:113], v[222:223], v[112:113] op_sel_hi:[0,1]
	v_lshlrev_b32_e32 v110, 16, v100
	v_and_b32_e32 v111, 0xffff0000, v100
	v_lshlrev_b32_e32 v100, 16, v101
	v_and_b32_e32 v101, 0xffff0000, v101
	v_pk_mul_f32 v[112:113], v[44:45], v[112:113]
	v_pk_mul_f32 v[96:97], v[46:47], v[96:97]
	v_pk_fma_f32 v[84:85], v[84:85], v[112:113], v[110:111]
	v_pk_fma_f32 v[86:87], v[86:87], v[96:97], v[100:101]
	global_store_dwordx4 v[104:105], v[84:87], off offset:512 nt
	v_lshlrev_b32_e32 v96, 16, v103
	v_and_b32_e32 v97, 0xffff0000, v103
	v_lshlrev_b32_e32 v86, 16, v98
	v_and_b32_e32 v87, 0xffff0000, v98
	v_lshlrev_b32_e32 v98, 16, v99
	v_and_b32_e32 v99, 0xffff0000, v99
	v_pk_mul_f32 v[98:99], v[222:223], v[98:99] op_sel_hi:[0,1]
	v_pk_mul_f32 v[86:87], v[222:223], v[86:87] op_sel_hi:[0,1]
	v_lshlrev_b32_e32 v84, 16, v102
	v_and_b32_e32 v85, 0xffff0000, v102
	v_pk_mul_f32 v[86:87], v[36:37], v[86:87]
	v_pk_mul_f32 v[98:99], v[38:39], v[98:99]
	v_pk_fma_f32 v[80:81], v[80:81], v[86:87], v[84:85]
	v_pk_fma_f32 v[82:83], v[82:83], v[98:99], v[96:97]
	global_store_dwordx4 v[104:105], v[80:83], off offset:528 nt
	global_load_dwordx4 v[84:87], v[106:107], off offset:256
	s_nop 0
	global_load_dwordx4 v[80:83], v[108:109], off offset:256
	v_lshlrev_b64 v[96:97], 12, v[220:221]
	v_pk_fma_f32 v[26:27], v[26:27], v[202:203], v[184:185] op_sel_hi:[1,0,1]
	v_pk_add_f32 v[30:31], v[30:31], 1.0 op_sel_hi:[1,0]
	v_exp_f32_e32 v26, v26
	v_exp_f32_e32 v27, v27
	v_pk_fma_f32 v[24:25], v[24:25], v[202:203], v[186:187] op_sel_hi:[1,0,1]
	v_pk_add_f32 v[28:29], v[28:29], 1.0 op_sel_hi:[1,0]
	v_rcp_f32_e32 v30, v30
	v_rcp_f32_e32 v31, v31
	v_exp_f32_e32 v24, v24
	v_exp_f32_e32 v25, v25
	v_rcp_f32_e32 v28, v28
	v_rcp_f32_e32 v29, v29
	v_pk_add_f32 v[26:27], v[26:27], 1.0 op_sel_hi:[1,0]
	v_pk_fma_f32 v[20:21], v[20:21], v[202:203], v[182:183] op_sel_hi:[1,0,1]
	v_pk_fma_f32 v[22:23], v[22:23], v[202:203], v[180:181] op_sel_hi:[1,0,1]
	v_rcp_f32_e32 v26, v26
	v_rcp_f32_e32 v27, v27
	v_exp_f32_e32 v20, v20
	v_exp_f32_e32 v21, v21
	v_exp_f32_e32 v22, v22
	v_exp_f32_e32 v23, v23
	v_pk_add_f32 v[24:25], v[24:25], 1.0 op_sel_hi:[1,0]
	v_pk_fma_f32 v[16:17], v[16:17], v[202:203], v[178:179] op_sel_hi:[1,0,1]
	v_rcp_f32_e32 v24, v24
	v_rcp_f32_e32 v25, v25
	v_pk_fma_f32 v[18:19], v[18:19], v[202:203], v[176:177] op_sel_hi:[1,0,1]
	v_pk_add_f32 v[20:21], v[20:21], 1.0 op_sel_hi:[1,0]
	v_pk_add_f32 v[22:23], v[22:23], 1.0 op_sel_hi:[1,0]
	v_exp_f32_e32 v16, v16
	v_exp_f32_e32 v17, v17
	v_exp_f32_e32 v18, v18
	v_exp_f32_e32 v19, v19
	v_rcp_f32_e32 v20, v20
	v_rcp_f32_e32 v21, v21
	v_rcp_f32_e32 v22, v22
	v_rcp_f32_e32 v23, v23
	v_pk_add_f32 v[16:17], v[16:17], 1.0 op_sel_hi:[1,0]
	v_pk_add_f32 v[18:19], v[18:19], 1.0 op_sel_hi:[1,0]
	v_rcp_f32_e32 v16, v16
	v_rcp_f32_e32 v17, v17
	v_rcp_f32_e32 v18, v18
	v_rcp_f32_e32 v19, v19
	v_pk_fma_f32 v[14:15], v[14:15], v[172:173], v[190:191] op_sel_hi:[1,0,1]
	v_pk_fma_f32 v[12:13], v[12:13], v[172:173], v[192:193] op_sel_hi:[1,0,1]
	s_waitcnt vmcnt(5)
	v_lshlrev_b32_e32 v98, 16, v88
	s_waitcnt vmcnt(4)
	v_lshlrev_b32_e32 v100, 16, v92
	v_and_b32_e32 v101, 0xffff0000, v92
	v_lshlrev_b32_e32 v92, 16, v93
	v_and_b32_e32 v93, 0xffff0000, v93
	v_pk_mul_f32 v[92:93], v[212:213], v[92:93] op_sel_hi:[0,1]
	v_and_b32_e32 v99, 0xffff0000, v88
	v_lshlrev_b32_e32 v88, 16, v89
	v_and_b32_e32 v89, 0xffff0000, v89
	v_pk_mul_f32 v[100:101], v[212:213], v[100:101] op_sel_hi:[0,1]
	v_pk_mul_f32 v[92:93], v[58:59], v[92:93]
	v_pk_mul_f32 v[100:101], v[56:57], v[100:101]
	v_pk_fma_f32 v[78:79], v[78:79], v[92:93], v[88:89]
	v_lshl_add_u64 v[88:89], s[36:37], 0, v[96:97]
	v_lshlrev_b32_e32 v92, 16, v95
	v_and_b32_e32 v93, 0xffff0000, v95
	v_pk_fma_f32 v[76:77], v[76:77], v[100:101], v[98:99]
	v_lshl_add_u64 v[88:89], v[88:89], 0, v[188:189]
	v_pk_mul_f32 v[92:93], v[212:213], v[92:93] op_sel_hi:[0,1]
	global_store_dwordx4 v[88:89], v[76:79], off nt
	v_pk_mul_f32 v[92:93], v[50:51], v[92:93]
	v_exp_f32_e32 v14, v14
	v_lshlrev_b32_e32 v76, 16, v90
	v_and_b32_e32 v77, 0xffff0000, v90
	v_lshlrev_b32_e32 v78, 16, v94
	v_and_b32_e32 v79, 0xffff0000, v94
	v_lshlrev_b32_e32 v90, 16, v91
	v_and_b32_e32 v91, 0xffff0000, v91
	v_pk_mul_f32 v[78:79], v[212:213], v[78:79] op_sel_hi:[0,1]
	v_pk_fma_f32 v[74:75], v[74:75], v[92:93], v[90:91]
	v_add_co_u32_e32 v90, vcc, s58, v216
	v_pk_mul_f32 v[78:79], v[48:49], v[78:79]
	s_nop 0
	v_addc_co_u32_e32 v91, vcc, 0, v217, vcc
	v_pk_fma_f32 v[72:73], v[72:73], v[78:79], v[76:77]
	v_add_co_u32_e32 v92, vcc, s58, v218
	global_store_dwordx4 v[88:89], v[72:75], off offset:16 nt
	s_nop 0
	v_addc_co_u32_e32 v93, vcc, 0, v219, vcc
	global_load_dwordx4 v[72:75], v[90:91], off
	global_load_dwordx4 v[76:79], v[92:93], off
	s_waitcnt vmcnt(4)
	v_lshlrev_b32_e32 v96, 16, v80
	v_and_b32_e32 v97, 0xffff0000, v80
	v_lshlrev_b32_e32 v80, 16, v81
	v_and_b32_e32 v81, 0xffff0000, v81
	v_pk_mul_f32 v[80:81], v[212:213], v[80:81] op_sel_hi:[0,1]
	v_pk_mul_f32 v[96:97], v[212:213], v[96:97] op_sel_hi:[0,1]
	v_lshlrev_b32_e32 v94, 16, v84
	v_and_b32_e32 v95, 0xffff0000, v84
	v_lshlrev_b32_e32 v84, 16, v85
	v_and_b32_e32 v85, 0xffff0000, v85
	v_pk_mul_f32 v[96:97], v[44:45], v[96:97]
	v_pk_mul_f32 v[80:81], v[46:47], v[80:81]
	v_pk_fma_f32 v[68:69], v[68:69], v[96:97], v[94:95]
	v_pk_fma_f32 v[70:71], v[70:71], v[80:81], v[84:85]
	global_store_dwordx4 v[88:89], v[68:71], off offset:512 nt
	v_lshlrev_b32_e32 v80, 16, v87
	v_and_b32_e32 v81, 0xffff0000, v87
	v_lshlrev_b32_e32 v70, 16, v82
	v_and_b32_e32 v71, 0xffff0000, v82
	v_lshlrev_b32_e32 v82, 16, v83
	v_and_b32_e32 v83, 0xffff0000, v83
	v_pk_mul_f32 v[82:83], v[212:213], v[82:83] op_sel_hi:[0,1]
	v_pk_mul_f32 v[70:71], v[212:213], v[70:71] op_sel_hi:[0,1]
	v_lshlrev_b32_e32 v68, 16, v86
	v_and_b32_e32 v69, 0xffff0000, v86
	v_pk_mul_f32 v[70:71], v[36:37], v[70:71]
	v_pk_mul_f32 v[82:83], v[38:39], v[82:83]
	v_pk_fma_f32 v[64:65], v[64:65], v[70:71], v[68:69]
	v_pk_fma_f32 v[66:67], v[66:67], v[82:83], v[80:81]
	global_store_dwordx4 v[88:89], v[64:67], off offset:528 nt
	global_load_dwordx4 v[64:67], v[90:91], off offset:256
	s_nop 0
	global_load_dwordx4 v[68:71], v[92:93], off offset:256
	v_lshlrev_b64 v[80:81], 12, v[210:211]
	v_exp_f32_e32 v15, v15
	v_exp_f32_e32 v12, v12
	v_exp_f32_e32 v13, v13
	v_pk_fma_f32 v[8:9], v[8:9], v[172:173], v[186:187] op_sel_hi:[1,0,1]
	v_pk_fma_f32 v[10:11], v[10:11], v[172:173], v[184:185] op_sel_hi:[1,0,1]
	v_exp_f32_e32 v8, v8
	v_exp_f32_e32 v9, v9
	v_exp_f32_e32 v10, v10
	v_exp_f32_e32 v11, v11
	v_pk_add_f32 v[14:15], v[14:15], 1.0 op_sel_hi:[1,0]
	v_pk_add_f32 v[12:13], v[12:13], 1.0 op_sel_hi:[1,0]
	v_rcp_f32_e32 v14, v14
	v_rcp_f32_e32 v15, v15
	v_pk_fma_f32 v[4:5], v[4:5], v[172:173], v[182:183] op_sel_hi:[1,0,1]
	v_pk_fma_f32 v[6:7], v[6:7], v[172:173], v[180:181] op_sel_hi:[1,0,1]
	v_rcp_f32_e32 v12, v12
	v_rcp_f32_e32 v13, v13
	v_pk_add_f32 v[8:9], v[8:9], 1.0 op_sel_hi:[1,0]
	v_pk_add_f32 v[10:11], v[10:11], 1.0 op_sel_hi:[1,0]
	v_exp_f32_e32 v4, v4
	v_exp_f32_e32 v5, v5
	v_exp_f32_e32 v6, v6
	v_exp_f32_e32 v7, v7
	v_rcp_f32_e32 v8, v8
	v_rcp_f32_e32 v9, v9
	v_rcp_f32_e32 v10, v10
	v_rcp_f32_e32 v11, v11
	v_pk_fma_f32 v[0:1], v[0:1], v[172:173], v[178:179] op_sel_hi:[1,0,1]
	v_pk_fma_f32 v[2:3], v[2:3], v[172:173], v[176:177] op_sel_hi:[1,0,1]
	v_pk_add_f32 v[4:5], v[4:5], 1.0 op_sel_hi:[1,0]
	v_pk_add_f32 v[6:7], v[6:7], 1.0 op_sel_hi:[1,0]
	v_exp_f32_e32 v0, v0
	v_exp_f32_e32 v1, v1
	v_exp_f32_e32 v2, v2
	v_exp_f32_e32 v3, v3
	v_rcp_f32_e32 v4, v4
	v_rcp_f32_e32 v5, v5
	v_rcp_f32_e32 v6, v6
	v_rcp_f32_e32 v7, v7
	v_pk_add_f32 v[0:1], v[0:1], 1.0 op_sel_hi:[1,0]
	v_pk_add_f32 v[2:3], v[2:3], 1.0 op_sel_hi:[1,0]
	v_rcp_f32_e32 v0, v0
	v_rcp_f32_e32 v1, v1
	v_rcp_f32_e32 v2, v2
	s_waitcnt vmcnt(5)
	v_lshlrev_b32_e32 v82, 16, v72
	s_waitcnt vmcnt(4)
	v_lshlrev_b32_e32 v84, 16, v76
	v_and_b32_e32 v85, 0xffff0000, v76
	v_lshlrev_b32_e32 v76, 16, v77
	v_and_b32_e32 v77, 0xffff0000, v77
	v_pk_mul_f32 v[76:77], v[206:207], v[76:77] op_sel_hi:[0,1]
	v_and_b32_e32 v83, 0xffff0000, v72
	v_lshlrev_b32_e32 v72, 16, v73
	v_and_b32_e32 v73, 0xffff0000, v73
	v_pk_mul_f32 v[84:85], v[206:207], v[84:85] op_sel_hi:[0,1]
	v_pk_mul_f32 v[76:77], v[58:59], v[76:77]
	v_pk_mul_f32 v[84:85], v[56:57], v[84:85]
	v_pk_fma_f32 v[62:63], v[62:63], v[76:77], v[72:73]
	v_lshl_add_u64 v[72:73], s[36:37], 0, v[80:81]
	v_lshlrev_b32_e32 v76, 16, v79
	v_and_b32_e32 v77, 0xffff0000, v79
	v_pk_fma_f32 v[60:61], v[60:61], v[84:85], v[82:83]
	v_lshl_add_u64 v[72:73], v[72:73], 0, v[188:189]
	v_pk_mul_f32 v[76:77], v[206:207], v[76:77] op_sel_hi:[0,1]
	global_store_dwordx4 v[72:73], v[60:63], off nt
	v_pk_mul_f32 v[76:77], v[50:51], v[76:77]
	v_rcp_f32_e32 v3, v3
	v_lshlrev_b32_e32 v60, 16, v74
	v_and_b32_e32 v61, 0xffff0000, v74
	v_lshlrev_b32_e32 v62, 16, v78
	v_and_b32_e32 v63, 0xffff0000, v78
	v_lshlrev_b32_e32 v74, 16, v75
	v_and_b32_e32 v75, 0xffff0000, v75
	v_pk_mul_f32 v[62:63], v[206:207], v[62:63] op_sel_hi:[0,1]
	v_pk_fma_f32 v[54:55], v[54:55], v[76:77], v[74:75]
	v_add_co_u32_e32 v74, vcc, s59, v216
	v_pk_mul_f32 v[62:63], v[48:49], v[62:63]
	s_nop 0
	v_addc_co_u32_e32 v75, vcc, 0, v217, vcc
	v_pk_fma_f32 v[52:53], v[52:53], v[62:63], v[60:61]
	v_add_co_u32_e32 v76, vcc, s59, v218
	global_store_dwordx4 v[72:73], v[52:55], off offset:16 nt
	s_nop 0
	v_addc_co_u32_e32 v77, vcc, 0, v219, vcc
	s_waitcnt vmcnt(2)
	v_lshlrev_b32_e32 v80, 16, v68
	v_and_b32_e32 v81, 0xffff0000, v68
	v_lshlrev_b32_e32 v68, 16, v69
	v_and_b32_e32 v69, 0xffff0000, v69
	global_load_dwordx4 v[52:55], v[74:75], off
	global_load_dwordx4 v[60:63], v[76:77], off
	v_pk_mul_f32 v[68:69], v[206:207], v[68:69] op_sel_hi:[0,1]
	v_pk_mul_f32 v[80:81], v[206:207], v[80:81] op_sel_hi:[0,1]
	v_lshlrev_b32_e32 v78, 16, v64
	v_and_b32_e32 v79, 0xffff0000, v64
	v_lshlrev_b32_e32 v64, 16, v65
	v_and_b32_e32 v65, 0xffff0000, v65
	v_pk_mul_f32 v[80:81], v[44:45], v[80:81]
	v_pk_mul_f32 v[68:69], v[46:47], v[68:69]
	v_pk_fma_f32 v[40:41], v[40:41], v[80:81], v[78:79]
	v_pk_fma_f32 v[42:43], v[42:43], v[68:69], v[64:65]
	global_store_dwordx4 v[72:73], v[40:43], off offset:512 nt
	v_lshlrev_b32_e32 v64, 16, v67
	v_and_b32_e32 v65, 0xffff0000, v67
	v_lshlrev_b32_e32 v40, 16, v66
	v_and_b32_e32 v41, 0xffff0000, v66
	v_lshlrev_b32_e32 v42, 16, v70
	v_and_b32_e32 v43, 0xffff0000, v70
	v_lshlrev_b32_e32 v66, 16, v71
	v_and_b32_e32 v67, 0xffff0000, v71
	v_pk_mul_f32 v[66:67], v[206:207], v[66:67] op_sel_hi:[0,1]
	v_pk_mul_f32 v[42:43], v[206:207], v[42:43] op_sel_hi:[0,1]
	v_pk_mul_f32 v[42:43], v[36:37], v[42:43]
	v_pk_mul_f32 v[66:67], v[38:39], v[66:67]
	v_pk_fma_f32 v[32:33], v[32:33], v[42:43], v[40:41]
	v_pk_fma_f32 v[34:35], v[34:35], v[66:67], v[64:65]
	global_store_dwordx4 v[72:73], v[32:35], off offset:528 nt
	global_load_dwordx4 v[32:35], v[74:75], off offset:256
	s_nop 0
	global_load_dwordx4 v[40:43], v[76:77], off offset:256
	v_lshlrev_b64 v[64:65], 12, v[204:205]
	s_waitcnt vmcnt(5)
	v_lshlrev_b32_e32 v66, 16, v52
	s_waitcnt vmcnt(4)
	v_lshlrev_b32_e32 v68, 16, v60
	v_and_b32_e32 v69, 0xffff0000, v60
	v_lshlrev_b32_e32 v60, 16, v61
	v_and_b32_e32 v61, 0xffff0000, v61
	v_pk_mul_f32 v[60:61], v[200:201], v[60:61] op_sel_hi:[0,1]
	v_and_b32_e32 v67, 0xffff0000, v52
	v_lshlrev_b32_e32 v52, 16, v53
	v_and_b32_e32 v53, 0xffff0000, v53
	v_pk_mul_f32 v[68:69], v[200:201], v[68:69] op_sel_hi:[0,1]
	v_pk_mul_f32 v[60:61], v[58:59], v[60:61]
	v_pk_mul_f32 v[68:69], v[56:57], v[68:69]
	v_pk_fma_f32 v[30:31], v[30:31], v[60:61], v[52:53]
	v_lshl_add_u64 v[52:53], s[36:37], 0, v[64:65]
	v_lshlrev_b32_e32 v60, 16, v63
	v_and_b32_e32 v61, 0xffff0000, v63
	v_pk_fma_f32 v[28:29], v[28:29], v[68:69], v[66:67]
	v_lshl_add_u64 v[52:53], v[52:53], 0, v[188:189]
	v_pk_mul_f32 v[60:61], v[200:201], v[60:61] op_sel_hi:[0,1]
	global_store_dwordx4 v[52:53], v[28:31], off nt
	v_pk_mul_f32 v[60:61], v[50:51], v[60:61]
	s_waitcnt vmcnt(2)
	v_and_b32_e32 v63, 0xffff0000, v32
	v_lshlrev_b32_e32 v28, 16, v54
	v_and_b32_e32 v29, 0xffff0000, v54
	v_lshlrev_b32_e32 v30, 16, v62
	v_and_b32_e32 v31, 0xffff0000, v62
	v_lshlrev_b32_e32 v54, 16, v55
	v_and_b32_e32 v55, 0xffff0000, v55
	v_pk_mul_f32 v[30:31], v[200:201], v[30:31] op_sel_hi:[0,1]
	v_pk_fma_f32 v[26:27], v[26:27], v[60:61], v[54:55]
	v_add_co_u32_e32 v54, vcc, s60, v216
	v_pk_mul_f32 v[30:31], v[48:49], v[30:31]
	s_nop 0
	v_addc_co_u32_e32 v55, vcc, 0, v217, vcc
	v_pk_fma_f32 v[24:25], v[24:25], v[30:31], v[28:29]
	v_add_co_u32_e32 v60, vcc, s60, v218
	s_waitcnt vmcnt(1)
	v_lshlrev_b32_e32 v64, 16, v40
	v_and_b32_e32 v65, 0xffff0000, v40
	v_lshlrev_b32_e32 v40, 16, v41
	v_and_b32_e32 v41, 0xffff0000, v41
	global_store_dwordx4 v[52:53], v[24:27], off offset:16 nt
	v_addc_co_u32_e32 v61, vcc, 0, v219, vcc
	v_pk_mul_f32 v[40:41], v[200:201], v[40:41] op_sel_hi:[0,1]
	v_pk_mul_f32 v[64:65], v[200:201], v[64:65] op_sel_hi:[0,1]
	global_load_dwordx4 v[24:27], v[54:55], off
	global_load_dwordx4 v[28:31], v[60:61], off
	v_lshlrev_b32_e32 v62, 16, v32
	v_lshlrev_b32_e32 v32, 16, v33
	v_and_b32_e32 v33, 0xffff0000, v33
	v_pk_mul_f32 v[64:65], v[44:45], v[64:65]
	v_pk_mul_f32 v[40:41], v[46:47], v[40:41]
	v_pk_fma_f32 v[20:21], v[20:21], v[64:65], v[62:63]
	v_pk_fma_f32 v[22:23], v[22:23], v[40:41], v[32:33]
	global_store_dwordx4 v[52:53], v[20:23], off offset:512 nt
	v_lshlrev_b32_e32 v32, 16, v35
	v_and_b32_e32 v33, 0xffff0000, v35
	v_lshlrev_b32_e32 v20, 16, v34
	v_and_b32_e32 v21, 0xffff0000, v34
	v_lshlrev_b32_e32 v22, 16, v42
	v_and_b32_e32 v23, 0xffff0000, v42
	v_lshlrev_b32_e32 v34, 16, v43
	v_and_b32_e32 v35, 0xffff0000, v43
	v_pk_mul_f32 v[34:35], v[200:201], v[34:35] op_sel_hi:[0,1]
	v_pk_mul_f32 v[22:23], v[200:201], v[22:23] op_sel_hi:[0,1]
	v_pk_mul_f32 v[22:23], v[36:37], v[22:23]
	v_pk_mul_f32 v[34:35], v[38:39], v[34:35]
	v_pk_fma_f32 v[16:17], v[16:17], v[22:23], v[20:21]
	v_pk_fma_f32 v[18:19], v[18:19], v[34:35], v[32:33]
	global_store_dwordx4 v[52:53], v[16:19], off offset:528 nt
	global_load_dwordx4 v[16:19], v[54:55], off offset:256
	s_nop 0
	global_load_dwordx4 v[20:23], v[60:61], off offset:256
	v_lshlrev_b64 v[40:41], 12, v[198:199]
	s_and_b64 vcc, exec, s[0:1]
	s_waitcnt vmcnt(5)
	v_lshlrev_b32_e32 v32, 16, v24
	s_waitcnt vmcnt(4)
	v_lshlrev_b32_e32 v34, 16, v28
	v_and_b32_e32 v35, 0xffff0000, v28
	v_lshlrev_b32_e32 v28, 16, v29
	v_and_b32_e32 v29, 0xffff0000, v29
	v_pk_mul_f32 v[28:29], v[194:195], v[28:29] op_sel_hi:[0,1]
	v_and_b32_e32 v33, 0xffff0000, v24
	v_lshlrev_b32_e32 v24, 16, v25
	v_and_b32_e32 v25, 0xffff0000, v25
	v_pk_mul_f32 v[34:35], v[194:195], v[34:35] op_sel_hi:[0,1]
	v_pk_mul_f32 v[28:29], v[58:59], v[28:29]
	v_pk_mul_f32 v[42:43], v[56:57], v[34:35]
	v_pk_fma_f32 v[34:35], v[14:15], v[28:29], v[24:25]
	v_lshlrev_b32_e32 v24, 16, v30
	v_and_b32_e32 v25, 0xffff0000, v30
	v_lshlrev_b32_e32 v28, 16, v31
	v_and_b32_e32 v29, 0xffff0000, v31
	v_pk_mul_f32 v[28:29], v[194:195], v[28:29] op_sel_hi:[0,1]
	v_pk_mul_f32 v[24:25], v[194:195], v[24:25] op_sel_hi:[0,1]
	v_pk_fma_f32 v[32:33], v[12:13], v[42:43], v[32:33]
	v_lshl_add_u64 v[12:13], s[36:37], 0, v[40:41]
	v_lshlrev_b32_e32 v14, 16, v26
	v_and_b32_e32 v15, 0xffff0000, v26
	v_lshlrev_b32_e32 v26, 16, v27
	v_and_b32_e32 v27, 0xffff0000, v27
	v_pk_mul_f32 v[24:25], v[48:49], v[24:25]
	v_pk_mul_f32 v[28:29], v[50:51], v[28:29]
	v_lshl_add_u64 v[12:13], v[12:13], 0, v[188:189]
	v_pk_fma_f32 v[10:11], v[10:11], v[28:29], v[26:27]
	v_pk_fma_f32 v[8:9], v[8:9], v[24:25], v[14:15]
	global_store_dwordx4 v[12:13], v[8:11], off offset:16 nt
	s_waitcnt vmcnt(2)
	v_lshlrev_b32_e32 v14, 16, v17
	v_and_b32_e32 v15, 0xffff0000, v17
	v_lshlrev_b32_e32 v8, 16, v16
	v_and_b32_e32 v9, 0xffff0000, v16
	s_waitcnt vmcnt(1)
	v_lshlrev_b32_e32 v10, 16, v20
	v_and_b32_e32 v11, 0xffff0000, v20
	v_lshlrev_b32_e32 v16, 16, v21
	v_and_b32_e32 v17, 0xffff0000, v21
	v_pk_mul_f32 v[16:17], v[194:195], v[16:17] op_sel_hi:[0,1]
	v_pk_mul_f32 v[10:11], v[194:195], v[10:11] op_sel_hi:[0,1]
	v_pk_mul_f32 v[10:11], v[44:45], v[10:11]
	v_pk_mul_f32 v[16:17], v[46:47], v[16:17]
	v_pk_fma_f32 v[4:5], v[4:5], v[10:11], v[8:9]
	v_pk_fma_f32 v[6:7], v[6:7], v[16:17], v[14:15]
	global_store_dwordx4 v[12:13], v[4:7], off offset:512 nt
	v_lshlrev_b32_e32 v10, 16, v23
	v_and_b32_e32 v11, 0xffff0000, v23
	v_lshlrev_b32_e32 v6, 16, v22
	v_and_b32_e32 v7, 0xffff0000, v22
	v_pk_mul_f32 v[10:11], v[194:195], v[10:11] op_sel_hi:[0,1]
	v_pk_mul_f32 v[6:7], v[194:195], v[6:7] op_sel_hi:[0,1]
	v_lshlrev_b32_e32 v4, 16, v18
	v_and_b32_e32 v5, 0xffff0000, v18
	v_lshlrev_b32_e32 v8, 16, v19
	v_and_b32_e32 v9, 0xffff0000, v19
	v_pk_mul_f32 v[6:7], v[36:37], v[6:7]
	v_pk_mul_f32 v[10:11], v[38:39], v[10:11]
	v_pk_fma_f32 v[0:1], v[0:1], v[6:7], v[4:5]
	v_pk_fma_f32 v[2:3], v[2:3], v[10:11], v[8:9]
	global_store_dwordx4 v[12:13], v[32:35], off nt
	global_store_dwordx4 v[12:13], v[0:3], off offset:528 nt
	s_cbranch_vccz .LBB0_2024
	s_waitcnt vmcnt(0)
	s_cmpk_gt_u32 s19, 0xff
	s_cbranch_scc1 .LBB0_2035
	s_barrier
